# v2 plus: per-segment s_setprio flips removed from the GEMM K-loops
# speedup vs baseline: 1.0048x; 1.0048x over previous
;     __device__ __forceinline__ void a_ready(const Unit& u) const { wait_panel(cnt, u.pm, need, tmo, wave); }
;     __device__ __forceinline__ void a_ready(const Unit& u) const { wait_panel(cnt, u.pm, need, tmo, wave); }
; #define PG8_STAGE(bufoff, gbase, voff) do { _Pragma("unroll") for (int _i = 0; _i < 2; ++_i) \
;         __builtin_amdgcn_global_load_lds((const unsigned*)((const char*)(gbase) + (voff)[_i]), (PG8_LAS unsigned*)(lds + (bufoff) + ldsw + _i * 8192), 16, 0, 0); } while (0)
; #define PG8_LDA(dst, b, h) do { _Pragma("unroll") for (int m = 0; m < 4; ++m) _Pragma("unroll") for (int k = 0; k < 2; ++k) dst[m][k] = *(const PG8_LAS bf16x8*)(lds + PG8_SA(b, h) + aoff + m * 2048 + k * 1024); } while (0)
; #define PG8_LDB(dst, b, h) do { _Pragma("unroll") for (int n = 0; n < 2; ++n) _Pragma("unroll") for (int k = 0; k < 2; ++k) dst[n][k] = *(const PG8_LAS bf16x8*)(lds + PG8_SB(b, h) + boff + n * 2048 + k * 1024); } while (0)
; #define PG8_WAIT_V(n) asm volatile("s_waitcnt vmcnt(" #n ")" ::: "memory")
; #define PG8_WAIT_L(n) asm volatile("s_waitcnt lgkmcnt(" #n ")" ::: "memory")
; #define PG8_BAR __builtin_amdgcn_s_barrier()
; #define PG8_SCHED __builtin_amdgcn_sched_barrier(0)
; template <class Epi, class Sched, bool ALIGN_EPI = false, bool SP2 = false>
; __device__ __forceinline__ void gemm_phase(PG8_LAS unsigned char* lds, const Gemm g, const Sched& S, const Epi& E, const int tid_in) {
;     ...
;             const bool last = (t == nt - 2);
;             const char* a1 = cA + (size_t)(t + 1) * kstep;
;             const char* a2 = last ? nA : cA + (size_t)(t + 2) * kstep; const char* b2 = last ? nB : cB + (size_t)(t + 2) * kstep;
;             const char* a3 = a2 + kstep; const char* b3 = b2 + kstep;
;             if (last && has_next) S.a_ready(nxt);
;             if constexpr (SP2) {
;             PG8_LDB(B0, 0, 0); PG8_LDB(B1, 0, 1); PG8_SCHED; PG8_LDA(At, 0, 0); PG8_STAGE(PG8_SA(1, 1), a1 + hstepA, voffA);
;             PG8_WAIT_V(8); PG8_WAIT_L(0); PG8_BAR; PG8_MMA(0, 0, At, B0); PG8_MMA(0, 1, At, B1); PG8_BAR; PG8_SCHED;
;             PG8_LDA(At, 0, 1); PG8_STAGE(PG8_SB(0, 0), b2, voffB); PG8_STAGE(PG8_SB(0, 1), b2 + hstepB, voffB); PG8_STAGE(PG8_SA(0, 0), a2, voffA);
;             PG8_WAIT_V(8); PG8_WAIT_L(0); PG8_BAR; PG8_MMA(1, 0, At, B0); PG8_MMA(1, 1, At, B1); PG8_BAR; PG8_SCHED;
.LBB0_476:
	s_add_u32 s22, s52, 0xfff80080
	s_addc_u32 s23, s53, -1
	s_add_i32 s45, 0, 0x10000
	s_cmp_eq_u32 s43, 28
	s_cselect_b32 s55, s6, s23
	s_cselect_b32 s54, s11, s22
	s_cselect_b32 s23, s12, s35
	s_cselect_b32 s22, s33, s34
	s_add_i32 s47, 0, 0x14000
	ds_read_b128 v[138:141], v249
	ds_read_b128 v[150:153], v249 offset:1024
	ds_read_b128 v[154:157], v249 offset:2048
	ds_read_b128 v[158:161], v249 offset:3072
	ds_read_b128 v[162:165], v249 offset:16384
	ds_read_b128 v[166:169], v249 offset:17408
	ds_read_b128 v[190:193], v249 offset:18432
	ds_read_b128 v[194:197], v249 offset:19456
	s_add_i32 m0, s21, 0xc000
	ds_read_b128 v[198:201], v148
	ds_read_b128 v[202:205], v148 offset:1024
	ds_read_b128 v[206:209], v148 offset:2048
	ds_read_b128 v[210:213], v148 offset:3072
	ds_read_b128 v[224:227], v148 offset:4096
	ds_read_b128 v[228:231], v148 offset:5120
	ds_read_b128 v[232:235], v148 offset:6144
	ds_read_b128 v[236:239], v148 offset:7168
	global_load_lds_dwordx4 v134, s[52:53]
	s_add_i32 m0, s21, 0xe000
	s_nop 0
	global_load_lds_dwordx4 v136, s[52:53]
	s_waitcnt vmcnt(8)
	s_waitcnt lgkmcnt(0)
	s_barrier
	s_waitcnt lgkmcnt(0)
	v_mfma_f32_16x16x32_bf16 v[124:127], v[138:141], v[198:201], v[124:127]
	v_mfma_f32_16x16x32_bf16 v[120:123], v[154:157], v[198:201], v[120:123]
	v_mfma_f32_16x16x32_bf16 v[108:111], v[138:141], v[206:209], v[108:111]
	v_mfma_f32_16x16x32_bf16 v[104:107], v[154:157], v[206:209], v[104:107]
	v_mfma_f32_16x16x32_bf16 v[92:95], v[138:141], v[224:227], v[92:95]
	v_mfma_f32_16x16x32_bf16 v[88:91], v[154:157], v[224:227], v[88:91]
	v_mfma_f32_16x16x32_bf16 v[76:79], v[138:141], v[232:235], v[76:79]
	v_mfma_f32_16x16x32_bf16 v[72:75], v[154:157], v[232:235], v[72:75]
	v_mfma_f32_16x16x32_bf16 v[124:127], v[150:153], v[202:205], v[124:127]
	v_mfma_f32_16x16x32_bf16 v[120:123], v[158:161], v[202:205], v[120:123]
	v_mfma_f32_16x16x32_bf16 v[108:111], v[150:153], v[210:213], v[108:111]
	v_mfma_f32_16x16x32_bf16 v[104:107], v[158:161], v[210:213], v[104:107]
	v_mfma_f32_16x16x32_bf16 v[92:95], v[150:153], v[228:231], v[92:95]
	v_mfma_f32_16x16x32_bf16 v[88:91], v[158:161], v[228:231], v[88:91]
	v_mfma_f32_16x16x32_bf16 v[76:79], v[150:153], v[236:239], v[76:79]
	v_mfma_f32_16x16x32_bf16 v[72:75], v[158:161], v[236:239], v[72:75]
	v_mfma_f32_16x16x32_bf16 v[116:119], v[162:165], v[198:201], v[116:119]
	v_mfma_f32_16x16x32_bf16 v[112:115], v[190:193], v[198:201], v[112:115]
	v_mfma_f32_16x16x32_bf16 v[100:103], v[162:165], v[206:209], v[100:103]
	v_mfma_f32_16x16x32_bf16 v[96:99], v[190:193], v[206:209], v[96:99]
	v_mfma_f32_16x16x32_bf16 v[84:87], v[162:165], v[224:227], v[84:87]
	v_mfma_f32_16x16x32_bf16 v[80:83], v[190:193], v[224:227], v[80:83]
	v_mfma_f32_16x16x32_bf16 v[68:71], v[162:165], v[232:235], v[68:71]
	v_mfma_f32_16x16x32_bf16 v[64:67], v[190:193], v[232:235], v[64:67]
	v_mfma_f32_16x16x32_bf16 v[116:119], v[166:169], v[202:205], v[116:119]
	v_mfma_f32_16x16x32_bf16 v[112:115], v[194:197], v[202:205], v[112:115]
	v_mfma_f32_16x16x32_bf16 v[100:103], v[166:169], v[210:213], v[100:103]
	v_mfma_f32_16x16x32_bf16 v[96:99], v[194:197], v[210:213], v[96:99]
	v_mfma_f32_16x16x32_bf16 v[84:87], v[166:169], v[228:231], v[84:87]
	v_mfma_f32_16x16x32_bf16 v[80:83], v[194:197], v[228:231], v[80:83]
	v_mfma_f32_16x16x32_bf16 v[68:71], v[166:169], v[236:239], v[68:71]
	v_mfma_f32_16x16x32_bf16 v[64:67], v[194:197], v[236:239], v[64:67]
	s_barrier
	s_add_i32 s45, s45, s20
	s_mov_b32 m0, s45
	ds_read_b128 v[198:201], v148 offset:16384
	ds_read_b128 v[202:205], v148 offset:17408
	ds_read_b128 v[206:209], v148 offset:18432
	ds_read_b128 v[210:213], v148 offset:19456
	ds_read_b128 v[224:227], v148 offset:20480
	ds_read_b128 v[228:231], v148 offset:21504
	ds_read_b128 v[232:235], v148 offset:22528
	ds_read_b128 v[236:239], v148 offset:23552
	global_load_lds_dwordx4 v172, s[22:23]
	s_add_i32 m0, s45, 0x2000
	s_add_u32 s60, s22, 0x80000
	s_addc_u32 s61, s23, 0
	s_add_i32 s45, s47, s20
	global_load_lds_dwordx4 v132, s[22:23]
	s_mov_b32 m0, s45
	s_nop 0
	global_load_lds_dwordx4 v172, s[60:61]
	s_add_i32 m0, s45, 0x2000
	s_nop 0
	global_load_lds_dwordx4 v132, s[60:61]
	s_mov_b32 m0, s21
	s_nop 0
	global_load_lds_dwordx4 v128, s[54:55]
	s_mov_b32 m0, s30
	s_nop 0
	global_load_lds_dwordx4 v130, s[54:55]
	s_waitcnt vmcnt(8)
	s_waitcnt lgkmcnt(0)
	s_barrier
	s_waitcnt lgkmcnt(0)
	v_mfma_f32_16x16x32_bf16 v[60:63], v[138:141], v[198:201], v[60:63]
	v_mfma_f32_16x16x32_bf16 v[56:59], v[154:157], v[198:201], v[56:59]
	v_mfma_f32_16x16x32_bf16 v[44:47], v[138:141], v[206:209], v[44:47]
	v_mfma_f32_16x16x32_bf16 v[40:43], v[154:157], v[206:209], v[40:43]
	v_mfma_f32_16x16x32_bf16 v[28:31], v[138:141], v[224:227], v[28:31]
	v_mfma_f32_16x16x32_bf16 v[24:27], v[154:157], v[224:227], v[24:27]
	v_mfma_f32_16x16x32_bf16 v[12:15], v[138:141], v[232:235], v[12:15]
	v_mfma_f32_16x16x32_bf16 v[8:11], v[154:157], v[232:235], v[8:11]
	v_mfma_f32_16x16x32_bf16 v[60:63], v[150:153], v[202:205], v[60:63]
	v_mfma_f32_16x16x32_bf16 v[56:59], v[158:161], v[202:205], v[56:59]
	v_mfma_f32_16x16x32_bf16 v[44:47], v[150:153], v[210:213], v[44:47]
	v_mfma_f32_16x16x32_bf16 v[40:43], v[158:161], v[210:213], v[40:43]
	v_mfma_f32_16x16x32_bf16 v[28:31], v[150:153], v[228:231], v[28:31]
	v_mfma_f32_16x16x32_bf16 v[24:27], v[158:161], v[228:231], v[24:27]
	v_mfma_f32_16x16x32_bf16 v[12:15], v[150:153], v[236:239], v[12:15]
	v_mfma_f32_16x16x32_bf16 v[8:11], v[158:161], v[236:239], v[8:11]
	v_mfma_f32_16x16x32_bf16 v[52:55], v[162:165], v[198:201], v[52:55]
	v_mfma_f32_16x16x32_bf16 v[48:51], v[190:193], v[198:201], v[48:51]
	v_mfma_f32_16x16x32_bf16 v[36:39], v[162:165], v[206:209], v[36:39]
	v_mfma_f32_16x16x32_bf16 v[32:35], v[190:193], v[206:209], v[32:35]
	v_mfma_f32_16x16x32_bf16 v[20:23], v[162:165], v[224:227], v[20:23]
	v_mfma_f32_16x16x32_bf16 v[16:19], v[190:193], v[224:227], v[16:19]
	v_mfma_f32_16x16x32_bf16 v[4:7], v[162:165], v[232:235], v[4:7]
	v_mfma_f32_16x16x32_bf16 v[0:3], v[190:193], v[232:235], v[0:3]
	v_mfma_f32_16x16x32_bf16 v[52:55], v[166:169], v[202:205], v[52:55]
	v_mfma_f32_16x16x32_bf16 v[48:51], v[194:197], v[202:205], v[48:51]
	v_mfma_f32_16x16x32_bf16 v[36:39], v[166:169], v[210:213], v[36:39]
	v_mfma_f32_16x16x32_bf16 v[32:35], v[194:197], v[210:213], v[32:35]
	v_mfma_f32_16x16x32_bf16 v[20:23], v[166:169], v[228:231], v[20:23]
	v_mfma_f32_16x16x32_bf16 v[16:19], v[194:197], v[228:231], v[16:19]
	v_mfma_f32_16x16x32_bf16 v[4:7], v[166:169], v[236:239], v[4:7]
	v_mfma_f32_16x16x32_bf16 v[0:3], v[194:197], v[236:239], v[0:3]
	s_barrier
; #define PG8_STAGE(bufoff, gbase, voff) do { _Pragma("unroll") for (int _i = 0; _i < 2; ++_i) \
;         __builtin_amdgcn_global_load_lds((const unsigned*)((const char*)(gbase) + (voff)[_i]), (PG8_LAS unsigned*)(lds + (bufoff) + ldsw + _i * 8192), 16, 0, 0); } while (0)
; #define PG8_LDA(dst, b, h) do { _Pragma("unroll") for (int m = 0; m < 4; ++m) _Pragma("unroll") for (int k = 0; k < 2; ++k) dst[m][k] = *(const PG8_LAS bf16x8*)(lds + PG8_SA(b, h) + aoff + m * 2048 + k * 1024); } while (0)
; #define PG8_LDB(dst, b, h) do { _Pragma("unroll") for (int n = 0; n < 2; ++n) _Pragma("unroll") for (int k = 0; k < 2; ++k) dst[n][k] = *(const PG8_LAS bf16x8*)(lds + PG8_SB(b, h) + boff + n * 2048 + k * 1024); } while (0)
; #define PG8_MMA(ai, bj, At, Bt) do { __builtin_amdgcn_s_setprio(1); _Pragma("unroll") for (int m = 0; m < 4; ++m) _Pragma("unroll") for (int n = 0; n < 2; ++n) _Pragma("unroll") for (int k = 0; k < 2; ++k) \
;         acc[ai][bj][m][n] = __builtin_amdgcn_mfma_f32_16x16x32_bf16(Bt[n][k], At[m][k], acc[ai][bj][m][n], 0, 0, 0); __builtin_amdgcn_s_setprio(0); } while (0)
; #define PG8_WAIT_V(n) asm volatile("s_waitcnt vmcnt(" #n ")" ::: "memory")
; #define PG8_WAIT_L(n) asm volatile("s_waitcnt lgkmcnt(" #n ")" ::: "memory")
; #define PG8_BAR __builtin_amdgcn_s_barrier()
; #define PG8_SCHED __builtin_amdgcn_sched_barrier(0)
; template <class Epi, class Sched, bool ALIGN_EPI = false, bool SP2 = false>
; __device__ __forceinline__ void gemm_phase(PG8_LAS unsigned char* lds, const Gemm g, const Sched& S, const Epi& E, const int tid_in) {
;     ...
;             PG8_LDB(B0, 1, 0); PG8_LDB(B1, 1, 1); PG8_SCHED; PG8_LDA(At, 1, 0); PG8_STAGE(PG8_SA(0, 1), a2 + hstepA, voffA);
;             PG8_WAIT_V(8); PG8_WAIT_L(0); PG8_BAR; PG8_MMA(0, 0, At, B0); PG8_MMA(0, 1, At, B1); PG8_BAR; PG8_SCHED;
;             PG8_LDA(At, 1, 1); PG8_STAGE(PG8_SB(1, 0), b3, voffB); PG8_STAGE(PG8_SB(1, 1), b3 + hstepB, voffB); PG8_STAGE(PG8_SA(1, 0), a3, voffA);
;             PG8_WAIT_V(8); PG8_WAIT_L(0); PG8_BAR; PG8_MMA(1, 0, At, B0); PG8_MMA(1, 1, At, B1); PG8_BAR; PG8_SCHED;
;     ...
;         if constexpr (ALIGN_EPI) { if (wr == 0) PG8_BAR; }
	s_add_i32 s45, 0, 0x18000
	s_add_i32 s47, 0, 0x1c000
	ds_read_b128 v[138:141], v249 offset:32768
	ds_read_b128 v[150:153], v249 offset:33792
	ds_read_b128 v[154:157], v249 offset:34816
	ds_read_b128 v[158:161], v249 offset:35840
	ds_read_b128 v[162:165], v249 offset:49152
	ds_read_b128 v[166:169], v249 offset:50176
	ds_read_b128 v[190:193], v249 offset:51200
	ds_read_b128 v[194:197], v249 offset:52224
	s_add_u32 s54, s54, 0x80000
	s_addc_u32 s55, s55, 0
	s_mov_b32 m0, s31
	ds_read_b128 v[198:201], v148 offset:32768
	ds_read_b128 v[202:205], v148 offset:33792
	ds_read_b128 v[206:209], v148 offset:34816
	ds_read_b128 v[210:213], v148 offset:35840
	ds_read_b128 v[224:227], v148 offset:36864
	ds_read_b128 v[228:231], v148 offset:37888
	ds_read_b128 v[232:235], v148 offset:38912
	ds_read_b128 v[236:239], v148 offset:39936
	global_load_lds_dwordx4 v128, s[54:55]
	s_mov_b32 m0, s37
	s_nop 0
	global_load_lds_dwordx4 v130, s[54:55]
	s_waitcnt vmcnt(8)
	s_waitcnt lgkmcnt(0)
	s_barrier
	s_waitcnt lgkmcnt(0)
	v_mfma_f32_16x16x32_bf16 v[124:127], v[138:141], v[198:201], v[124:127]
	v_mfma_f32_16x16x32_bf16 v[120:123], v[154:157], v[198:201], v[120:123]
	v_mfma_f32_16x16x32_bf16 v[108:111], v[138:141], v[206:209], v[108:111]
	v_mfma_f32_16x16x32_bf16 v[104:107], v[154:157], v[206:209], v[104:107]
	v_mfma_f32_16x16x32_bf16 v[92:95], v[138:141], v[224:227], v[92:95]
	v_mfma_f32_16x16x32_bf16 v[88:91], v[154:157], v[224:227], v[88:91]
	v_mfma_f32_16x16x32_bf16 v[76:79], v[138:141], v[232:235], v[76:79]
	v_mfma_f32_16x16x32_bf16 v[72:75], v[154:157], v[232:235], v[72:75]
	v_mfma_f32_16x16x32_bf16 v[124:127], v[150:153], v[202:205], v[124:127]
	v_mfma_f32_16x16x32_bf16 v[120:123], v[158:161], v[202:205], v[120:123]
	v_mfma_f32_16x16x32_bf16 v[108:111], v[150:153], v[210:213], v[108:111]
	v_mfma_f32_16x16x32_bf16 v[104:107], v[158:161], v[210:213], v[104:107]
	v_mfma_f32_16x16x32_bf16 v[92:95], v[150:153], v[228:231], v[92:95]
	v_mfma_f32_16x16x32_bf16 v[88:91], v[158:161], v[228:231], v[88:91]
	v_mfma_f32_16x16x32_bf16 v[76:79], v[150:153], v[236:239], v[76:79]
	v_mfma_f32_16x16x32_bf16 v[72:75], v[158:161], v[236:239], v[72:75]
	v_mfma_f32_16x16x32_bf16 v[116:119], v[162:165], v[198:201], v[116:119]
	v_mfma_f32_16x16x32_bf16 v[112:115], v[190:193], v[198:201], v[112:115]
	v_mfma_f32_16x16x32_bf16 v[100:103], v[162:165], v[206:209], v[100:103]
	v_mfma_f32_16x16x32_bf16 v[96:99], v[190:193], v[206:209], v[96:99]
	v_mfma_f32_16x16x32_bf16 v[84:87], v[162:165], v[224:227], v[84:87]
	v_mfma_f32_16x16x32_bf16 v[80:83], v[190:193], v[224:227], v[80:83]
	v_mfma_f32_16x16x32_bf16 v[68:71], v[162:165], v[232:235], v[68:71]
	v_mfma_f32_16x16x32_bf16 v[64:67], v[190:193], v[232:235], v[64:67]
	v_mfma_f32_16x16x32_bf16 v[116:119], v[166:169], v[202:205], v[116:119]
	v_mfma_f32_16x16x32_bf16 v[112:115], v[194:197], v[202:205], v[112:115]
	v_mfma_f32_16x16x32_bf16 v[100:103], v[166:169], v[210:213], v[100:103]
	v_mfma_f32_16x16x32_bf16 v[96:99], v[194:197], v[210:213], v[96:99]
	v_mfma_f32_16x16x32_bf16 v[84:87], v[166:169], v[228:231], v[84:87]
	v_mfma_f32_16x16x32_bf16 v[80:83], v[194:197], v[228:231], v[80:83]
	v_mfma_f32_16x16x32_bf16 v[68:71], v[166:169], v[236:239], v[68:71]
	v_mfma_f32_16x16x32_bf16 v[64:67], v[194:197], v[236:239], v[64:67]
	s_barrier
	s_add_i32 s45, s45, s20
	s_mov_b32 m0, s45
	ds_read_b128 v[198:201], v148 offset:49152
	ds_read_b128 v[202:205], v148 offset:50176
	ds_read_b128 v[206:209], v148 offset:51200
	ds_read_b128 v[210:213], v148 offset:52224
	ds_read_b128 v[224:227], v148 offset:53248
	ds_read_b128 v[228:231], v148 offset:54272
	ds_read_b128 v[232:235], v148 offset:55296
	ds_read_b128 v[236:239], v148 offset:56320
	s_add_u32 s100, s22, 0x80
	s_addc_u32 s101, s23, 0
	global_load_lds_dwordx4 v172, s[100:101]
	s_add_i32 m0, s45, 0x2000
	s_add_u32 s22, s22, 0x80080
	s_addc_u32 s23, s23, 0
	s_add_i32 s45, s47, s20
	global_load_lds_dwordx4 v132, s[100:101]
	s_mov_b32 m0, s45
	s_nop 0
	global_load_lds_dwordx4 v172, s[22:23]
	s_add_i32 m0, s45, 0x2000
	s_nop 0
	global_load_lds_dwordx4 v132, s[22:23]
	s_mov_b32 m0, s38
	s_nop 0
	s_add_u32 s100, s54, 0xfff80080
	s_addc_u32 s101, s55, -1
	global_load_lds_dwordx4 v128, s[100:101]
	s_mov_b32 m0, s56
	s_nop 0
	global_load_lds_dwordx4 v130, s[100:101]
	s_waitcnt vmcnt(8)
	s_waitcnt lgkmcnt(0)
	s_barrier
	s_waitcnt lgkmcnt(0)
	v_mfma_f32_16x16x32_bf16 v[60:63], v[138:141], v[198:201], v[60:63]
	v_mfma_f32_16x16x32_bf16 v[56:59], v[154:157], v[198:201], v[56:59]
	v_mfma_f32_16x16x32_bf16 v[44:47], v[138:141], v[206:209], v[44:47]
	v_mfma_f32_16x16x32_bf16 v[40:43], v[154:157], v[206:209], v[40:43]
	v_mfma_f32_16x16x32_bf16 v[28:31], v[138:141], v[224:227], v[28:31]
	v_mfma_f32_16x16x32_bf16 v[24:27], v[154:157], v[224:227], v[24:27]
	v_mfma_f32_16x16x32_bf16 v[12:15], v[138:141], v[232:235], v[12:15]
	v_mfma_f32_16x16x32_bf16 v[8:11], v[154:157], v[232:235], v[8:11]
	v_mfma_f32_16x16x32_bf16 v[60:63], v[150:153], v[202:205], v[60:63]
	v_mfma_f32_16x16x32_bf16 v[56:59], v[158:161], v[202:205], v[56:59]
	v_mfma_f32_16x16x32_bf16 v[44:47], v[150:153], v[210:213], v[44:47]
	v_mfma_f32_16x16x32_bf16 v[40:43], v[158:161], v[210:213], v[40:43]
	v_mfma_f32_16x16x32_bf16 v[28:31], v[150:153], v[228:231], v[28:31]
	v_mfma_f32_16x16x32_bf16 v[24:27], v[158:161], v[228:231], v[24:27]
	v_mfma_f32_16x16x32_bf16 v[12:15], v[150:153], v[236:239], v[12:15]
	v_mfma_f32_16x16x32_bf16 v[8:11], v[158:161], v[236:239], v[8:11]
	v_mfma_f32_16x16x32_bf16 v[52:55], v[162:165], v[198:201], v[52:55]
	v_mfma_f32_16x16x32_bf16 v[48:51], v[190:193], v[198:201], v[48:51]
	v_mfma_f32_16x16x32_bf16 v[36:39], v[162:165], v[206:209], v[36:39]
	v_mfma_f32_16x16x32_bf16 v[32:35], v[190:193], v[206:209], v[32:35]
	v_mfma_f32_16x16x32_bf16 v[20:23], v[162:165], v[224:227], v[20:23]
	v_mfma_f32_16x16x32_bf16 v[16:19], v[190:193], v[224:227], v[16:19]
	v_mfma_f32_16x16x32_bf16 v[4:7], v[162:165], v[232:235], v[4:7]
	v_mfma_f32_16x16x32_bf16 v[0:3], v[190:193], v[232:235], v[0:3]
	v_mfma_f32_16x16x32_bf16 v[52:55], v[166:169], v[202:205], v[52:55]
	v_mfma_f32_16x16x32_bf16 v[48:51], v[194:197], v[202:205], v[48:51]
	v_mfma_f32_16x16x32_bf16 v[36:39], v[166:169], v[210:213], v[36:39]
	v_mfma_f32_16x16x32_bf16 v[32:35], v[194:197], v[210:213], v[32:35]
	v_mfma_f32_16x16x32_bf16 v[20:23], v[166:169], v[228:231], v[20:23]
	v_mfma_f32_16x16x32_bf16 v[16:19], v[194:197], v[228:231], v[16:19]
	v_mfma_f32_16x16x32_bf16 v[4:7], v[166:169], v[236:239], v[4:7]
	v_mfma_f32_16x16x32_bf16 v[0:3], v[194:197], v[236:239], v[0:3]
	s_barrier
	s_add_i32 s43, s43, 2
	s_add_u32 s52, s52, 0x100
	s_addc_u32 s53, s53, 0
	s_add_u32 s34, s34, 0x100
	s_addc_u32 s35, s35, 0
	s_cmp_gt_u32 s43, 29
	s_cbranch_scc0 .LBB0_476
	s_and_b64 vcc, exec, s[28:29]
	s_cbranch_vccz .LBB0_479
	s_barrier

;     __device__ __forceinline__ void a_ready(const Unit& u) const { wait_panel(cnt, u.pm, need, tmo, wave); }
;     __device__ __forceinline__ void a_ready(const Unit& u) const { wait_panel(cnt, u.pm, need, tmo, wave); }
; #define PG8_STAGE(bufoff, gbase, voff) do { _Pragma("unroll") for (int _i = 0; _i < 2; ++_i) \
;         __builtin_amdgcn_global_load_lds((const unsigned*)((const char*)(gbase) + (voff)[_i]), (PG8_LAS unsigned*)(lds + (bufoff) + ldsw + _i * 8192), 16, 0, 0); } while (0)
; #define PG8_LDA(dst, b, h) do { _Pragma("unroll") for (int m = 0; m < 4; ++m) _Pragma("unroll") for (int k = 0; k < 2; ++k) dst[m][k] = *(const PG8_LAS bf16x8*)(lds + PG8_SA(b, h) + aoff + m * 2048 + k * 1024); } while (0)
; #define PG8_LDB(dst, b, h) do { _Pragma("unroll") for (int n = 0; n < 2; ++n) _Pragma("unroll") for (int k = 0; k < 2; ++k) dst[n][k] = *(const PG8_LAS bf16x8*)(lds + PG8_SB(b, h) + boff + n * 2048 + k * 1024); } while (0)
; #define PG8_WAIT_V(n) asm volatile("s_waitcnt vmcnt(" #n ")" ::: "memory")
; #define PG8_WAIT_L(n) asm volatile("s_waitcnt lgkmcnt(" #n ")" ::: "memory")
; #define PG8_BAR __builtin_amdgcn_s_barrier()
; #define PG8_SCHED __builtin_amdgcn_sched_barrier(0)
; template <class Epi, class Sched, bool ALIGN_EPI = false, bool SP2 = false>
; __device__ __forceinline__ void gemm_phase(PG8_LAS unsigned char* lds, const Gemm g, const Sched& S, const Epi& E, const int tid_in) {
;     ...
;             const bool last = (t == nt - 2);
;             const char* a1 = cA + (size_t)(t + 1) * kstep;
;             const char* a2 = last ? nA : cA + (size_t)(t + 2) * kstep; const char* b2 = last ? nB : cB + (size_t)(t + 2) * kstep;
;             const char* a3 = a2 + kstep; const char* b3 = b2 + kstep;
;             if (last && has_next) S.a_ready(nxt);
;             if constexpr (SP2) {
;             PG8_LDB(B0, 0, 0); PG8_LDB(B1, 0, 1); PG8_SCHED; PG8_LDA(At, 0, 0); PG8_STAGE(PG8_SA(1, 1), a1 + hstepA, voffA);
;             PG8_WAIT_V(8); PG8_WAIT_L(0); PG8_BAR; PG8_MMA(0, 0, At, B0); PG8_MMA(0, 1, At, B1); PG8_BAR; PG8_SCHED;
;             PG8_LDA(At, 0, 1); PG8_STAGE(PG8_SB(0, 0), b2, voffB); PG8_STAGE(PG8_SB(0, 1), b2 + hstepB, voffB); PG8_STAGE(PG8_SA(0, 0), a2, voffA);
;             PG8_WAIT_V(8); PG8_WAIT_L(0); PG8_BAR; PG8_MMA(1, 0, At, B0); PG8_MMA(1, 1, At, B1); PG8_BAR; PG8_SCHED;
.LBB0_756:
	s_add_u32 s22, s36, 0x100
	s_addc_u32 s23, s37, 0
	s_add_i32 s34, 0, 0x10000
	s_cmp_eq_u32 s33, 2
	s_cselect_b32 s45, s73, s23
	s_cselect_b32 s44, s72, s22
	s_cselect_b32 s43, s77, s21
	s_cselect_b32 s42, s76, s12
	s_add_i32 s46, 0, 0x14000
	ds_read_b128 v[88:91], v249
	ds_read_b128 v[92:95], v249 offset:1024
	ds_read_b128 v[96:99], v249 offset:2048
	ds_read_b128 v[146:149], v249 offset:3072
	ds_read_b128 v[150:153], v249 offset:16384
	ds_read_b128 v[154:157], v249 offset:17408
	ds_read_b128 v[158:161], v249 offset:18432
	ds_read_b128 v[162:165], v249 offset:19456
	s_add_i32 m0, s74, 0xc000
	ds_read_b128 v[166:169], v192
	ds_read_b128 v[194:197], v192 offset:1024
	ds_read_b128 v[198:201], v192 offset:2048
	ds_read_b128 v[202:205], v192 offset:3072
	ds_read_b128 v[206:209], v192 offset:4096
	ds_read_b128 v[210:213], v192 offset:5120
	ds_read_b128 v[224:227], v192 offset:6144
	ds_read_b128 v[228:231], v192 offset:7168
	global_load_lds_dwordx4 v142, s[36:37]
	s_add_i32 m0, s74, 0xe000
	s_nop 0
	global_load_lds_dwordx4 v144, s[36:37]
	s_waitcnt vmcnt(8)
	s_waitcnt lgkmcnt(0)
	s_barrier
	s_waitcnt lgkmcnt(0)
	v_mfma_f32_16x16x32_bf16 v[136:139], v[88:91], v[166:169], v[136:139]
	v_mfma_f32_16x16x32_bf16 v[60:63], v[96:99], v[166:169], v[60:63]
	v_mfma_f32_16x16x32_bf16 v[128:131], v[88:91], v[198:201], v[128:131]
	v_mfma_f32_16x16x32_bf16 v[52:55], v[96:99], v[198:201], v[52:55]
	v_mfma_f32_16x16x32_bf16 v[120:123], v[88:91], v[206:209], v[120:123]
	v_mfma_f32_16x16x32_bf16 v[44:47], v[96:99], v[206:209], v[44:47]
	v_mfma_f32_16x16x32_bf16 v[112:115], v[88:91], v[224:227], v[112:115]
	v_mfma_f32_16x16x32_bf16 v[36:39], v[96:99], v[224:227], v[36:39]
	v_mfma_f32_16x16x32_bf16 v[136:139], v[92:95], v[194:197], v[136:139]
	v_mfma_f32_16x16x32_bf16 v[60:63], v[146:149], v[194:197], v[60:63]
	v_mfma_f32_16x16x32_bf16 v[128:131], v[92:95], v[202:205], v[128:131]
	v_mfma_f32_16x16x32_bf16 v[52:55], v[146:149], v[202:205], v[52:55]
	v_mfma_f32_16x16x32_bf16 v[120:123], v[92:95], v[210:213], v[120:123]
	v_mfma_f32_16x16x32_bf16 v[44:47], v[146:149], v[210:213], v[44:47]
	v_mfma_f32_16x16x32_bf16 v[112:115], v[92:95], v[228:231], v[112:115]
	v_mfma_f32_16x16x32_bf16 v[36:39], v[146:149], v[228:231], v[36:39]
	v_mfma_f32_16x16x32_bf16 v[132:135], v[150:153], v[166:169], v[132:135]
	v_mfma_f32_16x16x32_bf16 v[56:59], v[158:161], v[166:169], v[56:59]
	v_mfma_f32_16x16x32_bf16 v[124:127], v[150:153], v[198:201], v[124:127]
	v_mfma_f32_16x16x32_bf16 v[48:51], v[158:161], v[198:201], v[48:51]
	v_mfma_f32_16x16x32_bf16 v[116:119], v[150:153], v[206:209], v[116:119]
	v_mfma_f32_16x16x32_bf16 v[40:43], v[158:161], v[206:209], v[40:43]
	v_mfma_f32_16x16x32_bf16 v[108:111], v[150:153], v[224:227], v[108:111]
	v_mfma_f32_16x16x32_bf16 v[32:35], v[158:161], v[224:227], v[32:35]
	v_mfma_f32_16x16x32_bf16 v[132:135], v[154:157], v[194:197], v[132:135]
	v_mfma_f32_16x16x32_bf16 v[56:59], v[162:165], v[194:197], v[56:59]
	v_mfma_f32_16x16x32_bf16 v[124:127], v[154:157], v[202:205], v[124:127]
	v_mfma_f32_16x16x32_bf16 v[48:51], v[162:165], v[202:205], v[48:51]
	v_mfma_f32_16x16x32_bf16 v[116:119], v[154:157], v[210:213], v[116:119]
	v_mfma_f32_16x16x32_bf16 v[40:43], v[162:165], v[210:213], v[40:43]
	v_mfma_f32_16x16x32_bf16 v[108:111], v[154:157], v[228:231], v[108:111]
	v_mfma_f32_16x16x32_bf16 v[32:35], v[162:165], v[228:231], v[32:35]
	s_barrier
	s_add_i32 s34, s34, s38
	s_mov_b32 m0, s34
	ds_read_b128 v[166:169], v192 offset:16384
	ds_read_b128 v[194:197], v192 offset:17408
	ds_read_b128 v[198:201], v192 offset:18432
	ds_read_b128 v[202:205], v192 offset:19456
	ds_read_b128 v[206:209], v192 offset:20480
	ds_read_b128 v[210:213], v192 offset:21504
	ds_read_b128 v[224:227], v192 offset:22528
	ds_read_b128 v[228:231], v192 offset:23552
	global_load_lds_dwordx4 v172, s[42:43]
	s_add_i32 m0, s34, 0x2000
	s_add_u32 s34, s42, 0xa0000
	s_addc_u32 s35, s43, 0
	s_add_i32 s36, s46, s38
	global_load_lds_dwordx4 v140, s[42:43]
	s_mov_b32 m0, s36
	s_nop 0
	global_load_lds_dwordx4 v172, s[34:35]
	s_add_i32 m0, s36, 0x2000
	s_nop 0
	global_load_lds_dwordx4 v140, s[34:35]
	s_mov_b32 m0, s74
	s_nop 0
	global_load_lds_dwordx4 v172, s[44:45]
	s_mov_b32 m0, s75
	s_nop 0
	global_load_lds_dwordx4 v140, s[44:45]
	s_waitcnt vmcnt(8)
	s_waitcnt lgkmcnt(0)
	s_barrier
	s_waitcnt lgkmcnt(0)
	v_mfma_f32_16x16x32_bf16 v[104:107], v[88:91], v[166:169], v[104:107]
	v_mfma_f32_16x16x32_bf16 v[28:31], v[96:99], v[166:169], v[28:31]
	v_mfma_f32_16x16x32_bf16 v[84:87], v[88:91], v[198:201], v[84:87]
	v_mfma_f32_16x16x32_bf16 v[20:23], v[96:99], v[198:201], v[20:23]
	v_mfma_f32_16x16x32_bf16 v[76:79], v[88:91], v[206:209], v[76:79]
	v_mfma_f32_16x16x32_bf16 v[12:15], v[96:99], v[206:209], v[12:15]
	v_mfma_f32_16x16x32_bf16 v[68:71], v[88:91], v[224:227], v[68:71]
	v_mfma_f32_16x16x32_bf16 v[4:7], v[96:99], v[224:227], v[4:7]
	v_mfma_f32_16x16x32_bf16 v[104:107], v[92:95], v[194:197], v[104:107]
	v_mfma_f32_16x16x32_bf16 v[28:31], v[146:149], v[194:197], v[28:31]
	v_mfma_f32_16x16x32_bf16 v[84:87], v[92:95], v[202:205], v[84:87]
	v_mfma_f32_16x16x32_bf16 v[20:23], v[146:149], v[202:205], v[20:23]
	v_mfma_f32_16x16x32_bf16 v[76:79], v[92:95], v[210:213], v[76:79]
	v_mfma_f32_16x16x32_bf16 v[12:15], v[146:149], v[210:213], v[12:15]
	v_mfma_f32_16x16x32_bf16 v[68:71], v[92:95], v[228:231], v[68:71]
	v_mfma_f32_16x16x32_bf16 v[4:7], v[146:149], v[228:231], v[4:7]
	v_mfma_f32_16x16x32_bf16 v[24:27], v[158:161], v[166:169], v[24:27]
	v_mfma_f32_16x16x32_bf16 v[80:83], v[150:153], v[198:201], v[80:83]
	v_mfma_f32_16x16x32_bf16 v[16:19], v[158:161], v[198:201], v[16:19]
	v_mfma_f32_16x16x32_bf16 v[72:75], v[150:153], v[206:209], v[72:75]
	v_mfma_f32_16x16x32_bf16 v[8:11], v[158:161], v[206:209], v[8:11]
	v_mfma_f32_16x16x32_bf16 v[64:67], v[150:153], v[224:227], v[64:67]
	v_mfma_f32_16x16x32_bf16 v[0:3], v[158:161], v[224:227], v[0:3]
	v_mfma_f32_16x16x32_bf16 v[88:91], v[150:153], v[166:169], v[100:103]
	v_mfma_f32_16x16x32_bf16 v[24:27], v[162:165], v[194:197], v[24:27]
	v_mfma_f32_16x16x32_bf16 v[80:83], v[154:157], v[202:205], v[80:83]
	v_mfma_f32_16x16x32_bf16 v[16:19], v[162:165], v[202:205], v[16:19]
	v_mfma_f32_16x16x32_bf16 v[72:75], v[154:157], v[210:213], v[72:75]
	v_mfma_f32_16x16x32_bf16 v[8:11], v[162:165], v[210:213], v[8:11]
	v_mfma_f32_16x16x32_bf16 v[64:67], v[154:157], v[228:231], v[64:67]
	v_mfma_f32_16x16x32_bf16 v[0:3], v[162:165], v[228:231], v[0:3]
	v_mfma_f32_16x16x32_bf16 v[88:91], v[154:157], v[194:197], v[88:91]
	s_barrier
; #define PG8_STAGE(bufoff, gbase, voff) do { _Pragma("unroll") for (int _i = 0; _i < 2; ++_i) \
;         __builtin_amdgcn_global_load_lds((const unsigned*)((const char*)(gbase) + (voff)[_i]), (PG8_LAS unsigned*)(lds + (bufoff) + ldsw + _i * 8192), 16, 0, 0); } while (0)
; #define PG8_LDA(dst, b, h) do { _Pragma("unroll") for (int m = 0; m < 4; ++m) _Pragma("unroll") for (int k = 0; k < 2; ++k) dst[m][k] = *(const PG8_LAS bf16x8*)(lds + PG8_SA(b, h) + aoff + m * 2048 + k * 1024); } while (0)
; #define PG8_LDB(dst, b, h) do { _Pragma("unroll") for (int n = 0; n < 2; ++n) _Pragma("unroll") for (int k = 0; k < 2; ++k) dst[n][k] = *(const PG8_LAS bf16x8*)(lds + PG8_SB(b, h) + boff + n * 2048 + k * 1024); } while (0)
; #define PG8_MMA(ai, bj, At, Bt) do { __builtin_amdgcn_s_setprio(1); _Pragma("unroll") for (int m = 0; m < 4; ++m) _Pragma("unroll") for (int n = 0; n < 2; ++n) _Pragma("unroll") for (int k = 0; k < 2; ++k) \
;         acc[ai][bj][m][n] = __builtin_amdgcn_mfma_f32_16x16x32_bf16(Bt[n][k], At[m][k], acc[ai][bj][m][n], 0, 0, 0); __builtin_amdgcn_s_setprio(0); } while (0)
; #define PG8_WAIT_V(n) asm volatile("s_waitcnt vmcnt(" #n ")" ::: "memory")
; #define PG8_WAIT_L(n) asm volatile("s_waitcnt lgkmcnt(" #n ")" ::: "memory")
; #define PG8_BAR __builtin_amdgcn_s_barrier()
; #define PG8_SCHED __builtin_amdgcn_sched_barrier(0)
; template <class Epi, class Sched, bool ALIGN_EPI = false, bool SP2 = false>
; __device__ __forceinline__ void gemm_phase(PG8_LAS unsigned char* lds, const Gemm g, const Sched& S, const Epi& E, const int tid_in) {
;     ...
;             PG8_LDB(B0, 1, 0); PG8_LDB(B1, 1, 1); PG8_SCHED; PG8_LDA(At, 1, 0); PG8_STAGE(PG8_SA(0, 1), a2 + hstepA, voffA);
;             PG8_WAIT_V(8); PG8_WAIT_L(0); PG8_BAR; PG8_MMA(0, 0, At, B0); PG8_MMA(0, 1, At, B1); PG8_BAR; PG8_SCHED;
;             PG8_LDA(At, 1, 1); PG8_STAGE(PG8_SB(1, 0), b3, voffB); PG8_STAGE(PG8_SB(1, 1), b3 + hstepB, voffB); PG8_STAGE(PG8_SA(1, 0), a3, voffA);
;             PG8_WAIT_V(8); PG8_WAIT_L(0); PG8_BAR; PG8_MMA(1, 0, At, B0); PG8_MMA(1, 1, At, B1); PG8_BAR; PG8_SCHED;
	s_add_i32 s36, 0, 0x18000
	s_add_i32 s37, 0, 0x1c000
	ds_read_b128 v[92:95], v249 offset:32768
	ds_read_b128 v[96:99], v249 offset:33792
	ds_read_b128 v[100:103], v249 offset:34816
	ds_read_b128 v[146:149], v249 offset:35840
	ds_read_b128 v[150:153], v249 offset:49152
	ds_read_b128 v[154:157], v249 offset:50176
	ds_read_b128 v[158:161], v249 offset:51200
	ds_read_b128 v[162:165], v249 offset:52224
	s_add_u32 s34, s44, 0xa0000
	s_addc_u32 s35, s45, 0
	s_mov_b32 m0, s60
	ds_read_b128 v[166:169], v192 offset:32768
	ds_read_b128 v[194:197], v192 offset:33792
	ds_read_b128 v[198:201], v192 offset:34816
	ds_read_b128 v[202:205], v192 offset:35840
	ds_read_b128 v[206:209], v192 offset:36864
	ds_read_b128 v[210:213], v192 offset:37888
	ds_read_b128 v[224:227], v192 offset:38912
	ds_read_b128 v[228:231], v192 offset:39936
	global_load_lds_dwordx4 v172, s[34:35]
	s_mov_b32 m0, s61
	s_nop 0
	global_load_lds_dwordx4 v140, s[34:35]
	s_waitcnt vmcnt(8)
	s_waitcnt lgkmcnt(0)
	s_barrier
	s_waitcnt lgkmcnt(0)
	v_mfma_f32_16x16x32_bf16 v[136:139], v[92:95], v[166:169], v[136:139]
	v_mfma_f32_16x16x32_bf16 v[60:63], v[100:103], v[166:169], v[60:63]
	v_mfma_f32_16x16x32_bf16 v[128:131], v[92:95], v[198:201], v[128:131]
	v_mfma_f32_16x16x32_bf16 v[52:55], v[100:103], v[198:201], v[52:55]
	v_mfma_f32_16x16x32_bf16 v[120:123], v[92:95], v[206:209], v[120:123]
	v_mfma_f32_16x16x32_bf16 v[44:47], v[100:103], v[206:209], v[44:47]
	v_mfma_f32_16x16x32_bf16 v[112:115], v[92:95], v[224:227], v[112:115]
	v_mfma_f32_16x16x32_bf16 v[36:39], v[100:103], v[224:227], v[36:39]
	v_mfma_f32_16x16x32_bf16 v[136:139], v[96:99], v[194:197], v[136:139]
	v_mfma_f32_16x16x32_bf16 v[60:63], v[146:149], v[194:197], v[60:63]
	v_mfma_f32_16x16x32_bf16 v[128:131], v[96:99], v[202:205], v[128:131]
	v_mfma_f32_16x16x32_bf16 v[52:55], v[146:149], v[202:205], v[52:55]
	v_mfma_f32_16x16x32_bf16 v[120:123], v[96:99], v[210:213], v[120:123]
	v_mfma_f32_16x16x32_bf16 v[44:47], v[146:149], v[210:213], v[44:47]
	v_mfma_f32_16x16x32_bf16 v[112:115], v[96:99], v[228:231], v[112:115]
	v_mfma_f32_16x16x32_bf16 v[36:39], v[146:149], v[228:231], v[36:39]
	v_mfma_f32_16x16x32_bf16 v[132:135], v[150:153], v[166:169], v[132:135]
	v_mfma_f32_16x16x32_bf16 v[56:59], v[158:161], v[166:169], v[56:59]
	v_mfma_f32_16x16x32_bf16 v[124:127], v[150:153], v[198:201], v[124:127]
	v_mfma_f32_16x16x32_bf16 v[48:51], v[158:161], v[198:201], v[48:51]
	v_mfma_f32_16x16x32_bf16 v[116:119], v[150:153], v[206:209], v[116:119]
	v_mfma_f32_16x16x32_bf16 v[40:43], v[158:161], v[206:209], v[40:43]
	v_mfma_f32_16x16x32_bf16 v[108:111], v[150:153], v[224:227], v[108:111]
	v_mfma_f32_16x16x32_bf16 v[32:35], v[158:161], v[224:227], v[32:35]
	v_mfma_f32_16x16x32_bf16 v[132:135], v[154:157], v[194:197], v[132:135]
	v_mfma_f32_16x16x32_bf16 v[56:59], v[162:165], v[194:197], v[56:59]
	v_mfma_f32_16x16x32_bf16 v[124:127], v[154:157], v[202:205], v[124:127]
	v_mfma_f32_16x16x32_bf16 v[48:51], v[162:165], v[202:205], v[48:51]
	v_mfma_f32_16x16x32_bf16 v[116:119], v[154:157], v[210:213], v[116:119]
	v_mfma_f32_16x16x32_bf16 v[40:43], v[162:165], v[210:213], v[40:43]
	v_mfma_f32_16x16x32_bf16 v[108:111], v[154:157], v[228:231], v[108:111]
	v_mfma_f32_16x16x32_bf16 v[32:35], v[162:165], v[228:231], v[32:35]
	s_barrier
	s_add_i32 s34, s36, s38
	s_mov_b32 m0, s34
	ds_read_b128 v[166:169], v192 offset:49152
	ds_read_b128 v[194:197], v192 offset:50176
	ds_read_b128 v[198:201], v192 offset:51200
	ds_read_b128 v[202:205], v192 offset:52224
	ds_read_b128 v[206:209], v192 offset:53248
	ds_read_b128 v[210:213], v192 offset:54272
	ds_read_b128 v[224:227], v192 offset:55296
	ds_read_b128 v[228:231], v192 offset:56320
	s_add_u32 s100, s42, 0x80
	s_addc_u32 s101, s43, 0
	global_load_lds_dwordx4 v172, s[100:101]
	s_add_i32 m0, s34, 0x2000
	s_add_u32 s34, s42, 0xa0080
	s_addc_u32 s35, s43, 0
	s_add_i32 s36, s37, s38
	global_load_lds_dwordx4 v140, s[100:101]
	s_mov_b32 m0, s36
	s_nop 0
	global_load_lds_dwordx4 v172, s[34:35]
	s_add_i32 m0, s36, 0x2000
	s_nop 0
	global_load_lds_dwordx4 v140, s[34:35]
	s_mov_b32 m0, s58
	s_nop 0
	s_add_u32 s100, s44, 0x80
	s_addc_u32 s101, s45, 0
	global_load_lds_dwordx4 v172, s[100:101]
	s_mov_b32 m0, s59
	s_nop 0
	global_load_lds_dwordx4 v140, s[100:101]
	s_waitcnt vmcnt(8)
	s_waitcnt lgkmcnt(0)
	s_barrier
	s_waitcnt lgkmcnt(0)
	v_mfma_f32_16x16x32_bf16 v[104:107], v[92:95], v[166:169], v[104:107]
	v_mfma_f32_16x16x32_bf16 v[28:31], v[100:103], v[166:169], v[28:31]
	v_mfma_f32_16x16x32_bf16 v[84:87], v[92:95], v[198:201], v[84:87]
	v_mfma_f32_16x16x32_bf16 v[20:23], v[100:103], v[198:201], v[20:23]
	v_mfma_f32_16x16x32_bf16 v[76:79], v[92:95], v[206:209], v[76:79]
	v_mfma_f32_16x16x32_bf16 v[12:15], v[100:103], v[206:209], v[12:15]
	v_mfma_f32_16x16x32_bf16 v[68:71], v[92:95], v[224:227], v[68:71]
	v_mfma_f32_16x16x32_bf16 v[4:7], v[100:103], v[224:227], v[4:7]
	v_mfma_f32_16x16x32_bf16 v[104:107], v[96:99], v[194:197], v[104:107]
	v_mfma_f32_16x16x32_bf16 v[28:31], v[146:149], v[194:197], v[28:31]
	v_mfma_f32_16x16x32_bf16 v[84:87], v[96:99], v[202:205], v[84:87]
	v_mfma_f32_16x16x32_bf16 v[20:23], v[146:149], v[202:205], v[20:23]
	v_mfma_f32_16x16x32_bf16 v[76:79], v[96:99], v[210:213], v[76:79]
	v_mfma_f32_16x16x32_bf16 v[12:15], v[146:149], v[210:213], v[12:15]
	v_mfma_f32_16x16x32_bf16 v[68:71], v[96:99], v[228:231], v[68:71]
	v_mfma_f32_16x16x32_bf16 v[4:7], v[146:149], v[228:231], v[4:7]
	v_mfma_f32_16x16x32_bf16 v[88:91], v[150:153], v[166:169], v[88:91]
	v_mfma_f32_16x16x32_bf16 v[24:27], v[158:161], v[166:169], v[24:27]
	v_mfma_f32_16x16x32_bf16 v[80:83], v[150:153], v[198:201], v[80:83]
	v_mfma_f32_16x16x32_bf16 v[16:19], v[158:161], v[198:201], v[16:19]
	v_mfma_f32_16x16x32_bf16 v[72:75], v[150:153], v[206:209], v[72:75]
	v_mfma_f32_16x16x32_bf16 v[8:11], v[158:161], v[206:209], v[8:11]
	v_mfma_f32_16x16x32_bf16 v[64:67], v[150:153], v[224:227], v[64:67]
	v_mfma_f32_16x16x32_bf16 v[0:3], v[158:161], v[224:227], v[0:3]
	v_mfma_f32_16x16x32_bf16 v[100:103], v[154:157], v[194:197], v[88:91]
	v_mfma_f32_16x16x32_bf16 v[24:27], v[162:165], v[194:197], v[24:27]
	v_mfma_f32_16x16x32_bf16 v[80:83], v[154:157], v[202:205], v[80:83]
	v_mfma_f32_16x16x32_bf16 v[16:19], v[162:165], v[202:205], v[16:19]
	v_mfma_f32_16x16x32_bf16 v[72:75], v[154:157], v[210:213], v[72:75]
	v_mfma_f32_16x16x32_bf16 v[8:11], v[162:165], v[210:213], v[8:11]
	v_mfma_f32_16x16x32_bf16 v[64:67], v[154:157], v[228:231], v[64:67]
	v_mfma_f32_16x16x32_bf16 v[0:3], v[162:165], v[228:231], v[0:3]
	s_barrier
	s_add_i32 s33, s33, 2
	s_add_u32 s12, s12, 0x100
	s_addc_u32 s21, s21, 0
	s_cmp_gt_u32 s33, 3
	s_mov_b64 s[36:37], s[22:23]
	s_cbranch_scc0 .LBB0_756
	s_and_b64 vcc, exec, s[70:71]
	s_cbranch_vccz .LBB0_759
	s_barrier

;     __device__ __forceinline__ void a_ready(const Unit& u) const { wait_panel(cnt, u.pm, need, tmo, wave); }
;     __device__ __forceinline__ void a_ready(const Unit& u) const { wait_panel(cnt, u.pm, need, tmo, wave); }
; #define PG8_STAGE(bufoff, gbase, voff) do { _Pragma("unroll") for (int _i = 0; _i < 2; ++_i) \
;         __builtin_amdgcn_global_load_lds((const unsigned*)((const char*)(gbase) + (voff)[_i]), (PG8_LAS unsigned*)(lds + (bufoff) + ldsw + _i * 8192), 16, 0, 0); } while (0)
; #define PG8_LDA(dst, b, h) do { _Pragma("unroll") for (int m = 0; m < 4; ++m) _Pragma("unroll") for (int k = 0; k < 2; ++k) dst[m][k] = *(const PG8_LAS bf16x8*)(lds + PG8_SA(b, h) + aoff + m * 2048 + k * 1024); } while (0)
; #define PG8_LDB(dst, b, h) do { _Pragma("unroll") for (int n = 0; n < 2; ++n) _Pragma("unroll") for (int k = 0; k < 2; ++k) dst[n][k] = *(const PG8_LAS bf16x8*)(lds + PG8_SB(b, h) + boff + n * 2048 + k * 1024); } while (0)
; #define PG8_WAIT_V(n) asm volatile("s_waitcnt vmcnt(" #n ")" ::: "memory")
; #define PG8_WAIT_L(n) asm volatile("s_waitcnt lgkmcnt(" #n ")" ::: "memory")
; #define PG8_BAR __builtin_amdgcn_s_barrier()
; #define PG8_SCHED __builtin_amdgcn_sched_barrier(0)
; template <class Epi, class Sched, bool ALIGN_EPI = false, bool SP2 = false>
; __device__ __forceinline__ void gemm_phase(PG8_LAS unsigned char* lds, const Gemm g, const Sched& S, const Epi& E, const int tid_in) {
;     ...
;             const bool last = (t == nt - 2);
;             const char* a1 = cA + (size_t)(t + 1) * kstep;
;             const char* a2 = last ? nA : cA + (size_t)(t + 2) * kstep; const char* b2 = last ? nB : cB + (size_t)(t + 2) * kstep;
;             const char* a3 = a2 + kstep; const char* b3 = b2 + kstep;
;             if (last && has_next) S.a_ready(nxt);
;             if constexpr (SP2) {
;             PG8_LDB(B0, 0, 0); PG8_LDB(B1, 0, 1); PG8_SCHED; PG8_LDA(At, 0, 0); PG8_STAGE(PG8_SA(1, 1), a1 + hstepA, voffA);
;             PG8_WAIT_V(8); PG8_WAIT_L(0); PG8_BAR; PG8_MMA(0, 0, At, B0); PG8_MMA(0, 1, At, B1); PG8_BAR; PG8_SCHED;
;             PG8_LDA(At, 0, 1); PG8_STAGE(PG8_SB(0, 0), b2, voffB); PG8_STAGE(PG8_SB(0, 1), b2 + hstepB, voffB); PG8_STAGE(PG8_SA(0, 0), a2, voffA);
;             PG8_WAIT_V(8); PG8_WAIT_L(0); PG8_BAR; PG8_MMA(1, 0, At, B0); PG8_MMA(1, 1, At, B1); PG8_BAR; PG8_SCHED;
.LBB0_1268:
	s_add_u32 s22, s50, 0x100
	s_addc_u32 s23, s51, 0
	s_add_i32 s63, 0, 0x10000
	s_cmp_eq_u32 s62, 36
	s_cselect_b32 s55, s43, s23
	s_cselect_b32 s54, s42, s22
	s_cselect_b32 s53, s49, s61
	s_cselect_b32 s52, s48, s60
	s_add_i32 s64, 0, 0x14000
	ds_read_b128 v[104:107], v249
	ds_read_b128 v[108:111], v249 offset:1024
	ds_read_b128 v[112:115], v249 offset:2048
	ds_read_b128 v[116:119], v249 offset:3072
	ds_read_b128 v[144:147], v249 offset:16384
	ds_read_b128 v[148:151], v249 offset:17408
	ds_read_b128 v[152:155], v249 offset:18432
	ds_read_b128 v[156:159], v249 offset:19456
	s_add_i32 m0, s30, 0xc000
	ds_read_b128 v[160:163], v204
	ds_read_b128 v[192:195], v204 offset:1024
	ds_read_b128 v[196:199], v204 offset:2048
	ds_read_b128 v[206:209], v204 offset:3072
	ds_read_b128 v[210:213], v204 offset:4096
	ds_read_b128 v[224:227], v204 offset:5120
	ds_read_b128 v[228:231], v204 offset:6144
	ds_read_b128 v[232:235], v204 offset:7168
	global_load_lds_dwordx4 v170, s[50:51]
	s_add_i32 m0, s30, 0xe000
	s_nop 0
	global_load_lds_dwordx4 v190, s[50:51]
	s_waitcnt vmcnt(8)
	s_waitcnt lgkmcnt(0)
	s_barrier
	s_waitcnt lgkmcnt(0)
	v_mfma_f32_16x16x32_bf16 v[140:143], v[104:107], v[160:163], v[140:143]
	v_mfma_f32_16x16x32_bf16 v[136:139], v[112:115], v[160:163], v[136:139]
	v_mfma_f32_16x16x32_bf16 v[124:127], v[104:107], v[196:199], v[124:127]
	v_mfma_f32_16x16x32_bf16 v[120:123], v[112:115], v[196:199], v[120:123]
	v_mfma_f32_16x16x32_bf16 v[92:95], v[104:107], v[210:213], v[92:95]
	v_mfma_f32_16x16x32_bf16 v[88:91], v[112:115], v[210:213], v[88:91]
	v_mfma_f32_16x16x32_bf16 v[76:79], v[104:107], v[228:231], v[76:79]
	v_mfma_f32_16x16x32_bf16 v[72:75], v[112:115], v[228:231], v[72:75]
	v_mfma_f32_16x16x32_bf16 v[140:143], v[108:111], v[192:195], v[140:143]
	v_mfma_f32_16x16x32_bf16 v[136:139], v[116:119], v[192:195], v[136:139]
	v_mfma_f32_16x16x32_bf16 v[124:127], v[108:111], v[206:209], v[124:127]
	v_mfma_f32_16x16x32_bf16 v[120:123], v[116:119], v[206:209], v[120:123]
	v_mfma_f32_16x16x32_bf16 v[92:95], v[108:111], v[224:227], v[92:95]
	v_mfma_f32_16x16x32_bf16 v[88:91], v[116:119], v[224:227], v[88:91]
	v_mfma_f32_16x16x32_bf16 v[76:79], v[108:111], v[232:235], v[76:79]
	v_mfma_f32_16x16x32_bf16 v[72:75], v[116:119], v[232:235], v[72:75]
	v_mfma_f32_16x16x32_bf16 v[132:135], v[144:147], v[160:163], v[132:135]
	v_mfma_f32_16x16x32_bf16 v[128:131], v[152:155], v[160:163], v[128:131]
	v_mfma_f32_16x16x32_bf16 v[100:103], v[144:147], v[196:199], v[100:103]
	v_mfma_f32_16x16x32_bf16 v[96:99], v[152:155], v[196:199], v[96:99]
	v_mfma_f32_16x16x32_bf16 v[84:87], v[144:147], v[210:213], v[84:87]
	v_mfma_f32_16x16x32_bf16 v[80:83], v[152:155], v[210:213], v[80:83]
	v_mfma_f32_16x16x32_bf16 v[68:71], v[144:147], v[228:231], v[68:71]
	v_mfma_f32_16x16x32_bf16 v[64:67], v[152:155], v[228:231], v[64:67]
	v_mfma_f32_16x16x32_bf16 v[132:135], v[148:151], v[192:195], v[132:135]
	v_mfma_f32_16x16x32_bf16 v[128:131], v[156:159], v[192:195], v[128:131]
	v_mfma_f32_16x16x32_bf16 v[100:103], v[148:151], v[206:209], v[100:103]
	v_mfma_f32_16x16x32_bf16 v[96:99], v[156:159], v[206:209], v[96:99]
	v_mfma_f32_16x16x32_bf16 v[84:87], v[148:151], v[224:227], v[84:87]
	v_mfma_f32_16x16x32_bf16 v[80:83], v[156:159], v[224:227], v[80:83]
	v_mfma_f32_16x16x32_bf16 v[68:71], v[148:151], v[232:235], v[68:71]
	v_mfma_f32_16x16x32_bf16 v[64:67], v[156:159], v[232:235], v[64:67]
	s_barrier
	s_add_i32 s50, s63, s21
	s_mov_b32 m0, s50
	ds_read_b128 v[160:163], v204 offset:16384
	ds_read_b128 v[192:195], v204 offset:17408
	ds_read_b128 v[196:199], v204 offset:18432
	ds_read_b128 v[206:209], v204 offset:19456
	ds_read_b128 v[210:213], v204 offset:20480
	ds_read_b128 v[224:227], v204 offset:21504
	ds_read_b128 v[228:231], v204 offset:22528
	ds_read_b128 v[232:235], v204 offset:23552
	global_load_lds_dwordx4 v172, s[52:53]
	s_add_i32 m0, s50, 0x2000
	s_add_u32 s50, s52, 0xa0000
	s_addc_u32 s51, s53, 0
	s_add_u32 vcc_lo, s52, 0x80
	s_addc_u32 vcc_hi, s53, 0
	s_add_i32 s63, s64, s21
	global_load_lds_dwordx4 v168, s[52:53]
	s_mov_b32 m0, s63
	s_nop 0
	global_load_lds_dwordx4 v172, s[50:51]
	s_add_i32 m0, s63, 0x2000
	s_nop 0
	global_load_lds_dwordx4 v168, s[50:51]
	s_mov_b32 m0, s30
	s_nop 0
	global_load_lds_dwordx4 v164, s[54:55]
	s_mov_b32 m0, s31
	s_nop 0
	global_load_lds_dwordx4 v166, s[54:55]
	s_waitcnt vmcnt(8)
	s_waitcnt lgkmcnt(0)
	s_barrier
	s_waitcnt lgkmcnt(0)
	v_mfma_f32_16x16x32_bf16 v[60:63], v[104:107], v[160:163], v[60:63]
	v_mfma_f32_16x16x32_bf16 v[56:59], v[112:115], v[160:163], v[56:59]
	v_mfma_f32_16x16x32_bf16 v[44:47], v[104:107], v[196:199], v[44:47]
	v_mfma_f32_16x16x32_bf16 v[40:43], v[112:115], v[196:199], v[40:43]
	v_mfma_f32_16x16x32_bf16 v[28:31], v[104:107], v[210:213], v[28:31]
	v_mfma_f32_16x16x32_bf16 v[24:27], v[112:115], v[210:213], v[24:27]
	v_mfma_f32_16x16x32_bf16 v[12:15], v[104:107], v[228:231], v[12:15]
	v_mfma_f32_16x16x32_bf16 v[8:11], v[112:115], v[228:231], v[8:11]
	v_mfma_f32_16x16x32_bf16 v[60:63], v[108:111], v[192:195], v[60:63]
	v_mfma_f32_16x16x32_bf16 v[56:59], v[116:119], v[192:195], v[56:59]
	v_mfma_f32_16x16x32_bf16 v[44:47], v[108:111], v[206:209], v[44:47]
	v_mfma_f32_16x16x32_bf16 v[40:43], v[116:119], v[206:209], v[40:43]
	v_mfma_f32_16x16x32_bf16 v[28:31], v[108:111], v[224:227], v[28:31]
	v_mfma_f32_16x16x32_bf16 v[24:27], v[116:119], v[224:227], v[24:27]
	v_mfma_f32_16x16x32_bf16 v[12:15], v[108:111], v[232:235], v[12:15]
	v_mfma_f32_16x16x32_bf16 v[8:11], v[116:119], v[232:235], v[8:11]
	v_mfma_f32_16x16x32_bf16 v[52:55], v[144:147], v[160:163], v[52:55]
	v_mfma_f32_16x16x32_bf16 v[48:51], v[152:155], v[160:163], v[48:51]
	v_mfma_f32_16x16x32_bf16 v[36:39], v[144:147], v[196:199], v[36:39]
	v_mfma_f32_16x16x32_bf16 v[32:35], v[152:155], v[196:199], v[32:35]
	v_mfma_f32_16x16x32_bf16 v[20:23], v[144:147], v[210:213], v[20:23]
	v_mfma_f32_16x16x32_bf16 v[16:19], v[152:155], v[210:213], v[16:19]
	v_mfma_f32_16x16x32_bf16 v[4:7], v[144:147], v[228:231], v[4:7]
	v_mfma_f32_16x16x32_bf16 v[0:3], v[152:155], v[228:231], v[0:3]
	v_mfma_f32_16x16x32_bf16 v[52:55], v[148:151], v[192:195], v[52:55]
	v_mfma_f32_16x16x32_bf16 v[48:51], v[156:159], v[192:195], v[48:51]
	v_mfma_f32_16x16x32_bf16 v[36:39], v[148:151], v[206:209], v[36:39]
	v_mfma_f32_16x16x32_bf16 v[32:35], v[156:159], v[206:209], v[32:35]
	v_mfma_f32_16x16x32_bf16 v[20:23], v[148:151], v[224:227], v[20:23]
	v_mfma_f32_16x16x32_bf16 v[16:19], v[156:159], v[224:227], v[16:19]
	v_mfma_f32_16x16x32_bf16 v[4:7], v[148:151], v[232:235], v[4:7]
	v_mfma_f32_16x16x32_bf16 v[0:3], v[156:159], v[232:235], v[0:3]
	s_barrier
; #define PG8_STAGE(bufoff, gbase, voff) do { _Pragma("unroll") for (int _i = 0; _i < 2; ++_i) \
;         __builtin_amdgcn_global_load_lds((const unsigned*)((const char*)(gbase) + (voff)[_i]), (PG8_LAS unsigned*)(lds + (bufoff) + ldsw + _i * 8192), 16, 0, 0); } while (0)
; #define PG8_LDA(dst, b, h) do { _Pragma("unroll") for (int m = 0; m < 4; ++m) _Pragma("unroll") for (int k = 0; k < 2; ++k) dst[m][k] = *(const PG8_LAS bf16x8*)(lds + PG8_SA(b, h) + aoff + m * 2048 + k * 1024); } while (0)
; #define PG8_LDB(dst, b, h) do { _Pragma("unroll") for (int n = 0; n < 2; ++n) _Pragma("unroll") for (int k = 0; k < 2; ++k) dst[n][k] = *(const PG8_LAS bf16x8*)(lds + PG8_SB(b, h) + boff + n * 2048 + k * 1024); } while (0)
; #define PG8_MMA(ai, bj, At, Bt) do { __builtin_amdgcn_s_setprio(1); _Pragma("unroll") for (int m = 0; m < 4; ++m) _Pragma("unroll") for (int n = 0; n < 2; ++n) _Pragma("unroll") for (int k = 0; k < 2; ++k) \
;         acc[ai][bj][m][n] = __builtin_amdgcn_mfma_f32_16x16x32_bf16(Bt[n][k], At[m][k], acc[ai][bj][m][n], 0, 0, 0); __builtin_amdgcn_s_setprio(0); } while (0)
; #define PG8_WAIT_V(n) asm volatile("s_waitcnt vmcnt(" #n ")" ::: "memory")
; #define PG8_WAIT_L(n) asm volatile("s_waitcnt lgkmcnt(" #n ")" ::: "memory")
; #define PG8_BAR __builtin_amdgcn_s_barrier()
; #define PG8_SCHED __builtin_amdgcn_sched_barrier(0)
; template <class Epi, class Sched, bool ALIGN_EPI = false, bool SP2 = false>
; __device__ __forceinline__ void gemm_phase(PG8_LAS unsigned char* lds, const Gemm g, const Sched& S, const Epi& E, const int tid_in) {
;     ...
;             PG8_LDB(B0, 1, 0); PG8_LDB(B1, 1, 1); PG8_SCHED; PG8_LDA(At, 1, 0); PG8_STAGE(PG8_SA(0, 1), a2 + hstepA, voffA);
;             PG8_WAIT_V(8); PG8_WAIT_L(0); PG8_BAR; PG8_MMA(0, 0, At, B0); PG8_MMA(0, 1, At, B1); PG8_BAR; PG8_SCHED;
;             PG8_LDA(At, 1, 1); PG8_STAGE(PG8_SB(1, 0), b3, voffB); PG8_STAGE(PG8_SB(1, 1), b3 + hstepB, voffB); PG8_STAGE(PG8_SA(1, 0), a3, voffA);
;             PG8_WAIT_V(8); PG8_WAIT_L(0); PG8_BAR; PG8_MMA(1, 0, At, B0); PG8_MMA(1, 1, At, B1); PG8_BAR; PG8_SCHED;
	s_add_i32 s63, 0, 0x18000
	s_add_i32 s64, 0, 0x1c000
	ds_read_b128 v[104:107], v249 offset:32768
	ds_read_b128 v[108:111], v249 offset:33792
	ds_read_b128 v[112:115], v249 offset:34816
	ds_read_b128 v[116:119], v249 offset:35840
	ds_read_b128 v[144:147], v249 offset:49152
	ds_read_b128 v[148:151], v249 offset:50176
	ds_read_b128 v[152:155], v249 offset:51200
	ds_read_b128 v[156:159], v249 offset:52224
	s_add_u32 s50, s54, 0xa0000
	s_addc_u32 s51, s55, 0
	s_mov_b32 m0, s6
	ds_read_b128 v[160:163], v204 offset:32768
	ds_read_b128 v[192:195], v204 offset:33792
	ds_read_b128 v[196:199], v204 offset:34816
	ds_read_b128 v[206:209], v204 offset:35840
	ds_read_b128 v[210:213], v204 offset:36864
	ds_read_b128 v[224:227], v204 offset:37888
	ds_read_b128 v[228:231], v204 offset:38912
	ds_read_b128 v[232:235], v204 offset:39936
	global_load_lds_dwordx4 v164, s[50:51]
	s_mov_b32 m0, s38
	s_nop 0
	global_load_lds_dwordx4 v166, s[50:51]
	s_waitcnt vmcnt(8)
	s_waitcnt lgkmcnt(0)
	s_barrier
	s_waitcnt lgkmcnt(0)
	v_mfma_f32_16x16x32_bf16 v[140:143], v[104:107], v[160:163], v[140:143]
	v_mfma_f32_16x16x32_bf16 v[136:139], v[112:115], v[160:163], v[136:139]
	v_mfma_f32_16x16x32_bf16 v[124:127], v[104:107], v[196:199], v[124:127]
	v_mfma_f32_16x16x32_bf16 v[120:123], v[112:115], v[196:199], v[120:123]
	v_mfma_f32_16x16x32_bf16 v[92:95], v[104:107], v[210:213], v[92:95]
	v_mfma_f32_16x16x32_bf16 v[88:91], v[112:115], v[210:213], v[88:91]
	v_mfma_f32_16x16x32_bf16 v[76:79], v[104:107], v[228:231], v[76:79]
	v_mfma_f32_16x16x32_bf16 v[72:75], v[112:115], v[228:231], v[72:75]
	v_mfma_f32_16x16x32_bf16 v[140:143], v[108:111], v[192:195], v[140:143]
	v_mfma_f32_16x16x32_bf16 v[136:139], v[116:119], v[192:195], v[136:139]
	v_mfma_f32_16x16x32_bf16 v[124:127], v[108:111], v[206:209], v[124:127]
	v_mfma_f32_16x16x32_bf16 v[120:123], v[116:119], v[206:209], v[120:123]
	v_mfma_f32_16x16x32_bf16 v[92:95], v[108:111], v[224:227], v[92:95]
	v_mfma_f32_16x16x32_bf16 v[88:91], v[116:119], v[224:227], v[88:91]
	v_mfma_f32_16x16x32_bf16 v[76:79], v[108:111], v[232:235], v[76:79]
	v_mfma_f32_16x16x32_bf16 v[72:75], v[116:119], v[232:235], v[72:75]
	v_mfma_f32_16x16x32_bf16 v[132:135], v[144:147], v[160:163], v[132:135]
	v_mfma_f32_16x16x32_bf16 v[128:131], v[152:155], v[160:163], v[128:131]
	v_mfma_f32_16x16x32_bf16 v[100:103], v[144:147], v[196:199], v[100:103]
	v_mfma_f32_16x16x32_bf16 v[96:99], v[152:155], v[196:199], v[96:99]
	v_mfma_f32_16x16x32_bf16 v[84:87], v[144:147], v[210:213], v[84:87]
	v_mfma_f32_16x16x32_bf16 v[80:83], v[152:155], v[210:213], v[80:83]
	v_mfma_f32_16x16x32_bf16 v[68:71], v[144:147], v[228:231], v[68:71]
	v_mfma_f32_16x16x32_bf16 v[64:67], v[152:155], v[228:231], v[64:67]
	v_mfma_f32_16x16x32_bf16 v[132:135], v[148:151], v[192:195], v[132:135]
	v_mfma_f32_16x16x32_bf16 v[128:131], v[156:159], v[192:195], v[128:131]
	v_mfma_f32_16x16x32_bf16 v[100:103], v[148:151], v[206:209], v[100:103]
	v_mfma_f32_16x16x32_bf16 v[96:99], v[156:159], v[206:209], v[96:99]
	v_mfma_f32_16x16x32_bf16 v[84:87], v[148:151], v[224:227], v[84:87]
	v_mfma_f32_16x16x32_bf16 v[80:83], v[156:159], v[224:227], v[80:83]
	v_mfma_f32_16x16x32_bf16 v[68:71], v[148:151], v[232:235], v[68:71]
	v_mfma_f32_16x16x32_bf16 v[64:67], v[156:159], v[232:235], v[64:67]
	s_barrier
	s_add_i32 s50, s63, s21
	s_mov_b32 m0, s50
	ds_read_b128 v[160:163], v204 offset:49152
	ds_read_b128 v[192:195], v204 offset:50176
	ds_read_b128 v[196:199], v204 offset:51200
	ds_read_b128 v[206:209], v204 offset:52224
	ds_read_b128 v[210:213], v204 offset:53248
	ds_read_b128 v[224:227], v204 offset:54272
	ds_read_b128 v[228:231], v204 offset:55296
	ds_read_b128 v[232:235], v204 offset:56320
	s_add_u32 s100, s52, 0x80
	s_addc_u32 s101, s53, 0
	global_load_lds_dwordx4 v172, s[100:101]
	s_add_i32 m0, s50, 0x2000
	s_add_u32 s50, s52, 0xa0080
	s_addc_u32 s51, s53, 0
	s_add_i32 s52, s64, s21
	global_load_lds_dwordx4 v168, vcc
	s_mov_b32 m0, s52
	s_nop 0
	global_load_lds_dwordx4 v172, s[50:51]
	s_add_i32 m0, s52, 0x2000
	s_nop 0
	global_load_lds_dwordx4 v168, s[50:51]
	s_mov_b32 m0, s33
	s_nop 0
	s_add_u32 s100, s54, 0x80
	s_addc_u32 s101, s55, 0
	global_load_lds_dwordx4 v164, s[100:101]
	s_mov_b32 m0, s35
	s_nop 0
	global_load_lds_dwordx4 v166, s[100:101]
	s_waitcnt vmcnt(8)
	s_waitcnt lgkmcnt(0)
	s_barrier
	s_waitcnt lgkmcnt(0)
	v_mfma_f32_16x16x32_bf16 v[60:63], v[104:107], v[160:163], v[60:63]
	v_mfma_f32_16x16x32_bf16 v[56:59], v[112:115], v[160:163], v[56:59]
	v_mfma_f32_16x16x32_bf16 v[44:47], v[104:107], v[196:199], v[44:47]
	v_mfma_f32_16x16x32_bf16 v[40:43], v[112:115], v[196:199], v[40:43]
	v_mfma_f32_16x16x32_bf16 v[28:31], v[104:107], v[210:213], v[28:31]
	v_mfma_f32_16x16x32_bf16 v[24:27], v[112:115], v[210:213], v[24:27]
	v_mfma_f32_16x16x32_bf16 v[12:15], v[104:107], v[228:231], v[12:15]
	v_mfma_f32_16x16x32_bf16 v[8:11], v[112:115], v[228:231], v[8:11]
	v_mfma_f32_16x16x32_bf16 v[60:63], v[108:111], v[192:195], v[60:63]
	v_mfma_f32_16x16x32_bf16 v[56:59], v[116:119], v[192:195], v[56:59]
	v_mfma_f32_16x16x32_bf16 v[44:47], v[108:111], v[206:209], v[44:47]
	v_mfma_f32_16x16x32_bf16 v[40:43], v[116:119], v[206:209], v[40:43]
	v_mfma_f32_16x16x32_bf16 v[28:31], v[108:111], v[224:227], v[28:31]
	v_mfma_f32_16x16x32_bf16 v[24:27], v[116:119], v[224:227], v[24:27]
	v_mfma_f32_16x16x32_bf16 v[12:15], v[108:111], v[232:235], v[12:15]
	v_mfma_f32_16x16x32_bf16 v[8:11], v[116:119], v[232:235], v[8:11]
	v_mfma_f32_16x16x32_bf16 v[52:55], v[144:147], v[160:163], v[52:55]
	v_mfma_f32_16x16x32_bf16 v[48:51], v[152:155], v[160:163], v[48:51]
	v_mfma_f32_16x16x32_bf16 v[36:39], v[144:147], v[196:199], v[36:39]
	v_mfma_f32_16x16x32_bf16 v[32:35], v[152:155], v[196:199], v[32:35]
	v_mfma_f32_16x16x32_bf16 v[20:23], v[144:147], v[210:213], v[20:23]
	v_mfma_f32_16x16x32_bf16 v[16:19], v[152:155], v[210:213], v[16:19]
	v_mfma_f32_16x16x32_bf16 v[4:7], v[144:147], v[228:231], v[4:7]
	v_mfma_f32_16x16x32_bf16 v[0:3], v[152:155], v[228:231], v[0:3]
	v_mfma_f32_16x16x32_bf16 v[52:55], v[148:151], v[192:195], v[52:55]
	v_mfma_f32_16x16x32_bf16 v[48:51], v[156:159], v[192:195], v[48:51]
	v_mfma_f32_16x16x32_bf16 v[36:39], v[148:151], v[206:209], v[36:39]
	v_mfma_f32_16x16x32_bf16 v[32:35], v[156:159], v[206:209], v[32:35]
	v_mfma_f32_16x16x32_bf16 v[20:23], v[148:151], v[224:227], v[20:23]
	v_mfma_f32_16x16x32_bf16 v[16:19], v[156:159], v[224:227], v[16:19]
	v_mfma_f32_16x16x32_bf16 v[4:7], v[148:151], v[232:235], v[4:7]
	v_mfma_f32_16x16x32_bf16 v[0:3], v[156:159], v[232:235], v[0:3]
	s_barrier
	s_add_i32 s62, s62, 2
	s_add_u32 s60, s60, 0x100
	s_addc_u32 s61, s61, 0
	s_cmp_gt_u32 s62, 37
	s_mov_b64 s[50:51], s[22:23]
	s_cbranch_scc0 .LBB0_1268
	s_and_b64 vcc, exec, s[46:47]
	s_cbranch_vccz .LBB0_1271
	s_barrier

;     __device__ __forceinline__ void a_ready(const Unit& u) const { wait_panel(cnt, u.pm, need, tmo, wave); }
;     __device__ __forceinline__ void a_ready(const Unit& u) const { wait_panel(cnt, u.pm, need, tmo, wave); }
; #define PG8_STAGE(bufoff, gbase, voff) do { _Pragma("unroll") for (int _i = 0; _i < 2; ++_i) \
;         __builtin_amdgcn_global_load_lds((const unsigned*)((const char*)(gbase) + (voff)[_i]), (PG8_LAS unsigned*)(lds + (bufoff) + ldsw + _i * 8192), 16, 0, 0); } while (0)
; #define PG8_LDA(dst, b, h) do { _Pragma("unroll") for (int m = 0; m < 4; ++m) _Pragma("unroll") for (int k = 0; k < 2; ++k) dst[m][k] = *(const PG8_LAS bf16x8*)(lds + PG8_SA(b, h) + aoff + m * 2048 + k * 1024); } while (0)
; #define PG8_LDB(dst, b, h) do { _Pragma("unroll") for (int n = 0; n < 2; ++n) _Pragma("unroll") for (int k = 0; k < 2; ++k) dst[n][k] = *(const PG8_LAS bf16x8*)(lds + PG8_SB(b, h) + boff + n * 2048 + k * 1024); } while (0)
; #define PG8_WAIT_V(n) asm volatile("s_waitcnt vmcnt(" #n ")" ::: "memory")
; #define PG8_WAIT_L(n) asm volatile("s_waitcnt lgkmcnt(" #n ")" ::: "memory")
; #define PG8_BAR __builtin_amdgcn_s_barrier()
; #define PG8_SCHED __builtin_amdgcn_sched_barrier(0)
; template <class Epi, class Sched, bool ALIGN_EPI = false, bool SP2 = false>
; __device__ __forceinline__ void gemm_phase(PG8_LAS unsigned char* lds, const Gemm g, const Sched& S, const Epi& E, const int tid_in) {
;     ...
;             const bool last = (t == nt - 2);
;             const char* a1 = cA + (size_t)(t + 1) * kstep;
;             const char* a2 = last ? nA : cA + (size_t)(t + 2) * kstep; const char* b2 = last ? nB : cB + (size_t)(t + 2) * kstep;
;             const char* a3 = a2 + kstep; const char* b3 = b2 + kstep;
;             if (last && has_next) S.a_ready(nxt);
;             if constexpr (SP2) {
;             PG8_LDB(B0, 0, 0); PG8_LDB(B1, 0, 1); PG8_SCHED; PG8_LDA(At, 0, 0); PG8_STAGE(PG8_SA(1, 1), a1 + hstepA, voffA);
;             PG8_WAIT_V(8); PG8_WAIT_L(0); PG8_BAR; PG8_MMA(0, 0, At, B0); PG8_MMA(0, 1, At, B1); PG8_BAR; PG8_SCHED;
;             PG8_LDA(At, 0, 1); PG8_STAGE(PG8_SB(0, 0), b2, voffB); PG8_STAGE(PG8_SB(0, 1), b2 + hstepB, voffB); PG8_STAGE(PG8_SA(0, 0), a2, voffA);
;             PG8_WAIT_V(8); PG8_WAIT_L(0); PG8_BAR; PG8_MMA(1, 0, At, B0); PG8_MMA(1, 1, At, B1); PG8_BAR; PG8_SCHED;
.LBB0_1286:
	s_add_u32 s22, s62, 0x100
	s_addc_u32 s23, s63, 0
	s_add_i32 s68, 0, 0x10000
	s_cmp_eq_u32 s61, 4
	s_cselect_b32 s67, s57, s23
	s_cselect_b32 s66, s56, s22
	s_cselect_b32 s65, s55, s60
	s_cselect_b32 s64, s54, s59
	s_add_i32 s69, 0, 0x14000
	ds_read_b128 v[64:67], v249
	ds_read_b128 v[68:71], v249 offset:1024
	ds_read_b128 v[72:75], v249 offset:2048
	ds_read_b128 v[76:79], v249 offset:3072
	ds_read_b128 v[80:83], v249 offset:16384
	ds_read_b128 v[84:87], v249 offset:17408
	ds_read_b128 v[88:91], v249 offset:18432
	ds_read_b128 v[92:95], v249 offset:19456
	s_add_i32 m0, s12, 0xc000
	ds_read_b128 v[96:99], v154
	ds_read_b128 v[100:103], v154 offset:1024
	ds_read_b128 v[104:107], v154 offset:2048
	ds_read_b128 v[108:111], v154 offset:3072
	ds_read_b128 v[112:115], v154 offset:4096
	ds_read_b128 v[116:119], v154 offset:5120
	ds_read_b128 v[120:123], v154 offset:6144
	ds_read_b128 v[124:127], v154 offset:7168
	global_load_lds_dwordx4 v148, s[62:63]
	s_add_i32 m0, s12, 0xe000
	s_nop 0
	global_load_lds_dwordx4 v146, s[62:63]
	s_waitcnt vmcnt(8)
	s_waitcnt lgkmcnt(0)
	s_barrier
	s_waitcnt lgkmcnt(0)
	v_mfma_f32_16x16x32_bf16 v[60:63], v[64:67], v[96:99], v[60:63]
	v_mfma_f32_16x16x32_bf16 v[56:59], v[72:75], v[96:99], v[56:59]
	v_mfma_f32_16x16x32_bf16 v[48:51], v[64:67], v[104:107], v[48:51]
	v_mfma_f32_16x16x32_bf16 v[40:43], v[72:75], v[104:107], v[40:43]
	v_mfma_f32_16x16x32_bf16 v[32:35], v[64:67], v[112:115], v[32:35]
	v_mfma_f32_16x16x32_bf16 v[24:27], v[72:75], v[112:115], v[24:27]
	v_mfma_f32_16x16x32_bf16 v[16:19], v[64:67], v[120:123], v[16:19]
	v_mfma_f32_16x16x32_bf16 v[8:11], v[72:75], v[120:123], v[8:11]
	v_mfma_f32_16x16x32_bf16 v[60:63], v[68:71], v[100:103], v[60:63]
	v_mfma_f32_16x16x32_bf16 v[56:59], v[76:79], v[100:103], v[56:59]
	v_mfma_f32_16x16x32_bf16 v[48:51], v[68:71], v[108:111], v[48:51]
	v_mfma_f32_16x16x32_bf16 v[40:43], v[76:79], v[108:111], v[40:43]
	v_mfma_f32_16x16x32_bf16 v[32:35], v[68:71], v[116:119], v[32:35]
	v_mfma_f32_16x16x32_bf16 v[24:27], v[76:79], v[116:119], v[24:27]
	v_mfma_f32_16x16x32_bf16 v[16:19], v[68:71], v[124:127], v[16:19]
	v_mfma_f32_16x16x32_bf16 v[8:11], v[76:79], v[124:127], v[8:11]
	v_mfma_f32_16x16x32_bf16 v[52:55], v[80:83], v[96:99], v[52:55]
	v_mfma_f32_16x16x32_bf16 v[44:47], v[88:91], v[96:99], v[44:47]
	v_mfma_f32_16x16x32_bf16 v[36:39], v[80:83], v[104:107], v[36:39]
	v_mfma_f32_16x16x32_bf16 v[28:31], v[88:91], v[104:107], v[28:31]
	v_mfma_f32_16x16x32_bf16 v[20:23], v[80:83], v[112:115], v[20:23]
	v_mfma_f32_16x16x32_bf16 v[12:15], v[88:91], v[112:115], v[12:15]
	v_mfma_f32_16x16x32_bf16 v[4:7], v[80:83], v[120:123], v[4:7]
	v_mfma_f32_16x16x32_bf16 v[0:3], v[88:91], v[120:123], v[0:3]
	v_mfma_f32_16x16x32_bf16 v[52:55], v[84:87], v[100:103], v[52:55]
	v_mfma_f32_16x16x32_bf16 v[44:47], v[92:95], v[100:103], v[44:47]
	v_mfma_f32_16x16x32_bf16 v[36:39], v[84:87], v[108:111], v[36:39]
	v_mfma_f32_16x16x32_bf16 v[28:31], v[92:95], v[108:111], v[28:31]
	v_mfma_f32_16x16x32_bf16 v[20:23], v[84:87], v[116:119], v[20:23]
	v_mfma_f32_16x16x32_bf16 v[12:15], v[92:95], v[116:119], v[12:15]
	v_mfma_f32_16x16x32_bf16 v[4:7], v[84:87], v[124:127], v[4:7]
	v_mfma_f32_16x16x32_bf16 v[0:3], v[92:95], v[124:127], v[0:3]
	s_barrier
	s_add_i32 s62, s68, s6
	s_mov_b32 m0, s62
	s_add_u32 vcc_lo, s64, 0x80
	s_addc_u32 vcc_hi, s65, 0
	global_load_lds_dwordx4 v172, s[64:65]
	s_add_i32 m0, s62, 0x2000
	s_add_u32 s62, s64, 0xa0000
	s_addc_u32 s63, s65, 0
	s_add_i32 s68, s69, s6
	global_load_lds_dwordx4 v128, s[64:65]
	s_mov_b32 m0, s68
	s_nop 0
	global_load_lds_dwordx4 v172, s[62:63]
	s_add_i32 m0, s68, 0x2000
	s_nop 0
	global_load_lds_dwordx4 v128, s[62:63]
	s_mov_b32 m0, s12
	s_nop 0
	global_load_lds_dwordx4 v172, s[66:67]
	s_mov_b32 m0, s20
	s_nop 0
	global_load_lds_dwordx4 v128, s[66:67]
	s_waitcnt vmcnt(8)
	s_waitcnt lgkmcnt(0)
	s_barrier
	s_barrier
; #define PG8_STAGE(bufoff, gbase, voff) do { _Pragma("unroll") for (int _i = 0; _i < 2; ++_i) \
;         __builtin_amdgcn_global_load_lds((const unsigned*)((const char*)(gbase) + (voff)[_i]), (PG8_LAS unsigned*)(lds + (bufoff) + ldsw + _i * 8192), 16, 0, 0); } while (0)
; #define PG8_LDA(dst, b, h) do { _Pragma("unroll") for (int m = 0; m < 4; ++m) _Pragma("unroll") for (int k = 0; k < 2; ++k) dst[m][k] = *(const PG8_LAS bf16x8*)(lds + PG8_SA(b, h) + aoff + m * 2048 + k * 1024); } while (0)
; #define PG8_LDB(dst, b, h) do { _Pragma("unroll") for (int n = 0; n < 2; ++n) _Pragma("unroll") for (int k = 0; k < 2; ++k) dst[n][k] = *(const PG8_LAS bf16x8*)(lds + PG8_SB(b, h) + boff + n * 2048 + k * 1024); } while (0)
; #define PG8_MMA(ai, bj, At, Bt) do { __builtin_amdgcn_s_setprio(1); _Pragma("unroll") for (int m = 0; m < 4; ++m) _Pragma("unroll") for (int n = 0; n < 2; ++n) _Pragma("unroll") for (int k = 0; k < 2; ++k) \
;         acc[ai][bj][m][n] = __builtin_amdgcn_mfma_f32_16x16x32_bf16(Bt[n][k], At[m][k], acc[ai][bj][m][n], 0, 0, 0); __builtin_amdgcn_s_setprio(0); } while (0)
; #define PG8_WAIT_V(n) asm volatile("s_waitcnt vmcnt(" #n ")" ::: "memory")
; #define PG8_WAIT_L(n) asm volatile("s_waitcnt lgkmcnt(" #n ")" ::: "memory")
; #define PG8_BAR __builtin_amdgcn_s_barrier()
; #define PG8_SCHED __builtin_amdgcn_sched_barrier(0)
; template <class Epi, class Sched, bool ALIGN_EPI = false, bool SP2 = false>
; __device__ __forceinline__ void gemm_phase(PG8_LAS unsigned char* lds, const Gemm g, const Sched& S, const Epi& E, const int tid_in) {
;     ...
;             PG8_LDB(B0, 1, 0); PG8_LDB(B1, 1, 1); PG8_SCHED; PG8_LDA(At, 1, 0); PG8_STAGE(PG8_SA(0, 1), a2 + hstepA, voffA);
;             PG8_WAIT_V(8); PG8_WAIT_L(0); PG8_BAR; PG8_MMA(0, 0, At, B0); PG8_MMA(0, 1, At, B1); PG8_BAR; PG8_SCHED;
;             PG8_LDA(At, 1, 1); PG8_STAGE(PG8_SB(1, 0), b3, voffB); PG8_STAGE(PG8_SB(1, 1), b3 + hstepB, voffB); PG8_STAGE(PG8_SA(1, 0), a3, voffA);
;             PG8_WAIT_V(8); PG8_WAIT_L(0); PG8_BAR; PG8_MMA(1, 0, At, B0); PG8_MMA(1, 1, At, B1); PG8_BAR; PG8_SCHED;
	s_add_i32 s68, 0, 0x18000
	s_add_i32 s69, 0, 0x1c000
	ds_read_b128 v[64:67], v249 offset:32768
	ds_read_b128 v[68:71], v249 offset:33792
	ds_read_b128 v[72:75], v249 offset:34816
	ds_read_b128 v[76:79], v249 offset:35840
	ds_read_b128 v[80:83], v249 offset:49152
	ds_read_b128 v[84:87], v249 offset:50176
	ds_read_b128 v[88:91], v249 offset:51200
	ds_read_b128 v[92:95], v249 offset:52224
	s_add_u32 s62, s66, 0xa0000
	s_addc_u32 s63, s67, 0
	s_mov_b32 m0, s21
	ds_read_b128 v[96:99], v154 offset:32768
	ds_read_b128 v[100:103], v154 offset:33792
	ds_read_b128 v[104:107], v154 offset:34816
	ds_read_b128 v[108:111], v154 offset:35840
	ds_read_b128 v[112:115], v154 offset:36864
	ds_read_b128 v[116:119], v154 offset:37888
	ds_read_b128 v[120:123], v154 offset:38912
	ds_read_b128 v[124:127], v154 offset:39936
	global_load_lds_dwordx4 v172, s[62:63]
	s_mov_b32 m0, s30
	s_nop 0
	global_load_lds_dwordx4 v128, s[62:63]
	s_waitcnt vmcnt(8)
	s_waitcnt lgkmcnt(0)
	s_barrier
	s_waitcnt lgkmcnt(0)
	v_mfma_f32_16x16x32_bf16 v[60:63], v[64:67], v[96:99], v[60:63]
	v_mfma_f32_16x16x32_bf16 v[56:59], v[72:75], v[96:99], v[56:59]
	v_mfma_f32_16x16x32_bf16 v[48:51], v[64:67], v[104:107], v[48:51]
	v_mfma_f32_16x16x32_bf16 v[40:43], v[72:75], v[104:107], v[40:43]
	v_mfma_f32_16x16x32_bf16 v[32:35], v[64:67], v[112:115], v[32:35]
	v_mfma_f32_16x16x32_bf16 v[24:27], v[72:75], v[112:115], v[24:27]
	v_mfma_f32_16x16x32_bf16 v[16:19], v[64:67], v[120:123], v[16:19]
	v_mfma_f32_16x16x32_bf16 v[8:11], v[72:75], v[120:123], v[8:11]
	v_mfma_f32_16x16x32_bf16 v[60:63], v[68:71], v[100:103], v[60:63]
	v_mfma_f32_16x16x32_bf16 v[56:59], v[76:79], v[100:103], v[56:59]
	v_mfma_f32_16x16x32_bf16 v[48:51], v[68:71], v[108:111], v[48:51]
	v_mfma_f32_16x16x32_bf16 v[40:43], v[76:79], v[108:111], v[40:43]
	v_mfma_f32_16x16x32_bf16 v[32:35], v[68:71], v[116:119], v[32:35]
	v_mfma_f32_16x16x32_bf16 v[24:27], v[76:79], v[116:119], v[24:27]
	v_mfma_f32_16x16x32_bf16 v[16:19], v[68:71], v[124:127], v[16:19]
	v_mfma_f32_16x16x32_bf16 v[8:11], v[76:79], v[124:127], v[8:11]
	v_mfma_f32_16x16x32_bf16 v[52:55], v[80:83], v[96:99], v[52:55]
	v_mfma_f32_16x16x32_bf16 v[44:47], v[88:91], v[96:99], v[44:47]
	v_mfma_f32_16x16x32_bf16 v[36:39], v[80:83], v[104:107], v[36:39]
	v_mfma_f32_16x16x32_bf16 v[28:31], v[88:91], v[104:107], v[28:31]
	v_mfma_f32_16x16x32_bf16 v[20:23], v[80:83], v[112:115], v[20:23]
	v_mfma_f32_16x16x32_bf16 v[12:15], v[88:91], v[112:115], v[12:15]
	v_mfma_f32_16x16x32_bf16 v[4:7], v[80:83], v[120:123], v[4:7]
	v_mfma_f32_16x16x32_bf16 v[0:3], v[88:91], v[120:123], v[0:3]
	v_mfma_f32_16x16x32_bf16 v[52:55], v[84:87], v[100:103], v[52:55]
	v_mfma_f32_16x16x32_bf16 v[44:47], v[92:95], v[100:103], v[44:47]
	v_mfma_f32_16x16x32_bf16 v[36:39], v[84:87], v[108:111], v[36:39]
	v_mfma_f32_16x16x32_bf16 v[28:31], v[92:95], v[108:111], v[28:31]
	v_mfma_f32_16x16x32_bf16 v[20:23], v[84:87], v[116:119], v[20:23]
	v_mfma_f32_16x16x32_bf16 v[12:15], v[92:95], v[116:119], v[12:15]
	v_mfma_f32_16x16x32_bf16 v[4:7], v[84:87], v[124:127], v[4:7]
	v_mfma_f32_16x16x32_bf16 v[0:3], v[92:95], v[124:127], v[0:3]
	s_barrier
	s_add_i32 s62, s68, s6
	s_mov_b32 m0, s62
	s_nop 0
	s_add_u32 s100, s64, 0x80
	s_addc_u32 s101, s65, 0
	global_load_lds_dwordx4 v172, s[100:101]
	s_add_i32 m0, s62, 0x2000
	s_add_u32 s62, s64, 0xa0080
	s_addc_u32 s63, s65, 0
	s_add_i32 s64, s69, s6
	global_load_lds_dwordx4 v128, vcc
	s_mov_b32 m0, s64
	s_nop 0
	global_load_lds_dwordx4 v172, s[62:63]
	s_add_i32 m0, s64, 0x2000
	s_nop 0
	global_load_lds_dwordx4 v128, s[62:63]
	s_mov_b32 m0, s31
	s_nop 0
	s_add_u32 s100, s66, 0x80
	s_addc_u32 s101, s67, 0
	global_load_lds_dwordx4 v172, s[100:101]
	s_mov_b32 m0, s33
	s_nop 0
	global_load_lds_dwordx4 v128, s[100:101]
	s_waitcnt vmcnt(8)
	s_waitcnt lgkmcnt(0)
	s_barrier
	s_barrier
	s_add_i32 s61, s61, 2
	s_add_u32 s59, s59, 0x100
	s_addc_u32 s60, s60, 0
	s_cmp_gt_u32 s61, 5
	s_mov_b64 s[62:63], s[22:23]
	s_cbranch_scc0 .LBB0_1286
	s_and_b64 vcc, exec, s[28:29]
	s_cbranch_vccz .LBB0_1289
	s_barrier

;     __device__ __forceinline__ void a_ready(const Unit& u) const { wait_panel(cnt, u.pm, need, tmo, wave); }
;     __device__ __forceinline__ void a_ready(const Unit& u) const { wait_panel(cnt, u.pm, need, tmo, wave); }
; #define PG8_STAGE(bufoff, gbase, voff) do { _Pragma("unroll") for (int _i = 0; _i < 2; ++_i) \
;         __builtin_amdgcn_global_load_lds((const unsigned*)((const char*)(gbase) + (voff)[_i]), (PG8_LAS unsigned*)(lds + (bufoff) + ldsw + _i * 8192), 16, 0, 0); } while (0)
; #define PG8_LDA(dst, b, h) do { _Pragma("unroll") for (int m = 0; m < 4; ++m) _Pragma("unroll") for (int k = 0; k < 2; ++k) dst[m][k] = *(const PG8_LAS bf16x8*)(lds + PG8_SA(b, h) + aoff + m * 2048 + k * 1024); } while (0)
; #define PG8_LDB(dst, b, h) do { _Pragma("unroll") for (int n = 0; n < 2; ++n) _Pragma("unroll") for (int k = 0; k < 2; ++k) dst[n][k] = *(const PG8_LAS bf16x8*)(lds + PG8_SB(b, h) + boff + n * 2048 + k * 1024); } while (0)
; #define PG8_WAIT_V(n) asm volatile("s_waitcnt vmcnt(" #n ")" ::: "memory")
; #define PG8_WAIT_L(n) asm volatile("s_waitcnt lgkmcnt(" #n ")" ::: "memory")
; #define PG8_BAR __builtin_amdgcn_s_barrier()
; #define PG8_SCHED __builtin_amdgcn_sched_barrier(0)
; template <class Epi, class Sched, bool ALIGN_EPI = false, bool SP2 = false>
; __device__ __forceinline__ void gemm_phase(PG8_LAS unsigned char* lds, const Gemm g, const Sched& S, const Epi& E, const int tid_in) {
;     ...
;             const bool last = (t == nt - 2);
;             const char* a1 = cA + (size_t)(t + 1) * kstep;
;             const char* a2 = last ? nA : cA + (size_t)(t + 2) * kstep; const char* b2 = last ? nB : cB + (size_t)(t + 2) * kstep;
;             const char* a3 = a2 + kstep; const char* b3 = b2 + kstep;
;             if (last && has_next) S.a_ready(nxt);
;             if constexpr (SP2) {
;             PG8_LDB(B0, 0, 0); PG8_LDB(B1, 0, 1); PG8_SCHED; PG8_LDA(At, 0, 0); PG8_STAGE(PG8_SA(1, 1), a1 + hstepA, voffA);
;             PG8_WAIT_V(8); PG8_WAIT_L(0); PG8_BAR; PG8_MMA(0, 0, At, B0); PG8_MMA(0, 1, At, B1); PG8_BAR; PG8_SCHED;
;             PG8_LDA(At, 0, 1); PG8_STAGE(PG8_SB(0, 0), b2, voffB); PG8_STAGE(PG8_SB(0, 1), b2 + hstepB, voffB); PG8_STAGE(PG8_SA(0, 0), a2, voffA);
;             PG8_WAIT_V(8); PG8_WAIT_L(0); PG8_BAR; PG8_MMA(1, 0, At, B0); PG8_MMA(1, 1, At, B1); PG8_BAR; PG8_SCHED;
.LBB0_1444:
	s_add_u32 s22, s52, 0xfff80080
	s_addc_u32 s23, s53, -1
	s_add_i32 s58, 0, 0x10000
	s_cmp_eq_u32 s57, 28
	s_cselect_b32 s55, s35, s23
	s_cselect_b32 s54, s38, s22
	s_cselect_b32 s23, s43, s56
	s_cselect_b32 s22, s45, s51
	s_add_i32 s60, 0, 0x14000
	ds_read_b128 v[140:143], v249
	ds_read_b128 v[148:151], v249 offset:1024
	ds_read_b128 v[152:155], v249 offset:2048
	ds_read_b128 v[156:159], v249 offset:3072
	ds_read_b128 v[160:163], v249 offset:16384
	ds_read_b128 v[164:167], v249 offset:17408
	ds_read_b128 v[168:171], v249 offset:18432
	ds_read_b128 v[190:193], v249 offset:19456
	s_add_i32 m0, s18, 0xc000
	ds_read_b128 v[194:197], v147
	ds_read_b128 v[198:201], v147 offset:1024
	ds_read_b128 v[202:205], v147 offset:2048
	ds_read_b128 v[206:209], v147 offset:3072
	ds_read_b128 v[210:213], v147 offset:4096
	ds_read_b128 v[224:227], v147 offset:5120
	ds_read_b128 v[228:231], v147 offset:6144
	ds_read_b128 v[232:235], v147 offset:7168
	global_load_lds_dwordx4 v134, s[52:53]
	s_add_i32 m0, s18, 0xe000
	s_nop 0
	global_load_lds_dwordx4 v136, s[52:53]
	s_waitcnt vmcnt(8)
	s_waitcnt lgkmcnt(0)
	s_barrier
	s_waitcnt lgkmcnt(0)
	v_mfma_f32_16x16x32_bf16 v[124:127], v[140:143], v[194:197], v[124:127]
	v_mfma_f32_16x16x32_bf16 v[120:123], v[152:155], v[194:197], v[120:123]
	v_mfma_f32_16x16x32_bf16 v[112:115], v[140:143], v[202:205], v[112:115]
	v_mfma_f32_16x16x32_bf16 v[104:107], v[152:155], v[202:205], v[104:107]
	v_mfma_f32_16x16x32_bf16 v[96:99], v[140:143], v[210:213], v[96:99]
	v_mfma_f32_16x16x32_bf16 v[88:91], v[152:155], v[210:213], v[88:91]
	v_mfma_f32_16x16x32_bf16 v[80:83], v[140:143], v[228:231], v[80:83]
	v_mfma_f32_16x16x32_bf16 v[72:75], v[152:155], v[228:231], v[72:75]
	v_mfma_f32_16x16x32_bf16 v[124:127], v[148:151], v[198:201], v[124:127]
	v_mfma_f32_16x16x32_bf16 v[120:123], v[156:159], v[198:201], v[120:123]
	v_mfma_f32_16x16x32_bf16 v[112:115], v[148:151], v[206:209], v[112:115]
	v_mfma_f32_16x16x32_bf16 v[104:107], v[156:159], v[206:209], v[104:107]
	v_mfma_f32_16x16x32_bf16 v[96:99], v[148:151], v[224:227], v[96:99]
	v_mfma_f32_16x16x32_bf16 v[88:91], v[156:159], v[224:227], v[88:91]
	v_mfma_f32_16x16x32_bf16 v[80:83], v[148:151], v[232:235], v[80:83]
	v_mfma_f32_16x16x32_bf16 v[72:75], v[156:159], v[232:235], v[72:75]
	v_mfma_f32_16x16x32_bf16 v[116:119], v[160:163], v[194:197], v[116:119]
	v_mfma_f32_16x16x32_bf16 v[108:111], v[168:171], v[194:197], v[108:111]
	v_mfma_f32_16x16x32_bf16 v[100:103], v[160:163], v[202:205], v[100:103]
	v_mfma_f32_16x16x32_bf16 v[92:95], v[168:171], v[202:205], v[92:95]
	v_mfma_f32_16x16x32_bf16 v[84:87], v[160:163], v[210:213], v[84:87]
	v_mfma_f32_16x16x32_bf16 v[76:79], v[168:171], v[210:213], v[76:79]
	v_mfma_f32_16x16x32_bf16 v[68:71], v[160:163], v[228:231], v[68:71]
	v_mfma_f32_16x16x32_bf16 v[64:67], v[168:171], v[228:231], v[64:67]
	v_mfma_f32_16x16x32_bf16 v[116:119], v[164:167], v[198:201], v[116:119]
	v_mfma_f32_16x16x32_bf16 v[108:111], v[190:193], v[198:201], v[108:111]
	v_mfma_f32_16x16x32_bf16 v[100:103], v[164:167], v[206:209], v[100:103]
	v_mfma_f32_16x16x32_bf16 v[92:95], v[190:193], v[206:209], v[92:95]
	v_mfma_f32_16x16x32_bf16 v[84:87], v[164:167], v[224:227], v[84:87]
	v_mfma_f32_16x16x32_bf16 v[76:79], v[190:193], v[224:227], v[76:79]
	v_mfma_f32_16x16x32_bf16 v[68:71], v[164:167], v[232:235], v[68:71]
	v_mfma_f32_16x16x32_bf16 v[64:67], v[190:193], v[232:235], v[64:67]
	s_barrier
	s_add_i32 s58, s58, s17
	s_mov_b32 m0, s58
	ds_read_b128 v[194:197], v147 offset:16384
	ds_read_b128 v[198:201], v147 offset:17408
	ds_read_b128 v[202:205], v147 offset:18432
	ds_read_b128 v[206:209], v147 offset:19456
	ds_read_b128 v[210:213], v147 offset:20480
	ds_read_b128 v[224:227], v147 offset:21504
	ds_read_b128 v[228:231], v147 offset:22528
	ds_read_b128 v[232:235], v147 offset:23552
	global_load_lds_dwordx4 v172, s[22:23]
	s_add_i32 m0, s58, 0x2000
	s_add_u32 s58, s22, 0x80000
	s_addc_u32 s59, s23, 0
	s_add_i32 s60, s60, s17
	global_load_lds_dwordx4 v132, s[22:23]
	s_mov_b32 m0, s60
	s_nop 0
	global_load_lds_dwordx4 v172, s[58:59]
	s_add_i32 m0, s60, 0x2000
	s_nop 0
	global_load_lds_dwordx4 v132, s[58:59]
	s_add_u32 vcc_lo, s54, 0x80
	s_addc_u32 vcc_hi, s55, 0
	s_mov_b32 m0, s18
	s_nop 0
	global_load_lds_dwordx4 v128, s[54:55]
	s_mov_b32 m0, s19
	s_nop 0
	global_load_lds_dwordx4 v130, s[54:55]
	s_waitcnt vmcnt(8)
	s_waitcnt lgkmcnt(0)
	s_barrier
	s_waitcnt lgkmcnt(0)
	v_mfma_f32_16x16x32_bf16 v[60:63], v[140:143], v[194:197], v[60:63]
	v_mfma_f32_16x16x32_bf16 v[56:59], v[152:155], v[194:197], v[56:59]
	v_mfma_f32_16x16x32_bf16 v[48:51], v[140:143], v[202:205], v[48:51]
	v_mfma_f32_16x16x32_bf16 v[40:43], v[152:155], v[202:205], v[40:43]
	v_mfma_f32_16x16x32_bf16 v[32:35], v[140:143], v[210:213], v[32:35]
	v_mfma_f32_16x16x32_bf16 v[24:27], v[152:155], v[210:213], v[24:27]
	v_mfma_f32_16x16x32_bf16 v[16:19], v[140:143], v[228:231], v[16:19]
	v_mfma_f32_16x16x32_bf16 v[8:11], v[152:155], v[228:231], v[8:11]
	v_mfma_f32_16x16x32_bf16 v[60:63], v[148:151], v[198:201], v[60:63]
	v_mfma_f32_16x16x32_bf16 v[56:59], v[156:159], v[198:201], v[56:59]
	v_mfma_f32_16x16x32_bf16 v[48:51], v[148:151], v[206:209], v[48:51]
	v_mfma_f32_16x16x32_bf16 v[40:43], v[156:159], v[206:209], v[40:43]
	v_mfma_f32_16x16x32_bf16 v[32:35], v[148:151], v[224:227], v[32:35]
	v_mfma_f32_16x16x32_bf16 v[24:27], v[156:159], v[224:227], v[24:27]
	v_mfma_f32_16x16x32_bf16 v[16:19], v[148:151], v[232:235], v[16:19]
	v_mfma_f32_16x16x32_bf16 v[8:11], v[156:159], v[232:235], v[8:11]
	v_mfma_f32_16x16x32_bf16 v[52:55], v[160:163], v[194:197], v[52:55]
	v_mfma_f32_16x16x32_bf16 v[44:47], v[168:171], v[194:197], v[44:47]
	v_mfma_f32_16x16x32_bf16 v[36:39], v[160:163], v[202:205], v[36:39]
	v_mfma_f32_16x16x32_bf16 v[28:31], v[168:171], v[202:205], v[28:31]
	v_mfma_f32_16x16x32_bf16 v[20:23], v[160:163], v[210:213], v[20:23]
	v_mfma_f32_16x16x32_bf16 v[12:15], v[168:171], v[210:213], v[12:15]
	v_mfma_f32_16x16x32_bf16 v[4:7], v[160:163], v[228:231], v[4:7]
	v_mfma_f32_16x16x32_bf16 v[0:3], v[168:171], v[228:231], v[0:3]
	v_mfma_f32_16x16x32_bf16 v[52:55], v[164:167], v[198:201], v[52:55]
	v_mfma_f32_16x16x32_bf16 v[44:47], v[190:193], v[198:201], v[44:47]
	v_mfma_f32_16x16x32_bf16 v[36:39], v[164:167], v[206:209], v[36:39]
	v_mfma_f32_16x16x32_bf16 v[28:31], v[190:193], v[206:209], v[28:31]
	v_mfma_f32_16x16x32_bf16 v[20:23], v[164:167], v[224:227], v[20:23]
	v_mfma_f32_16x16x32_bf16 v[12:15], v[190:193], v[224:227], v[12:15]
	v_mfma_f32_16x16x32_bf16 v[4:7], v[164:167], v[232:235], v[4:7]
	v_mfma_f32_16x16x32_bf16 v[0:3], v[190:193], v[232:235], v[0:3]
	s_barrier
; #define PG8_STAGE(bufoff, gbase, voff) do { _Pragma("unroll") for (int _i = 0; _i < 2; ++_i) \
;         __builtin_amdgcn_global_load_lds((const unsigned*)((const char*)(gbase) + (voff)[_i]), (PG8_LAS unsigned*)(lds + (bufoff) + ldsw + _i * 8192), 16, 0, 0); } while (0)
; #define PG8_LDA(dst, b, h) do { _Pragma("unroll") for (int m = 0; m < 4; ++m) _Pragma("unroll") for (int k = 0; k < 2; ++k) dst[m][k] = *(const PG8_LAS bf16x8*)(lds + PG8_SA(b, h) + aoff + m * 2048 + k * 1024); } while (0)
; #define PG8_LDB(dst, b, h) do { _Pragma("unroll") for (int n = 0; n < 2; ++n) _Pragma("unroll") for (int k = 0; k < 2; ++k) dst[n][k] = *(const PG8_LAS bf16x8*)(lds + PG8_SB(b, h) + boff + n * 2048 + k * 1024); } while (0)
; #define PG8_MMA(ai, bj, At, Bt) do { __builtin_amdgcn_s_setprio(1); _Pragma("unroll") for (int m = 0; m < 4; ++m) _Pragma("unroll") for (int n = 0; n < 2; ++n) _Pragma("unroll") for (int k = 0; k < 2; ++k) \
;         acc[ai][bj][m][n] = __builtin_amdgcn_mfma_f32_16x16x32_bf16(Bt[n][k], At[m][k], acc[ai][bj][m][n], 0, 0, 0); __builtin_amdgcn_s_setprio(0); } while (0)
; #define PG8_WAIT_V(n) asm volatile("s_waitcnt vmcnt(" #n ")" ::: "memory")
; #define PG8_WAIT_L(n) asm volatile("s_waitcnt lgkmcnt(" #n ")" ::: "memory")
; #define PG8_BAR __builtin_amdgcn_s_barrier()
; #define PG8_SCHED __builtin_amdgcn_sched_barrier(0)
; template <class Epi, class Sched, bool ALIGN_EPI = false, bool SP2 = false>
; __device__ __forceinline__ void gemm_phase(PG8_LAS unsigned char* lds, const Gemm g, const Sched& S, const Epi& E, const int tid_in) {
;     ...
;             PG8_LDB(B0, 1, 0); PG8_LDB(B1, 1, 1); PG8_SCHED; PG8_LDA(At, 1, 0); PG8_STAGE(PG8_SA(0, 1), a2 + hstepA, voffA);
;             PG8_WAIT_V(8); PG8_WAIT_L(0); PG8_BAR; PG8_MMA(0, 0, At, B0); PG8_MMA(0, 1, At, B1); PG8_BAR; PG8_SCHED;
;             PG8_LDA(At, 1, 1); PG8_STAGE(PG8_SB(1, 0), b3, voffB); PG8_STAGE(PG8_SB(1, 1), b3 + hstepB, voffB); PG8_STAGE(PG8_SA(1, 0), a3, voffA);
;             PG8_WAIT_V(8); PG8_WAIT_L(0); PG8_BAR; PG8_MMA(1, 0, At, B0); PG8_MMA(1, 1, At, B1); PG8_BAR; PG8_SCHED;
	s_add_i32 s58, 0, 0x18000
	s_add_i32 s59, 0, 0x1c000
	ds_read_b128 v[140:143], v249 offset:32768
	ds_read_b128 v[148:151], v249 offset:33792
	ds_read_b128 v[152:155], v249 offset:34816
	ds_read_b128 v[156:159], v249 offset:35840
	ds_read_b128 v[160:163], v249 offset:49152
	ds_read_b128 v[164:167], v249 offset:50176
	ds_read_b128 v[168:171], v249 offset:51200
	ds_read_b128 v[190:193], v249 offset:52224
	s_add_u32 s54, s54, 0x80000
	s_addc_u32 s55, s55, 0
	s_mov_b32 m0, s20
	ds_read_b128 v[194:197], v147 offset:32768
	ds_read_b128 v[198:201], v147 offset:33792
	ds_read_b128 v[202:205], v147 offset:34816
	ds_read_b128 v[206:209], v147 offset:35840
	ds_read_b128 v[210:213], v147 offset:36864
	ds_read_b128 v[224:227], v147 offset:37888
	ds_read_b128 v[228:231], v147 offset:38912
	ds_read_b128 v[232:235], v147 offset:39936
	global_load_lds_dwordx4 v128, s[54:55]
	s_mov_b32 m0, s21
	s_nop 0
	global_load_lds_dwordx4 v130, s[54:55]
	s_waitcnt vmcnt(8)
	s_waitcnt lgkmcnt(0)
	s_barrier
	s_waitcnt lgkmcnt(0)
	v_mfma_f32_16x16x32_bf16 v[124:127], v[140:143], v[194:197], v[124:127]
	v_mfma_f32_16x16x32_bf16 v[120:123], v[152:155], v[194:197], v[120:123]
	v_mfma_f32_16x16x32_bf16 v[112:115], v[140:143], v[202:205], v[112:115]
	v_mfma_f32_16x16x32_bf16 v[104:107], v[152:155], v[202:205], v[104:107]
	v_mfma_f32_16x16x32_bf16 v[96:99], v[140:143], v[210:213], v[96:99]
	v_mfma_f32_16x16x32_bf16 v[88:91], v[152:155], v[210:213], v[88:91]
	v_mfma_f32_16x16x32_bf16 v[80:83], v[140:143], v[228:231], v[80:83]
	v_mfma_f32_16x16x32_bf16 v[72:75], v[152:155], v[228:231], v[72:75]
	v_mfma_f32_16x16x32_bf16 v[124:127], v[148:151], v[198:201], v[124:127]
	v_mfma_f32_16x16x32_bf16 v[120:123], v[156:159], v[198:201], v[120:123]
	v_mfma_f32_16x16x32_bf16 v[112:115], v[148:151], v[206:209], v[112:115]
	v_mfma_f32_16x16x32_bf16 v[104:107], v[156:159], v[206:209], v[104:107]
	v_mfma_f32_16x16x32_bf16 v[96:99], v[148:151], v[224:227], v[96:99]
	v_mfma_f32_16x16x32_bf16 v[88:91], v[156:159], v[224:227], v[88:91]
	v_mfma_f32_16x16x32_bf16 v[80:83], v[148:151], v[232:235], v[80:83]
	v_mfma_f32_16x16x32_bf16 v[72:75], v[156:159], v[232:235], v[72:75]
	v_mfma_f32_16x16x32_bf16 v[116:119], v[160:163], v[194:197], v[116:119]
	v_mfma_f32_16x16x32_bf16 v[108:111], v[168:171], v[194:197], v[108:111]
	v_mfma_f32_16x16x32_bf16 v[100:103], v[160:163], v[202:205], v[100:103]
	v_mfma_f32_16x16x32_bf16 v[92:95], v[168:171], v[202:205], v[92:95]
	v_mfma_f32_16x16x32_bf16 v[84:87], v[160:163], v[210:213], v[84:87]
	v_mfma_f32_16x16x32_bf16 v[76:79], v[168:171], v[210:213], v[76:79]
	v_mfma_f32_16x16x32_bf16 v[68:71], v[160:163], v[228:231], v[68:71]
	v_mfma_f32_16x16x32_bf16 v[64:67], v[168:171], v[228:231], v[64:67]
	v_mfma_f32_16x16x32_bf16 v[116:119], v[164:167], v[198:201], v[116:119]
	v_mfma_f32_16x16x32_bf16 v[108:111], v[190:193], v[198:201], v[108:111]
	v_mfma_f32_16x16x32_bf16 v[100:103], v[164:167], v[206:209], v[100:103]
	v_mfma_f32_16x16x32_bf16 v[92:95], v[190:193], v[206:209], v[92:95]
	v_mfma_f32_16x16x32_bf16 v[84:87], v[164:167], v[224:227], v[84:87]
	v_mfma_f32_16x16x32_bf16 v[76:79], v[190:193], v[224:227], v[76:79]
	v_mfma_f32_16x16x32_bf16 v[68:71], v[164:167], v[232:235], v[68:71]
	v_mfma_f32_16x16x32_bf16 v[64:67], v[190:193], v[232:235], v[64:67]
	s_barrier
	s_add_i32 s54, s58, s17
	s_mov_b32 m0, s54
	ds_read_b128 v[194:197], v147 offset:49152
	ds_read_b128 v[198:201], v147 offset:50176
	ds_read_b128 v[202:205], v147 offset:51200
	ds_read_b128 v[206:209], v147 offset:52224
	ds_read_b128 v[210:213], v147 offset:53248
	ds_read_b128 v[224:227], v147 offset:54272
	ds_read_b128 v[228:231], v147 offset:55296
	ds_read_b128 v[232:235], v147 offset:56320
	s_add_u32 s100, s22, 0x80
	s_addc_u32 s101, s23, 0
	global_load_lds_dwordx4 v172, s[100:101]
	s_add_i32 m0, s54, 0x2000
	s_add_u32 s22, s22, 0x80080
	s_addc_u32 s23, s23, 0
	s_add_i32 s54, s59, s17
	global_load_lds_dwordx4 v132, s[100:101]
	s_mov_b32 m0, s54
	s_nop 0
	global_load_lds_dwordx4 v172, s[22:23]
	s_add_i32 m0, s54, 0x2000
	s_nop 0
	global_load_lds_dwordx4 v132, s[22:23]
	s_mov_b32 m0, s29
	s_nop 0
	global_load_lds_dwordx4 v128, vcc
	s_mov_b32 m0, s30
	s_nop 0
	global_load_lds_dwordx4 v130, vcc
	s_waitcnt vmcnt(8)
	s_waitcnt lgkmcnt(0)
	s_barrier
	s_waitcnt lgkmcnt(0)
	v_mfma_f32_16x16x32_bf16 v[60:63], v[140:143], v[194:197], v[60:63]
	v_mfma_f32_16x16x32_bf16 v[56:59], v[152:155], v[194:197], v[56:59]
	v_mfma_f32_16x16x32_bf16 v[48:51], v[140:143], v[202:205], v[48:51]
	v_mfma_f32_16x16x32_bf16 v[40:43], v[152:155], v[202:205], v[40:43]
	v_mfma_f32_16x16x32_bf16 v[32:35], v[140:143], v[210:213], v[32:35]
	v_mfma_f32_16x16x32_bf16 v[24:27], v[152:155], v[210:213], v[24:27]
	v_mfma_f32_16x16x32_bf16 v[16:19], v[140:143], v[228:231], v[16:19]
	v_mfma_f32_16x16x32_bf16 v[8:11], v[152:155], v[228:231], v[8:11]
	v_mfma_f32_16x16x32_bf16 v[60:63], v[148:151], v[198:201], v[60:63]
	v_mfma_f32_16x16x32_bf16 v[56:59], v[156:159], v[198:201], v[56:59]
	v_mfma_f32_16x16x32_bf16 v[48:51], v[148:151], v[206:209], v[48:51]
	v_mfma_f32_16x16x32_bf16 v[40:43], v[156:159], v[206:209], v[40:43]
	v_mfma_f32_16x16x32_bf16 v[32:35], v[148:151], v[224:227], v[32:35]
	v_mfma_f32_16x16x32_bf16 v[24:27], v[156:159], v[224:227], v[24:27]
	v_mfma_f32_16x16x32_bf16 v[16:19], v[148:151], v[232:235], v[16:19]
	v_mfma_f32_16x16x32_bf16 v[8:11], v[156:159], v[232:235], v[8:11]
	v_mfma_f32_16x16x32_bf16 v[52:55], v[160:163], v[194:197], v[52:55]
	v_mfma_f32_16x16x32_bf16 v[44:47], v[168:171], v[194:197], v[44:47]
	v_mfma_f32_16x16x32_bf16 v[36:39], v[160:163], v[202:205], v[36:39]
	v_mfma_f32_16x16x32_bf16 v[28:31], v[168:171], v[202:205], v[28:31]
	v_mfma_f32_16x16x32_bf16 v[20:23], v[160:163], v[210:213], v[20:23]
	v_mfma_f32_16x16x32_bf16 v[12:15], v[168:171], v[210:213], v[12:15]
	v_mfma_f32_16x16x32_bf16 v[4:7], v[160:163], v[228:231], v[4:7]
	v_mfma_f32_16x16x32_bf16 v[0:3], v[168:171], v[228:231], v[0:3]
	v_mfma_f32_16x16x32_bf16 v[52:55], v[164:167], v[198:201], v[52:55]
	v_mfma_f32_16x16x32_bf16 v[44:47], v[190:193], v[198:201], v[44:47]
	v_mfma_f32_16x16x32_bf16 v[36:39], v[164:167], v[206:209], v[36:39]
	v_mfma_f32_16x16x32_bf16 v[28:31], v[190:193], v[206:209], v[28:31]
	v_mfma_f32_16x16x32_bf16 v[20:23], v[164:167], v[224:227], v[20:23]
	v_mfma_f32_16x16x32_bf16 v[12:15], v[190:193], v[224:227], v[12:15]
	v_mfma_f32_16x16x32_bf16 v[4:7], v[164:167], v[232:235], v[4:7]
	v_mfma_f32_16x16x32_bf16 v[0:3], v[190:193], v[232:235], v[0:3]
	s_barrier
	s_add_i32 s57, s57, 2
	s_add_u32 s52, s52, 0x100
	s_addc_u32 s53, s53, 0
	s_add_u32 s51, s51, 0x100
	s_addc_u32 s56, s56, 0
	s_cmp_gt_u32 s57, 29
	s_cbranch_scc0 .LBB0_1444
	s_and_b64 vcc, exec, s[36:37]
	s_cbranch_vccz .LBB0_1447
	s_barrier

;     __device__ __forceinline__ void a_ready(const Unit& u) const { wait_panel(cnt, u.pm, need, tmo, wave); }
;     __device__ __forceinline__ void a_ready(const Unit& u) const { wait_panel(cnt, u.pm, need, tmo, wave); }
; #define PG8_STAGE(bufoff, gbase, voff) do { _Pragma("unroll") for (int _i = 0; _i < 2; ++_i) \
;         __builtin_amdgcn_global_load_lds((const unsigned*)((const char*)(gbase) + (voff)[_i]), (PG8_LAS unsigned*)(lds + (bufoff) + ldsw + _i * 8192), 16, 0, 0); } while (0)
; #define PG8_LDA(dst, b, h) do { _Pragma("unroll") for (int m = 0; m < 4; ++m) _Pragma("unroll") for (int k = 0; k < 2; ++k) dst[m][k] = *(const PG8_LAS bf16x8*)(lds + PG8_SA(b, h) + aoff + m * 2048 + k * 1024); } while (0)
; #define PG8_LDB(dst, b, h) do { _Pragma("unroll") for (int n = 0; n < 2; ++n) _Pragma("unroll") for (int k = 0; k < 2; ++k) dst[n][k] = *(const PG8_LAS bf16x8*)(lds + PG8_SB(b, h) + boff + n * 2048 + k * 1024); } while (0)
; #define PG8_WAIT_V(n) asm volatile("s_waitcnt vmcnt(" #n ")" ::: "memory")
; #define PG8_WAIT_L(n) asm volatile("s_waitcnt lgkmcnt(" #n ")" ::: "memory")
; #define PG8_BAR __builtin_amdgcn_s_barrier()
; #define PG8_SCHED __builtin_amdgcn_sched_barrier(0)
; template <class Epi, class Sched, bool ALIGN_EPI = false, bool SP2 = false>
; __device__ __forceinline__ void gemm_phase(PG8_LAS unsigned char* lds, const Gemm g, const Sched& S, const Epi& E, const int tid_in) {
;     ...
;             const bool last = (t == nt - 2);
;             const char* a1 = cA + (size_t)(t + 1) * kstep;
;             const char* a2 = last ? nA : cA + (size_t)(t + 2) * kstep; const char* b2 = last ? nB : cB + (size_t)(t + 2) * kstep;
;             const char* a3 = a2 + kstep; const char* b3 = b2 + kstep;
;             if (last && has_next) S.a_ready(nxt);
;             if constexpr (SP2) {
;             PG8_LDB(B0, 0, 0); PG8_LDB(B1, 0, 1); PG8_SCHED; PG8_LDA(At, 0, 0); PG8_STAGE(PG8_SA(1, 1), a1 + hstepA, voffA);
;             PG8_WAIT_V(8); PG8_WAIT_L(0); PG8_BAR; PG8_MMA(0, 0, At, B0); PG8_MMA(0, 1, At, B1); PG8_BAR; PG8_SCHED;
;             PG8_LDA(At, 0, 1); PG8_STAGE(PG8_SB(0, 0), b2, voffB); PG8_STAGE(PG8_SB(0, 1), b2 + hstepB, voffB); PG8_STAGE(PG8_SA(0, 0), a2, voffA);
;             PG8_WAIT_V(8); PG8_WAIT_L(0); PG8_BAR; PG8_MMA(1, 0, At, B0); PG8_MMA(1, 1, At, B1); PG8_BAR; PG8_SCHED;
.LBB0_1960:
	s_add_u32 s22, s58, 0xfffc0080
	s_addc_u32 s23, s59, -1
	s_add_i32 s62, 0, 0x10000
	s_cmp_eq_u32 s53, 12
	s_cselect_b32 s61, s11, s23
	s_cselect_b32 s60, s12, s22
	s_cselect_b32 s23, s33, s51
	s_cselect_b32 s22, s34, s35
	s_add_i32 s64, 0, 0x14000
	ds_read_b128 v[32:35], v249
	ds_read_b128 v[36:39], v249 offset:1024
	ds_read_b128 v[48:51], v249 offset:2048
	ds_read_b128 v[52:55], v249 offset:3072
	ds_read_b128 v[104:107], v249 offset:16384
	ds_read_b128 v[116:119], v249 offset:17408
	ds_read_b128 v[128:131], v249 offset:18432
	ds_read_b128 v[140:143], v249 offset:19456
	s_add_i32 m0, s17, 0xc000
	ds_read_b128 v[144:147], v225
	ds_read_b128 v[156:159], v225 offset:1024
	ds_read_b128 v[160:163], v225 offset:2048
	ds_read_b128 v[200:203], v225 offset:3072
	ds_read_b128 v[204:207], v225 offset:4096
	ds_read_b128 v[208:211], v225 offset:5120
	ds_read_b128 v[226:229], v225 offset:6144
	ds_read_b128 v[230:233], v225 offset:7168
	global_load_lds_dwordx4 v196, s[58:59]
	s_add_i32 m0, s17, 0xe000
	s_nop 0
	global_load_lds_dwordx4 v198, s[58:59]
	s_waitcnt vmcnt(8)
	s_waitcnt lgkmcnt(0)
	s_barrier
	s_waitcnt lgkmcnt(0)
	v_mfma_f32_16x16x32_bf16 v[168:171], v[32:35], v[144:147], v[168:171]
	v_mfma_f32_16x16x32_bf16 v[164:167], v[48:51], v[144:147], v[164:167]
	v_mfma_f32_16x16x32_bf16 v[136:139], v[32:35], v[160:163], v[136:139]
	v_mfma_f32_16x16x32_bf16 v[132:135], v[48:51], v[160:163], v[132:135]
	v_mfma_f32_16x16x32_bf16 v[112:115], v[32:35], v[204:207], v[112:115]
	v_mfma_f32_16x16x32_bf16 v[108:111], v[48:51], v[204:207], v[108:111]
	v_mfma_f32_16x16x32_bf16 v[92:95], v[32:35], v[226:229], v[92:95]
	v_mfma_f32_16x16x32_bf16 v[88:91], v[48:51], v[226:229], v[88:91]
	v_mfma_f32_16x16x32_bf16 v[168:171], v[36:39], v[156:159], v[168:171]
	v_mfma_f32_16x16x32_bf16 v[164:167], v[52:55], v[156:159], v[164:167]
	v_mfma_f32_16x16x32_bf16 v[136:139], v[36:39], v[200:203], v[136:139]
	v_mfma_f32_16x16x32_bf16 v[132:135], v[52:55], v[200:203], v[132:135]
	v_mfma_f32_16x16x32_bf16 v[112:115], v[36:39], v[208:211], v[112:115]
	v_mfma_f32_16x16x32_bf16 v[108:111], v[52:55], v[208:211], v[108:111]
	v_mfma_f32_16x16x32_bf16 v[92:95], v[36:39], v[230:233], v[92:95]
	v_mfma_f32_16x16x32_bf16 v[88:91], v[52:55], v[230:233], v[88:91]
	v_mfma_f32_16x16x32_bf16 v[152:155], v[104:107], v[144:147], v[152:155]
	v_mfma_f32_16x16x32_bf16 v[124:127], v[104:107], v[160:163], v[124:127]
	v_mfma_f32_16x16x32_bf16 v[120:123], v[128:131], v[160:163], v[120:123]
	v_mfma_f32_16x16x32_bf16 v[100:103], v[104:107], v[204:207], v[100:103]
	v_mfma_f32_16x16x32_bf16 v[96:99], v[128:131], v[204:207], v[96:99]
	v_mfma_f32_16x16x32_bf16 v[84:87], v[104:107], v[226:229], v[84:87]
	v_mfma_f32_16x16x32_bf16 v[80:83], v[128:131], v[226:229], v[80:83]
	v_mfma_f32_16x16x32_bf16 v[152:155], v[116:119], v[156:159], v[152:155]
	v_mfma_f32_16x16x32_bf16 v[144:147], v[128:131], v[144:147], v[148:151]
	v_mfma_f32_16x16x32_bf16 v[124:127], v[116:119], v[200:203], v[124:127]
	v_mfma_f32_16x16x32_bf16 v[120:123], v[140:143], v[200:203], v[120:123]
	v_mfma_f32_16x16x32_bf16 v[100:103], v[116:119], v[208:211], v[100:103]
	v_mfma_f32_16x16x32_bf16 v[96:99], v[140:143], v[208:211], v[96:99]
	v_mfma_f32_16x16x32_bf16 v[84:87], v[116:119], v[230:233], v[84:87]
	v_mfma_f32_16x16x32_bf16 v[80:83], v[140:143], v[230:233], v[80:83]
	v_mfma_f32_16x16x32_bf16 v[144:147], v[140:143], v[156:159], v[144:147]
	s_barrier
	s_add_i32 s62, s62, s16
	s_mov_b32 m0, s62
	ds_read_b128 v[148:151], v225 offset:16384
	ds_read_b128 v[156:159], v225 offset:17408
	ds_read_b128 v[160:163], v225 offset:18432
	ds_read_b128 v[200:203], v225 offset:19456
	ds_read_b128 v[204:207], v225 offset:20480
	ds_read_b128 v[208:211], v225 offset:21504
	ds_read_b128 v[226:229], v225 offset:22528
	ds_read_b128 v[230:233], v225 offset:23552
	global_load_lds_dwordx4 v172, s[22:23]
	s_add_i32 m0, s62, 0x2000
	s_add_u32 s62, s22, 0x40000
	s_addc_u32 s63, s23, 0
	s_add_i32 s64, s64, s16
	global_load_lds_dwordx4 v194, s[22:23]
	s_mov_b32 m0, s64
	s_nop 0
	global_load_lds_dwordx4 v172, s[62:63]
	s_add_i32 m0, s64, 0x2000
	s_nop 0
	global_load_lds_dwordx4 v194, s[62:63]
	s_add_u32 vcc_lo, s60, 0x80
	s_addc_u32 vcc_hi, s61, 0
	s_mov_b32 m0, s17
	s_nop 0
	global_load_lds_dwordx4 v190, s[60:61]
	s_mov_b32 m0, s18
	s_nop 0
	global_load_lds_dwordx4 v192, s[60:61]
	s_waitcnt vmcnt(8)
	s_waitcnt lgkmcnt(0)
	s_barrier
	s_waitcnt lgkmcnt(0)
	v_mfma_f32_16x16x32_bf16 v[76:79], v[32:35], v[148:151], v[76:79]
	v_mfma_f32_16x16x32_bf16 v[72:75], v[48:51], v[148:151], v[72:75]
	v_mfma_f32_16x16x32_bf16 v[60:63], v[32:35], v[160:163], v[60:63]
	v_mfma_f32_16x16x32_bf16 v[56:59], v[48:51], v[160:163], v[56:59]
	v_mfma_f32_16x16x32_bf16 v[28:31], v[32:35], v[204:207], v[28:31]
	v_mfma_f32_16x16x32_bf16 v[24:27], v[48:51], v[204:207], v[24:27]
	v_mfma_f32_16x16x32_bf16 v[12:15], v[32:35], v[226:229], v[12:15]
	v_mfma_f32_16x16x32_bf16 v[8:11], v[48:51], v[226:229], v[8:11]
	v_mfma_f32_16x16x32_bf16 v[76:79], v[36:39], v[156:159], v[76:79]
	v_mfma_f32_16x16x32_bf16 v[72:75], v[52:55], v[156:159], v[72:75]
	v_mfma_f32_16x16x32_bf16 v[60:63], v[36:39], v[200:203], v[60:63]
	v_mfma_f32_16x16x32_bf16 v[56:59], v[52:55], v[200:203], v[56:59]
	v_mfma_f32_16x16x32_bf16 v[28:31], v[36:39], v[208:211], v[28:31]
	v_mfma_f32_16x16x32_bf16 v[24:27], v[52:55], v[208:211], v[24:27]
	v_mfma_f32_16x16x32_bf16 v[12:15], v[36:39], v[230:233], v[12:15]
	v_mfma_f32_16x16x32_bf16 v[8:11], v[52:55], v[230:233], v[8:11]
	v_mfma_f32_16x16x32_bf16 v[44:47], v[104:107], v[160:163], v[44:47]
	v_mfma_f32_16x16x32_bf16 v[40:43], v[128:131], v[160:163], v[40:43]
	v_mfma_f32_16x16x32_bf16 v[20:23], v[104:107], v[204:207], v[20:23]
	v_mfma_f32_16x16x32_bf16 v[16:19], v[128:131], v[204:207], v[16:19]
	v_mfma_f32_16x16x32_bf16 v[4:7], v[104:107], v[226:229], v[4:7]
	v_mfma_f32_16x16x32_bf16 v[0:3], v[128:131], v[226:229], v[0:3]
	v_mfma_f32_16x16x32_bf16 v[32:35], v[104:107], v[148:151], v[68:71]
	v_mfma_f32_16x16x32_bf16 v[36:39], v[128:131], v[148:151], v[64:67]
	v_mfma_f32_16x16x32_bf16 v[44:47], v[116:119], v[200:203], v[44:47]
	v_mfma_f32_16x16x32_bf16 v[40:43], v[140:143], v[200:203], v[40:43]
	v_mfma_f32_16x16x32_bf16 v[20:23], v[116:119], v[208:211], v[20:23]
	v_mfma_f32_16x16x32_bf16 v[16:19], v[140:143], v[208:211], v[16:19]
	v_mfma_f32_16x16x32_bf16 v[4:7], v[116:119], v[230:233], v[4:7]
	v_mfma_f32_16x16x32_bf16 v[0:3], v[140:143], v[230:233], v[0:3]
	v_mfma_f32_16x16x32_bf16 v[32:35], v[116:119], v[156:159], v[32:35]
	v_mfma_f32_16x16x32_bf16 v[36:39], v[140:143], v[156:159], v[36:39]
	s_barrier
; #define PG8_STAGE(bufoff, gbase, voff) do { _Pragma("unroll") for (int _i = 0; _i < 2; ++_i) \
;         __builtin_amdgcn_global_load_lds((const unsigned*)((const char*)(gbase) + (voff)[_i]), (PG8_LAS unsigned*)(lds + (bufoff) + ldsw + _i * 8192), 16, 0, 0); } while (0)
; #define PG8_LDA(dst, b, h) do { _Pragma("unroll") for (int m = 0; m < 4; ++m) _Pragma("unroll") for (int k = 0; k < 2; ++k) dst[m][k] = *(const PG8_LAS bf16x8*)(lds + PG8_SA(b, h) + aoff + m * 2048 + k * 1024); } while (0)
; #define PG8_LDB(dst, b, h) do { _Pragma("unroll") for (int n = 0; n < 2; ++n) _Pragma("unroll") for (int k = 0; k < 2; ++k) dst[n][k] = *(const PG8_LAS bf16x8*)(lds + PG8_SB(b, h) + boff + n * 2048 + k * 1024); } while (0)
; #define PG8_MMA(ai, bj, At, Bt) do { __builtin_amdgcn_s_setprio(1); _Pragma("unroll") for (int m = 0; m < 4; ++m) _Pragma("unroll") for (int n = 0; n < 2; ++n) _Pragma("unroll") for (int k = 0; k < 2; ++k) \
;         acc[ai][bj][m][n] = __builtin_amdgcn_mfma_f32_16x16x32_bf16(Bt[n][k], At[m][k], acc[ai][bj][m][n], 0, 0, 0); __builtin_amdgcn_s_setprio(0); } while (0)
; #define PG8_WAIT_V(n) asm volatile("s_waitcnt vmcnt(" #n ")" ::: "memory")
; #define PG8_WAIT_L(n) asm volatile("s_waitcnt lgkmcnt(" #n ")" ::: "memory")
; #define PG8_BAR __builtin_amdgcn_s_barrier()
; #define PG8_SCHED __builtin_amdgcn_sched_barrier(0)
; template <class Epi, class Sched, bool ALIGN_EPI = false, bool SP2 = false>
; __device__ __forceinline__ void gemm_phase(PG8_LAS unsigned char* lds, const Gemm g, const Sched& S, const Epi& E, const int tid_in) {
;     ...
;             PG8_LDB(B0, 1, 0); PG8_LDB(B1, 1, 1); PG8_SCHED; PG8_LDA(At, 1, 0); PG8_STAGE(PG8_SA(0, 1), a2 + hstepA, voffA);
;             PG8_WAIT_V(8); PG8_WAIT_L(0); PG8_BAR; PG8_MMA(0, 0, At, B0); PG8_MMA(0, 1, At, B1); PG8_BAR; PG8_SCHED;
;             PG8_LDA(At, 1, 1); PG8_STAGE(PG8_SB(1, 0), b3, voffB); PG8_STAGE(PG8_SB(1, 1), b3 + hstepB, voffB); PG8_STAGE(PG8_SA(1, 0), a3, voffA);
;             PG8_WAIT_V(8); PG8_WAIT_L(0); PG8_BAR; PG8_MMA(1, 0, At, B0); PG8_MMA(1, 1, At, B1); PG8_BAR; PG8_SCHED;
	s_add_i32 s62, 0, 0x18000
	s_add_i32 s63, 0, 0x1c000
	ds_read_b128 v[48:51], v249 offset:32768
	ds_read_b128 v[52:55], v249 offset:33792
	ds_read_b128 v[64:67], v249 offset:34816
	ds_read_b128 v[68:71], v249 offset:35840
	ds_read_b128 v[104:107], v249 offset:49152
	ds_read_b128 v[116:119], v249 offset:50176
	ds_read_b128 v[128:131], v249 offset:51200
	ds_read_b128 v[140:143], v249 offset:52224
	s_add_u32 s60, s60, 0x40000
	s_addc_u32 s61, s61, 0
	s_mov_b32 m0, s19
	ds_read_b128 v[148:151], v225 offset:32768
	ds_read_b128 v[156:159], v225 offset:33792
	ds_read_b128 v[160:163], v225 offset:34816
	ds_read_b128 v[200:203], v225 offset:35840
	ds_read_b128 v[204:207], v225 offset:36864
	ds_read_b128 v[208:211], v225 offset:37888
	ds_read_b128 v[226:229], v225 offset:38912
	ds_read_b128 v[230:233], v225 offset:39936
	global_load_lds_dwordx4 v190, s[60:61]
	s_mov_b32 m0, s20
	s_nop 0
	global_load_lds_dwordx4 v192, s[60:61]
	s_waitcnt vmcnt(8)
	s_waitcnt lgkmcnt(0)
	s_barrier
	s_waitcnt lgkmcnt(0)
	v_mfma_f32_16x16x32_bf16 v[168:171], v[48:51], v[148:151], v[168:171]
	v_mfma_f32_16x16x32_bf16 v[164:167], v[64:67], v[148:151], v[164:167]
	v_mfma_f32_16x16x32_bf16 v[136:139], v[48:51], v[160:163], v[136:139]
	v_mfma_f32_16x16x32_bf16 v[132:135], v[64:67], v[160:163], v[132:135]
	v_mfma_f32_16x16x32_bf16 v[112:115], v[48:51], v[204:207], v[112:115]
	v_mfma_f32_16x16x32_bf16 v[108:111], v[64:67], v[204:207], v[108:111]
	v_mfma_f32_16x16x32_bf16 v[92:95], v[48:51], v[226:229], v[92:95]
	v_mfma_f32_16x16x32_bf16 v[88:91], v[64:67], v[226:229], v[88:91]
	v_mfma_f32_16x16x32_bf16 v[168:171], v[52:55], v[156:159], v[168:171]
	v_mfma_f32_16x16x32_bf16 v[164:167], v[68:71], v[156:159], v[164:167]
	v_mfma_f32_16x16x32_bf16 v[136:139], v[52:55], v[200:203], v[136:139]
	v_mfma_f32_16x16x32_bf16 v[132:135], v[68:71], v[200:203], v[132:135]
	v_mfma_f32_16x16x32_bf16 v[112:115], v[52:55], v[208:211], v[112:115]
	v_mfma_f32_16x16x32_bf16 v[108:111], v[68:71], v[208:211], v[108:111]
	v_mfma_f32_16x16x32_bf16 v[92:95], v[52:55], v[230:233], v[92:95]
	v_mfma_f32_16x16x32_bf16 v[88:91], v[68:71], v[230:233], v[88:91]
	v_mfma_f32_16x16x32_bf16 v[152:155], v[104:107], v[148:151], v[152:155]
	v_mfma_f32_16x16x32_bf16 v[144:147], v[128:131], v[148:151], v[144:147]
	v_mfma_f32_16x16x32_bf16 v[124:127], v[104:107], v[160:163], v[124:127]
	v_mfma_f32_16x16x32_bf16 v[120:123], v[128:131], v[160:163], v[120:123]
	v_mfma_f32_16x16x32_bf16 v[100:103], v[104:107], v[204:207], v[100:103]
	v_mfma_f32_16x16x32_bf16 v[96:99], v[128:131], v[204:207], v[96:99]
	v_mfma_f32_16x16x32_bf16 v[84:87], v[104:107], v[226:229], v[84:87]
	v_mfma_f32_16x16x32_bf16 v[80:83], v[128:131], v[226:229], v[80:83]
	v_mfma_f32_16x16x32_bf16 v[152:155], v[116:119], v[156:159], v[152:155]
	v_mfma_f32_16x16x32_bf16 v[148:151], v[140:143], v[156:159], v[144:147]
	v_mfma_f32_16x16x32_bf16 v[124:127], v[116:119], v[200:203], v[124:127]
	v_mfma_f32_16x16x32_bf16 v[120:123], v[140:143], v[200:203], v[120:123]
	v_mfma_f32_16x16x32_bf16 v[100:103], v[116:119], v[208:211], v[100:103]
	v_mfma_f32_16x16x32_bf16 v[96:99], v[140:143], v[208:211], v[96:99]
	v_mfma_f32_16x16x32_bf16 v[84:87], v[116:119], v[230:233], v[84:87]
	v_mfma_f32_16x16x32_bf16 v[80:83], v[140:143], v[230:233], v[80:83]
	s_barrier
	s_add_i32 s60, s62, s16
	s_mov_b32 m0, s60
	ds_read_b128 v[144:147], v225 offset:49152
	ds_read_b128 v[156:159], v225 offset:50176
	ds_read_b128 v[160:163], v225 offset:51200
	ds_read_b128 v[200:203], v225 offset:52224
	ds_read_b128 v[204:207], v225 offset:53248
	ds_read_b128 v[208:211], v225 offset:54272
	ds_read_b128 v[226:229], v225 offset:55296
	ds_read_b128 v[230:233], v225 offset:56320
	s_add_u32 s100, s22, 0x80
	s_addc_u32 s101, s23, 0
	global_load_lds_dwordx4 v172, s[100:101]
	s_add_i32 m0, s60, 0x2000
	s_add_u32 s22, s22, 0x40080
	s_addc_u32 s23, s23, 0
	s_add_i32 s60, s63, s16
	global_load_lds_dwordx4 v194, s[100:101]
	s_mov_b32 m0, s60
	s_nop 0
	global_load_lds_dwordx4 v172, s[22:23]
	s_add_i32 m0, s60, 0x2000
	s_nop 0
	global_load_lds_dwordx4 v194, s[22:23]
	s_mov_b32 m0, s30
	s_nop 0
	global_load_lds_dwordx4 v190, vcc
	s_mov_b32 m0, s31
	s_nop 0
	global_load_lds_dwordx4 v192, vcc
	s_waitcnt vmcnt(8)
	s_waitcnt lgkmcnt(0)
	s_barrier
	s_waitcnt lgkmcnt(0)
	v_mfma_f32_16x16x32_bf16 v[76:79], v[48:51], v[144:147], v[76:79]
	v_mfma_f32_16x16x32_bf16 v[72:75], v[64:67], v[144:147], v[72:75]
	v_mfma_f32_16x16x32_bf16 v[60:63], v[48:51], v[160:163], v[60:63]
	v_mfma_f32_16x16x32_bf16 v[56:59], v[64:67], v[160:163], v[56:59]
	v_mfma_f32_16x16x32_bf16 v[28:31], v[48:51], v[204:207], v[28:31]
	v_mfma_f32_16x16x32_bf16 v[24:27], v[64:67], v[204:207], v[24:27]
	v_mfma_f32_16x16x32_bf16 v[12:15], v[48:51], v[226:229], v[12:15]
	v_mfma_f32_16x16x32_bf16 v[8:11], v[64:67], v[226:229], v[8:11]
	v_mfma_f32_16x16x32_bf16 v[76:79], v[52:55], v[156:159], v[76:79]
	v_mfma_f32_16x16x32_bf16 v[72:75], v[68:71], v[156:159], v[72:75]
	v_mfma_f32_16x16x32_bf16 v[60:63], v[52:55], v[200:203], v[60:63]
	v_mfma_f32_16x16x32_bf16 v[56:59], v[68:71], v[200:203], v[56:59]
	v_mfma_f32_16x16x32_bf16 v[28:31], v[52:55], v[208:211], v[28:31]
	v_mfma_f32_16x16x32_bf16 v[24:27], v[68:71], v[208:211], v[24:27]
	v_mfma_f32_16x16x32_bf16 v[12:15], v[52:55], v[230:233], v[12:15]
	v_mfma_f32_16x16x32_bf16 v[8:11], v[68:71], v[230:233], v[8:11]
	v_mfma_f32_16x16x32_bf16 v[32:35], v[104:107], v[144:147], v[32:35]
	v_mfma_f32_16x16x32_bf16 v[68:71], v[116:119], v[156:159], v[32:35]
	v_mfma_f32_16x16x32_bf16 v[32:35], v[128:131], v[144:147], v[36:39]
	v_mfma_f32_16x16x32_bf16 v[64:67], v[140:143], v[156:159], v[32:35]
	v_mfma_f32_16x16x32_bf16 v[32:35], v[104:107], v[160:163], v[44:47]
	v_mfma_f32_16x16x32_bf16 v[44:47], v[116:119], v[200:203], v[32:35]
	v_mfma_f32_16x16x32_bf16 v[32:35], v[128:131], v[160:163], v[40:43]
	v_mfma_f32_16x16x32_bf16 v[20:23], v[104:107], v[204:207], v[20:23]
	v_mfma_f32_16x16x32_bf16 v[16:19], v[128:131], v[204:207], v[16:19]
	v_mfma_f32_16x16x32_bf16 v[4:7], v[104:107], v[226:229], v[4:7]
	v_mfma_f32_16x16x32_bf16 v[0:3], v[128:131], v[226:229], v[0:3]
	v_mfma_f32_16x16x32_bf16 v[40:43], v[140:143], v[200:203], v[32:35]
	v_mfma_f32_16x16x32_bf16 v[20:23], v[116:119], v[208:211], v[20:23]
	v_mfma_f32_16x16x32_bf16 v[16:19], v[140:143], v[208:211], v[16:19]
	v_mfma_f32_16x16x32_bf16 v[4:7], v[116:119], v[230:233], v[4:7]
	v_mfma_f32_16x16x32_bf16 v[0:3], v[140:143], v[230:233], v[0:3]
	s_barrier
	s_add_i32 s53, s53, 2
	s_add_u32 s58, s58, 0x100
	s_addc_u32 s59, s59, 0
	s_add_u32 s35, s35, 0x100
	s_addc_u32 s51, s51, 0
	s_cmp_gt_u32 s53, 13
	s_cbranch_scc0 .LBB0_1960
	s_and_b64 vcc, exec, s[48:49]
	s_cbranch_vccz .LBB0_1963
	s_barrier

;     __device__ __forceinline__ void a_ready(const Unit& u) const { wait_panel(cnt, u.pm, need, tmo, wave); }
;     __device__ __forceinline__ void a_ready(const Unit& u) const { wait_panel(cnt, u.pm, need, tmo, wave); }
; #define PG8_STAGE(bufoff, gbase, voff) do { _Pragma("unroll") for (int _i = 0; _i < 2; ++_i) \
;         __builtin_amdgcn_global_load_lds((const unsigned*)((const char*)(gbase) + (voff)[_i]), (PG8_LAS unsigned*)(lds + (bufoff) + ldsw + _i * 8192), 16, 0, 0); } while (0)
; #define PG8_LDA(dst, b, h) do { _Pragma("unroll") for (int m = 0; m < 4; ++m) _Pragma("unroll") for (int k = 0; k < 2; ++k) dst[m][k] = *(const PG8_LAS bf16x8*)(lds + PG8_SA(b, h) + aoff + m * 2048 + k * 1024); } while (0)
; #define PG8_LDB(dst, b, h) do { _Pragma("unroll") for (int n = 0; n < 2; ++n) _Pragma("unroll") for (int k = 0; k < 2; ++k) dst[n][k] = *(const PG8_LAS bf16x8*)(lds + PG8_SB(b, h) + boff + n * 2048 + k * 1024); } while (0)
; #define PG8_WAIT_V(n) asm volatile("s_waitcnt vmcnt(" #n ")" ::: "memory")
; #define PG8_WAIT_L(n) asm volatile("s_waitcnt lgkmcnt(" #n ")" ::: "memory")
; #define PG8_BAR __builtin_amdgcn_s_barrier()
; #define PG8_SCHED __builtin_amdgcn_sched_barrier(0)
; template <class Epi, class Sched, bool ALIGN_EPI = false, bool SP2 = false>
; __device__ __forceinline__ void gemm_phase(PG8_LAS unsigned char* lds, const Gemm g, const Sched& S, const Epi& E, const int tid_in) {
;     ...
;             const bool last = (t == nt - 2);
;             const char* a1 = cA + (size_t)(t + 1) * kstep;
;             const char* a2 = last ? nA : cA + (size_t)(t + 2) * kstep; const char* b2 = last ? nB : cB + (size_t)(t + 2) * kstep;
;             const char* a3 = a2 + kstep; const char* b3 = b2 + kstep;
;             if (last && has_next) S.a_ready(nxt);
;             if constexpr (SP2) {
;             PG8_LDB(B0, 0, 0); PG8_LDB(B1, 0, 1); PG8_SCHED; PG8_LDA(At, 0, 0); PG8_STAGE(PG8_SA(1, 1), a1 + hstepA, voffA);
;             PG8_WAIT_V(8); PG8_WAIT_L(0); PG8_BAR; PG8_MMA(0, 0, At, B0); PG8_MMA(0, 1, At, B1); PG8_BAR; PG8_SCHED;
;             PG8_LDA(At, 0, 1); PG8_STAGE(PG8_SB(0, 0), b2, voffB); PG8_STAGE(PG8_SB(0, 1), b2 + hstepB, voffB); PG8_STAGE(PG8_SA(0, 0), a2, voffA);
;             PG8_WAIT_V(8); PG8_WAIT_L(0); PG8_BAR; PG8_MMA(1, 0, At, B0); PG8_MMA(1, 1, At, B1); PG8_BAR; PG8_SCHED;
.LBB0_2041:
	s_add_u32 s22, s58, 0xfff80080
	s_addc_u32 s23, s59, -1
	s_add_i32 s65, 0, 0x10000
	s_cmp_eq_u32 s64, 28
	s_cselect_b32 s61, s38, s23
	s_cselect_b32 s60, s51, s22
	s_cselect_b32 s23, s49, s63
	s_cselect_b32 s22, s57, s62
	s_add_i32 s68, 0, 0x14000
	ds_read_b128 v[104:107], v249
	ds_read_b128 v[108:111], v249 offset:1024
	ds_read_b128 v[112:115], v249 offset:2048
	ds_read_b128 v[116:119], v249 offset:3072
	ds_read_b128 v[144:147], v249 offset:16384
	ds_read_b128 v[148:151], v249 offset:17408
	ds_read_b128 v[152:155], v249 offset:18432
	ds_read_b128 v[156:159], v249 offset:19456
	s_add_i32 m0, s28, 0xc000
	ds_read_b128 v[160:163], v204
	ds_read_b128 v[192:195], v204 offset:1024
	ds_read_b128 v[196:199], v204 offset:2048
	ds_read_b128 v[206:209], v204 offset:3072
	ds_read_b128 v[210:213], v204 offset:4096
	ds_read_b128 v[224:227], v204 offset:5120
	ds_read_b128 v[228:231], v204 offset:6144
	ds_read_b128 v[232:235], v204 offset:7168
	global_load_lds_dwordx4 v170, s[58:59]
	s_add_i32 m0, s28, 0xe000
	s_nop 0
	global_load_lds_dwordx4 v190, s[58:59]
	s_waitcnt vmcnt(8)
	s_waitcnt lgkmcnt(0)
	s_barrier
	s_waitcnt lgkmcnt(0)
	v_mfma_f32_16x16x32_bf16 v[140:143], v[104:107], v[160:163], v[140:143]
	v_mfma_f32_16x16x32_bf16 v[136:139], v[112:115], v[160:163], v[136:139]
	v_mfma_f32_16x16x32_bf16 v[124:127], v[104:107], v[196:199], v[124:127]
	v_mfma_f32_16x16x32_bf16 v[120:123], v[112:115], v[196:199], v[120:123]
	v_mfma_f32_16x16x32_bf16 v[92:95], v[104:107], v[210:213], v[92:95]
	v_mfma_f32_16x16x32_bf16 v[88:91], v[112:115], v[210:213], v[88:91]
	v_mfma_f32_16x16x32_bf16 v[76:79], v[104:107], v[228:231], v[76:79]
	v_mfma_f32_16x16x32_bf16 v[72:75], v[112:115], v[228:231], v[72:75]
	v_mfma_f32_16x16x32_bf16 v[140:143], v[108:111], v[192:195], v[140:143]
	v_mfma_f32_16x16x32_bf16 v[136:139], v[116:119], v[192:195], v[136:139]
	v_mfma_f32_16x16x32_bf16 v[124:127], v[108:111], v[206:209], v[124:127]
	v_mfma_f32_16x16x32_bf16 v[120:123], v[116:119], v[206:209], v[120:123]
	v_mfma_f32_16x16x32_bf16 v[92:95], v[108:111], v[224:227], v[92:95]
	v_mfma_f32_16x16x32_bf16 v[88:91], v[116:119], v[224:227], v[88:91]
	v_mfma_f32_16x16x32_bf16 v[76:79], v[108:111], v[232:235], v[76:79]
	v_mfma_f32_16x16x32_bf16 v[72:75], v[116:119], v[232:235], v[72:75]
	v_mfma_f32_16x16x32_bf16 v[132:135], v[144:147], v[160:163], v[132:135]
	v_mfma_f32_16x16x32_bf16 v[128:131], v[152:155], v[160:163], v[128:131]
	v_mfma_f32_16x16x32_bf16 v[100:103], v[144:147], v[196:199], v[100:103]
	v_mfma_f32_16x16x32_bf16 v[96:99], v[152:155], v[196:199], v[96:99]
	v_mfma_f32_16x16x32_bf16 v[84:87], v[144:147], v[210:213], v[84:87]
	v_mfma_f32_16x16x32_bf16 v[80:83], v[152:155], v[210:213], v[80:83]
	v_mfma_f32_16x16x32_bf16 v[68:71], v[144:147], v[228:231], v[68:71]
	v_mfma_f32_16x16x32_bf16 v[64:67], v[152:155], v[228:231], v[64:67]
	v_mfma_f32_16x16x32_bf16 v[132:135], v[148:151], v[192:195], v[132:135]
	v_mfma_f32_16x16x32_bf16 v[128:131], v[156:159], v[192:195], v[128:131]
	v_mfma_f32_16x16x32_bf16 v[100:103], v[148:151], v[206:209], v[100:103]
	v_mfma_f32_16x16x32_bf16 v[96:99], v[156:159], v[206:209], v[96:99]
	v_mfma_f32_16x16x32_bf16 v[84:87], v[148:151], v[224:227], v[84:87]
	v_mfma_f32_16x16x32_bf16 v[80:83], v[156:159], v[224:227], v[80:83]
	v_mfma_f32_16x16x32_bf16 v[68:71], v[148:151], v[232:235], v[68:71]
	v_mfma_f32_16x16x32_bf16 v[64:67], v[156:159], v[232:235], v[64:67]
	s_barrier
	s_add_i32 s65, s65, s21
	s_mov_b32 m0, s65
	ds_read_b128 v[160:163], v204 offset:16384
	ds_read_b128 v[192:195], v204 offset:17408
	ds_read_b128 v[196:199], v204 offset:18432
	ds_read_b128 v[206:209], v204 offset:19456
	ds_read_b128 v[210:213], v204 offset:20480
	ds_read_b128 v[224:227], v204 offset:21504
	ds_read_b128 v[228:231], v204 offset:22528
	ds_read_b128 v[232:235], v204 offset:23552
	global_load_lds_dwordx4 v172, s[22:23]
	s_add_i32 m0, s65, 0x2000
	s_add_u32 s66, s22, 0x80000
	s_addc_u32 s67, s23, 0
	s_add_i32 s65, s68, s21
	global_load_lds_dwordx4 v168, s[22:23]
	s_mov_b32 m0, s65
	s_nop 0
	global_load_lds_dwordx4 v172, s[66:67]
	s_add_i32 m0, s65, 0x2000
	s_nop 0
	global_load_lds_dwordx4 v168, s[66:67]
	s_add_u32 vcc_lo, s60, 0x80
	s_addc_u32 vcc_hi, s61, 0
	s_mov_b32 m0, s28
	s_nop 0
	global_load_lds_dwordx4 v164, s[60:61]
	s_mov_b32 m0, s29
	s_nop 0
	global_load_lds_dwordx4 v166, s[60:61]
	s_waitcnt vmcnt(8)
	s_waitcnt lgkmcnt(0)
	s_barrier
	s_waitcnt lgkmcnt(0)
	v_mfma_f32_16x16x32_bf16 v[60:63], v[104:107], v[160:163], v[60:63]
	v_mfma_f32_16x16x32_bf16 v[56:59], v[112:115], v[160:163], v[56:59]
	v_mfma_f32_16x16x32_bf16 v[44:47], v[104:107], v[196:199], v[44:47]
	v_mfma_f32_16x16x32_bf16 v[40:43], v[112:115], v[196:199], v[40:43]
	v_mfma_f32_16x16x32_bf16 v[28:31], v[104:107], v[210:213], v[28:31]
	v_mfma_f32_16x16x32_bf16 v[24:27], v[112:115], v[210:213], v[24:27]
	v_mfma_f32_16x16x32_bf16 v[12:15], v[104:107], v[228:231], v[12:15]
	v_mfma_f32_16x16x32_bf16 v[8:11], v[112:115], v[228:231], v[8:11]
	v_mfma_f32_16x16x32_bf16 v[60:63], v[108:111], v[192:195], v[60:63]
	v_mfma_f32_16x16x32_bf16 v[56:59], v[116:119], v[192:195], v[56:59]
	v_mfma_f32_16x16x32_bf16 v[44:47], v[108:111], v[206:209], v[44:47]
	v_mfma_f32_16x16x32_bf16 v[40:43], v[116:119], v[206:209], v[40:43]
	v_mfma_f32_16x16x32_bf16 v[28:31], v[108:111], v[224:227], v[28:31]
	v_mfma_f32_16x16x32_bf16 v[24:27], v[116:119], v[224:227], v[24:27]
	v_mfma_f32_16x16x32_bf16 v[12:15], v[108:111], v[232:235], v[12:15]
	v_mfma_f32_16x16x32_bf16 v[8:11], v[116:119], v[232:235], v[8:11]
	v_mfma_f32_16x16x32_bf16 v[52:55], v[144:147], v[160:163], v[52:55]
	v_mfma_f32_16x16x32_bf16 v[48:51], v[152:155], v[160:163], v[48:51]
	v_mfma_f32_16x16x32_bf16 v[36:39], v[144:147], v[196:199], v[36:39]
	v_mfma_f32_16x16x32_bf16 v[32:35], v[152:155], v[196:199], v[32:35]
	v_mfma_f32_16x16x32_bf16 v[20:23], v[144:147], v[210:213], v[20:23]
	v_mfma_f32_16x16x32_bf16 v[16:19], v[152:155], v[210:213], v[16:19]
	v_mfma_f32_16x16x32_bf16 v[4:7], v[144:147], v[228:231], v[4:7]
	v_mfma_f32_16x16x32_bf16 v[0:3], v[152:155], v[228:231], v[0:3]
	v_mfma_f32_16x16x32_bf16 v[52:55], v[148:151], v[192:195], v[52:55]
	v_mfma_f32_16x16x32_bf16 v[48:51], v[156:159], v[192:195], v[48:51]
	v_mfma_f32_16x16x32_bf16 v[36:39], v[148:151], v[206:209], v[36:39]
	v_mfma_f32_16x16x32_bf16 v[32:35], v[156:159], v[206:209], v[32:35]
	v_mfma_f32_16x16x32_bf16 v[20:23], v[148:151], v[224:227], v[20:23]
	v_mfma_f32_16x16x32_bf16 v[16:19], v[156:159], v[224:227], v[16:19]
	v_mfma_f32_16x16x32_bf16 v[4:7], v[148:151], v[232:235], v[4:7]
	v_mfma_f32_16x16x32_bf16 v[0:3], v[156:159], v[232:235], v[0:3]
	s_barrier
; #define PG8_STAGE(bufoff, gbase, voff) do { _Pragma("unroll") for (int _i = 0; _i < 2; ++_i) \
;         __builtin_amdgcn_global_load_lds((const unsigned*)((const char*)(gbase) + (voff)[_i]), (PG8_LAS unsigned*)(lds + (bufoff) + ldsw + _i * 8192), 16, 0, 0); } while (0)
; #define PG8_LDA(dst, b, h) do { _Pragma("unroll") for (int m = 0; m < 4; ++m) _Pragma("unroll") for (int k = 0; k < 2; ++k) dst[m][k] = *(const PG8_LAS bf16x8*)(lds + PG8_SA(b, h) + aoff + m * 2048 + k * 1024); } while (0)
; #define PG8_LDB(dst, b, h) do { _Pragma("unroll") for (int n = 0; n < 2; ++n) _Pragma("unroll") for (int k = 0; k < 2; ++k) dst[n][k] = *(const PG8_LAS bf16x8*)(lds + PG8_SB(b, h) + boff + n * 2048 + k * 1024); } while (0)
; #define PG8_MMA(ai, bj, At, Bt) do { __builtin_amdgcn_s_setprio(1); _Pragma("unroll") for (int m = 0; m < 4; ++m) _Pragma("unroll") for (int n = 0; n < 2; ++n) _Pragma("unroll") for (int k = 0; k < 2; ++k) \
;         acc[ai][bj][m][n] = __builtin_amdgcn_mfma_f32_16x16x32_bf16(Bt[n][k], At[m][k], acc[ai][bj][m][n], 0, 0, 0); __builtin_amdgcn_s_setprio(0); } while (0)
; #define PG8_WAIT_V(n) asm volatile("s_waitcnt vmcnt(" #n ")" ::: "memory")
; #define PG8_WAIT_L(n) asm volatile("s_waitcnt lgkmcnt(" #n ")" ::: "memory")
; #define PG8_BAR __builtin_amdgcn_s_barrier()
; #define PG8_SCHED __builtin_amdgcn_sched_barrier(0)
; template <class Epi, class Sched, bool ALIGN_EPI = false, bool SP2 = false>
; __device__ __forceinline__ void gemm_phase(PG8_LAS unsigned char* lds, const Gemm g, const Sched& S, const Epi& E, const int tid_in) {
;     ...
;             PG8_LDB(B0, 1, 0); PG8_LDB(B1, 1, 1); PG8_SCHED; PG8_LDA(At, 1, 0); PG8_STAGE(PG8_SA(0, 1), a2 + hstepA, voffA);
;             PG8_WAIT_V(8); PG8_WAIT_L(0); PG8_BAR; PG8_MMA(0, 0, At, B0); PG8_MMA(0, 1, At, B1); PG8_BAR; PG8_SCHED;
;             PG8_LDA(At, 1, 1); PG8_STAGE(PG8_SB(1, 0), b3, voffB); PG8_STAGE(PG8_SB(1, 1), b3 + hstepB, voffB); PG8_STAGE(PG8_SA(1, 0), a3, voffA);
;             PG8_WAIT_V(8); PG8_WAIT_L(0); PG8_BAR; PG8_MMA(1, 0, At, B0); PG8_MMA(1, 1, At, B1); PG8_BAR; PG8_SCHED;
	s_add_i32 s65, 0, 0x18000
	s_add_i32 s66, 0, 0x1c000
	ds_read_b128 v[104:107], v249 offset:32768
	ds_read_b128 v[108:111], v249 offset:33792
	ds_read_b128 v[112:115], v249 offset:34816
	ds_read_b128 v[116:119], v249 offset:35840
	ds_read_b128 v[144:147], v249 offset:49152
	ds_read_b128 v[148:151], v249 offset:50176
	ds_read_b128 v[152:155], v249 offset:51200
	ds_read_b128 v[156:159], v249 offset:52224
	s_add_u32 s60, s60, 0x80000
	s_addc_u32 s61, s61, 0
	s_mov_b32 m0, s30
	ds_read_b128 v[160:163], v204 offset:32768
	ds_read_b128 v[192:195], v204 offset:33792
	ds_read_b128 v[196:199], v204 offset:34816
	ds_read_b128 v[206:209], v204 offset:35840
	ds_read_b128 v[210:213], v204 offset:36864
	ds_read_b128 v[224:227], v204 offset:37888
	ds_read_b128 v[228:231], v204 offset:38912
	ds_read_b128 v[232:235], v204 offset:39936
	global_load_lds_dwordx4 v164, s[60:61]
	s_mov_b32 m0, s6
	s_nop 0
	global_load_lds_dwordx4 v166, s[60:61]
	s_waitcnt vmcnt(8)
	s_waitcnt lgkmcnt(0)
	s_barrier
	s_waitcnt lgkmcnt(0)
	v_mfma_f32_16x16x32_bf16 v[140:143], v[104:107], v[160:163], v[140:143]
	v_mfma_f32_16x16x32_bf16 v[136:139], v[112:115], v[160:163], v[136:139]
	v_mfma_f32_16x16x32_bf16 v[124:127], v[104:107], v[196:199], v[124:127]
	v_mfma_f32_16x16x32_bf16 v[120:123], v[112:115], v[196:199], v[120:123]
	v_mfma_f32_16x16x32_bf16 v[92:95], v[104:107], v[210:213], v[92:95]
	v_mfma_f32_16x16x32_bf16 v[88:91], v[112:115], v[210:213], v[88:91]
	v_mfma_f32_16x16x32_bf16 v[76:79], v[104:107], v[228:231], v[76:79]
	v_mfma_f32_16x16x32_bf16 v[72:75], v[112:115], v[228:231], v[72:75]
	v_mfma_f32_16x16x32_bf16 v[140:143], v[108:111], v[192:195], v[140:143]
	v_mfma_f32_16x16x32_bf16 v[136:139], v[116:119], v[192:195], v[136:139]
	v_mfma_f32_16x16x32_bf16 v[124:127], v[108:111], v[206:209], v[124:127]
	v_mfma_f32_16x16x32_bf16 v[120:123], v[116:119], v[206:209], v[120:123]
	v_mfma_f32_16x16x32_bf16 v[92:95], v[108:111], v[224:227], v[92:95]
	v_mfma_f32_16x16x32_bf16 v[88:91], v[116:119], v[224:227], v[88:91]
	v_mfma_f32_16x16x32_bf16 v[76:79], v[108:111], v[232:235], v[76:79]
	v_mfma_f32_16x16x32_bf16 v[72:75], v[116:119], v[232:235], v[72:75]
	v_mfma_f32_16x16x32_bf16 v[132:135], v[144:147], v[160:163], v[132:135]
	v_mfma_f32_16x16x32_bf16 v[128:131], v[152:155], v[160:163], v[128:131]
	v_mfma_f32_16x16x32_bf16 v[100:103], v[144:147], v[196:199], v[100:103]
	v_mfma_f32_16x16x32_bf16 v[96:99], v[152:155], v[196:199], v[96:99]
	v_mfma_f32_16x16x32_bf16 v[84:87], v[144:147], v[210:213], v[84:87]
	v_mfma_f32_16x16x32_bf16 v[80:83], v[152:155], v[210:213], v[80:83]
	v_mfma_f32_16x16x32_bf16 v[68:71], v[144:147], v[228:231], v[68:71]
	v_mfma_f32_16x16x32_bf16 v[64:67], v[152:155], v[228:231], v[64:67]
	v_mfma_f32_16x16x32_bf16 v[132:135], v[148:151], v[192:195], v[132:135]
	v_mfma_f32_16x16x32_bf16 v[128:131], v[156:159], v[192:195], v[128:131]
	v_mfma_f32_16x16x32_bf16 v[100:103], v[148:151], v[206:209], v[100:103]
	v_mfma_f32_16x16x32_bf16 v[96:99], v[156:159], v[206:209], v[96:99]
	v_mfma_f32_16x16x32_bf16 v[84:87], v[148:151], v[224:227], v[84:87]
	v_mfma_f32_16x16x32_bf16 v[80:83], v[156:159], v[224:227], v[80:83]
	v_mfma_f32_16x16x32_bf16 v[68:71], v[148:151], v[232:235], v[68:71]
	v_mfma_f32_16x16x32_bf16 v[64:67], v[156:159], v[232:235], v[64:67]
	s_barrier
	s_add_i32 s60, s65, s21
	s_mov_b32 m0, s60
	ds_read_b128 v[160:163], v204 offset:49152
	ds_read_b128 v[192:195], v204 offset:50176
	ds_read_b128 v[196:199], v204 offset:51200
	ds_read_b128 v[206:209], v204 offset:52224
	ds_read_b128 v[210:213], v204 offset:53248
	ds_read_b128 v[224:227], v204 offset:54272
	ds_read_b128 v[228:231], v204 offset:55296
	ds_read_b128 v[232:235], v204 offset:56320
	s_add_u32 s100, s22, 0x80
	s_addc_u32 s101, s23, 0
	global_load_lds_dwordx4 v172, s[100:101]
	s_add_i32 m0, s60, 0x2000
	s_add_u32 s22, s22, 0x80080
	s_addc_u32 s23, s23, 0
	s_add_i32 s60, s66, s21
	global_load_lds_dwordx4 v168, s[100:101]
	s_mov_b32 m0, s60
	s_nop 0
	global_load_lds_dwordx4 v172, s[22:23]
	s_add_i32 m0, s60, 0x2000
	s_nop 0
	global_load_lds_dwordx4 v168, s[22:23]
	s_mov_b32 m0, s33
	s_nop 0
	global_load_lds_dwordx4 v164, vcc
	s_mov_b32 m0, s34
	s_nop 0
	global_load_lds_dwordx4 v166, vcc
	s_waitcnt vmcnt(8)
	s_waitcnt lgkmcnt(0)
	s_barrier
	s_waitcnt lgkmcnt(0)
	v_mfma_f32_16x16x32_bf16 v[60:63], v[104:107], v[160:163], v[60:63]
	v_mfma_f32_16x16x32_bf16 v[56:59], v[112:115], v[160:163], v[56:59]
	v_mfma_f32_16x16x32_bf16 v[44:47], v[104:107], v[196:199], v[44:47]
	v_mfma_f32_16x16x32_bf16 v[40:43], v[112:115], v[196:199], v[40:43]
	v_mfma_f32_16x16x32_bf16 v[28:31], v[104:107], v[210:213], v[28:31]
	v_mfma_f32_16x16x32_bf16 v[24:27], v[112:115], v[210:213], v[24:27]
	v_mfma_f32_16x16x32_bf16 v[12:15], v[104:107], v[228:231], v[12:15]
	v_mfma_f32_16x16x32_bf16 v[8:11], v[112:115], v[228:231], v[8:11]
	v_mfma_f32_16x16x32_bf16 v[60:63], v[108:111], v[192:195], v[60:63]
	v_mfma_f32_16x16x32_bf16 v[56:59], v[116:119], v[192:195], v[56:59]
	v_mfma_f32_16x16x32_bf16 v[44:47], v[108:111], v[206:209], v[44:47]
	v_mfma_f32_16x16x32_bf16 v[40:43], v[116:119], v[206:209], v[40:43]
	v_mfma_f32_16x16x32_bf16 v[28:31], v[108:111], v[224:227], v[28:31]
	v_mfma_f32_16x16x32_bf16 v[24:27], v[116:119], v[224:227], v[24:27]
	v_mfma_f32_16x16x32_bf16 v[12:15], v[108:111], v[232:235], v[12:15]
	v_mfma_f32_16x16x32_bf16 v[8:11], v[116:119], v[232:235], v[8:11]
	v_mfma_f32_16x16x32_bf16 v[52:55], v[144:147], v[160:163], v[52:55]
	v_mfma_f32_16x16x32_bf16 v[48:51], v[152:155], v[160:163], v[48:51]
	v_mfma_f32_16x16x32_bf16 v[36:39], v[144:147], v[196:199], v[36:39]
	v_mfma_f32_16x16x32_bf16 v[32:35], v[152:155], v[196:199], v[32:35]
	v_mfma_f32_16x16x32_bf16 v[20:23], v[144:147], v[210:213], v[20:23]
	v_mfma_f32_16x16x32_bf16 v[16:19], v[152:155], v[210:213], v[16:19]
	v_mfma_f32_16x16x32_bf16 v[4:7], v[144:147], v[228:231], v[4:7]
	v_mfma_f32_16x16x32_bf16 v[0:3], v[152:155], v[228:231], v[0:3]
	v_mfma_f32_16x16x32_bf16 v[52:55], v[148:151], v[192:195], v[52:55]
	v_mfma_f32_16x16x32_bf16 v[48:51], v[156:159], v[192:195], v[48:51]
	v_mfma_f32_16x16x32_bf16 v[36:39], v[148:151], v[206:209], v[36:39]
	v_mfma_f32_16x16x32_bf16 v[32:35], v[156:159], v[206:209], v[32:35]
	v_mfma_f32_16x16x32_bf16 v[20:23], v[148:151], v[224:227], v[20:23]
	v_mfma_f32_16x16x32_bf16 v[16:19], v[156:159], v[224:227], v[16:19]
	v_mfma_f32_16x16x32_bf16 v[4:7], v[148:151], v[232:235], v[4:7]
	v_mfma_f32_16x16x32_bf16 v[0:3], v[156:159], v[232:235], v[0:3]
	s_barrier
	s_add_i32 s64, s64, 2
	s_add_u32 s58, s58, 0x100
	s_addc_u32 s59, s59, 0
	s_add_u32 s62, s62, 0x100
	s_addc_u32 s63, s63, 0
	s_cmp_gt_u32 s64, 29
	s_cbranch_scc0 .LBB0_2041
	s_and_b64 vcc, exec, s[46:47]
	s_cbranch_vccz .LBB0_2044
	s_barrier

;     __device__ __forceinline__ void a_ready(const Unit& u) const { wait_panel(cnt, u.pm, need, tmo, wave); }
;     __device__ __forceinline__ void a_ready(const Unit& u) const { wait_panel(cnt, u.pm, need, tmo, wave); }
; #define PG8_STAGE(bufoff, gbase, voff) do { _Pragma("unroll") for (int _i = 0; _i < 2; ++_i) \
;         __builtin_amdgcn_global_load_lds((const unsigned*)((const char*)(gbase) + (voff)[_i]), (PG8_LAS unsigned*)(lds + (bufoff) + ldsw + _i * 8192), 16, 0, 0); } while (0)
; #define PG8_LDA(dst, b, h) do { _Pragma("unroll") for (int m = 0; m < 4; ++m) _Pragma("unroll") for (int k = 0; k < 2; ++k) dst[m][k] = *(const PG8_LAS bf16x8*)(lds + PG8_SA(b, h) + aoff + m * 2048 + k * 1024); } while (0)
; #define PG8_LDB(dst, b, h) do { _Pragma("unroll") for (int n = 0; n < 2; ++n) _Pragma("unroll") for (int k = 0; k < 2; ++k) dst[n][k] = *(const PG8_LAS bf16x8*)(lds + PG8_SB(b, h) + boff + n * 2048 + k * 1024); } while (0)
; #define PG8_WAIT_V(n) asm volatile("s_waitcnt vmcnt(" #n ")" ::: "memory")
; #define PG8_WAIT_L(n) asm volatile("s_waitcnt lgkmcnt(" #n ")" ::: "memory")
; #define PG8_BAR __builtin_amdgcn_s_barrier()
; #define PG8_SCHED __builtin_amdgcn_sched_barrier(0)
; template <class Epi, class Sched, bool ALIGN_EPI = false, bool SP2 = false>
; __device__ __forceinline__ void gemm_phase(PG8_LAS unsigned char* lds, const Gemm g, const Sched& S, const Epi& E, const int tid_in) {
;     ...
;             const bool last = (t == nt - 2);
;             const char* a1 = cA + (size_t)(t + 1) * kstep;
;             const char* a2 = last ? nA : cA + (size_t)(t + 2) * kstep; const char* b2 = last ? nB : cB + (size_t)(t + 2) * kstep;
;             const char* a3 = a2 + kstep; const char* b3 = b2 + kstep;
;             if (last && has_next) S.a_ready(nxt);
;             if constexpr (SP2) {
;             PG8_LDB(B0, 0, 0); PG8_LDB(B1, 0, 1); PG8_SCHED; PG8_LDA(At, 0, 0); PG8_STAGE(PG8_SA(1, 1), a1 + hstepA, voffA);
;             PG8_WAIT_V(8); PG8_WAIT_L(0); PG8_BAR; PG8_MMA(0, 0, At, B0); PG8_MMA(0, 1, At, B1); PG8_BAR; PG8_SCHED;
;             PG8_LDA(At, 0, 1); PG8_STAGE(PG8_SB(0, 0), b2, voffB); PG8_STAGE(PG8_SB(0, 1), b2 + hstepB, voffB); PG8_STAGE(PG8_SA(0, 0), a2, voffA);
;             PG8_WAIT_V(8); PG8_WAIT_L(0); PG8_BAR; PG8_MMA(1, 0, At, B0); PG8_MMA(1, 1, At, B1); PG8_BAR; PG8_SCHED;
.LBB0_2059:
	s_add_u32 s22, s62, 0xfff80080
	s_addc_u32 s23, s63, -1
	s_add_i32 s55, 0, 0x10000
	s_cmp_eq_u32 s53, 4
	s_cselect_b32 s65, s61, s23
	s_cselect_b32 s64, s60, s22
	s_cselect_b32 s23, s59, s38
	s_cselect_b32 s22, s58, s35
	s_add_i32 s57, 0, 0x14000
	ds_read_b128 v[64:67], v249
	ds_read_b128 v[68:71], v249 offset:1024
	ds_read_b128 v[72:75], v249 offset:2048
	ds_read_b128 v[76:79], v249 offset:3072
	ds_read_b128 v[80:83], v249 offset:16384
	ds_read_b128 v[84:87], v249 offset:17408
	ds_read_b128 v[88:91], v249 offset:18432
	ds_read_b128 v[92:95], v249 offset:19456
	s_add_i32 m0, s12, 0xc000
	ds_read_b128 v[96:99], v154
	ds_read_b128 v[100:103], v154 offset:1024
	ds_read_b128 v[104:107], v154 offset:2048
	ds_read_b128 v[108:111], v154 offset:3072
	ds_read_b128 v[112:115], v154 offset:4096
	ds_read_b128 v[116:119], v154 offset:5120
	ds_read_b128 v[120:123], v154 offset:6144
	ds_read_b128 v[124:127], v154 offset:7168
	global_load_lds_dwordx4 v148, s[62:63]
	s_add_i32 m0, s12, 0xe000
	s_nop 0
	global_load_lds_dwordx4 v146, s[62:63]
	s_waitcnt vmcnt(8)
	s_waitcnt lgkmcnt(0)
	s_barrier
	s_waitcnt lgkmcnt(0)
	v_mfma_f32_16x16x32_bf16 v[60:63], v[64:67], v[96:99], v[60:63]
	v_mfma_f32_16x16x32_bf16 v[56:59], v[72:75], v[96:99], v[56:59]
	v_mfma_f32_16x16x32_bf16 v[48:51], v[64:67], v[104:107], v[48:51]
	v_mfma_f32_16x16x32_bf16 v[40:43], v[72:75], v[104:107], v[40:43]
	v_mfma_f32_16x16x32_bf16 v[32:35], v[64:67], v[112:115], v[32:35]
	v_mfma_f32_16x16x32_bf16 v[24:27], v[72:75], v[112:115], v[24:27]
	v_mfma_f32_16x16x32_bf16 v[16:19], v[64:67], v[120:123], v[16:19]
	v_mfma_f32_16x16x32_bf16 v[8:11], v[72:75], v[120:123], v[8:11]
	v_mfma_f32_16x16x32_bf16 v[60:63], v[68:71], v[100:103], v[60:63]
	v_mfma_f32_16x16x32_bf16 v[56:59], v[76:79], v[100:103], v[56:59]
	v_mfma_f32_16x16x32_bf16 v[48:51], v[68:71], v[108:111], v[48:51]
	v_mfma_f32_16x16x32_bf16 v[40:43], v[76:79], v[108:111], v[40:43]
	v_mfma_f32_16x16x32_bf16 v[32:35], v[68:71], v[116:119], v[32:35]
	v_mfma_f32_16x16x32_bf16 v[24:27], v[76:79], v[116:119], v[24:27]
	v_mfma_f32_16x16x32_bf16 v[16:19], v[68:71], v[124:127], v[16:19]
	v_mfma_f32_16x16x32_bf16 v[8:11], v[76:79], v[124:127], v[8:11]
	v_mfma_f32_16x16x32_bf16 v[52:55], v[80:83], v[96:99], v[52:55]
	v_mfma_f32_16x16x32_bf16 v[44:47], v[88:91], v[96:99], v[44:47]
	v_mfma_f32_16x16x32_bf16 v[36:39], v[80:83], v[104:107], v[36:39]
	v_mfma_f32_16x16x32_bf16 v[28:31], v[88:91], v[104:107], v[28:31]
	v_mfma_f32_16x16x32_bf16 v[20:23], v[80:83], v[112:115], v[20:23]
	v_mfma_f32_16x16x32_bf16 v[12:15], v[88:91], v[112:115], v[12:15]
	v_mfma_f32_16x16x32_bf16 v[4:7], v[80:83], v[120:123], v[4:7]
	v_mfma_f32_16x16x32_bf16 v[0:3], v[88:91], v[120:123], v[0:3]
	v_mfma_f32_16x16x32_bf16 v[52:55], v[84:87], v[100:103], v[52:55]
	v_mfma_f32_16x16x32_bf16 v[44:47], v[92:95], v[100:103], v[44:47]
	v_mfma_f32_16x16x32_bf16 v[36:39], v[84:87], v[108:111], v[36:39]
	v_mfma_f32_16x16x32_bf16 v[28:31], v[92:95], v[108:111], v[28:31]
	v_mfma_f32_16x16x32_bf16 v[20:23], v[84:87], v[116:119], v[20:23]
	v_mfma_f32_16x16x32_bf16 v[12:15], v[92:95], v[116:119], v[12:15]
	v_mfma_f32_16x16x32_bf16 v[4:7], v[84:87], v[124:127], v[4:7]
	v_mfma_f32_16x16x32_bf16 v[0:3], v[92:95], v[124:127], v[0:3]
	s_barrier
	s_add_i32 s55, s55, s6
	s_mov_b32 m0, s55
	s_nop 0
	global_load_lds_dwordx4 v172, s[22:23]
	s_add_i32 m0, s55, 0x2000
	s_add_u32 s66, s22, 0x80000
	s_addc_u32 s67, s23, 0
	s_add_i32 s55, s57, s6
	global_load_lds_dwordx4 v128, s[22:23]
	s_mov_b32 m0, s55
	s_nop 0
	global_load_lds_dwordx4 v172, s[66:67]
	s_add_i32 m0, s55, 0x2000
	s_nop 0
	global_load_lds_dwordx4 v128, s[66:67]
	s_mov_b32 m0, s12
	s_nop 0
	global_load_lds_dwordx4 v172, s[64:65]
	s_mov_b32 m0, s20
	s_nop 0
	global_load_lds_dwordx4 v128, s[64:65]
	s_waitcnt vmcnt(8)
	s_waitcnt lgkmcnt(0)
	s_barrier
	s_barrier
; #define PG8_STAGE(bufoff, gbase, voff) do { _Pragma("unroll") for (int _i = 0; _i < 2; ++_i) \
;         __builtin_amdgcn_global_load_lds((const unsigned*)((const char*)(gbase) + (voff)[_i]), (PG8_LAS unsigned*)(lds + (bufoff) + ldsw + _i * 8192), 16, 0, 0); } while (0)
; #define PG8_LDA(dst, b, h) do { _Pragma("unroll") for (int m = 0; m < 4; ++m) _Pragma("unroll") for (int k = 0; k < 2; ++k) dst[m][k] = *(const PG8_LAS bf16x8*)(lds + PG8_SA(b, h) + aoff + m * 2048 + k * 1024); } while (0)
; #define PG8_LDB(dst, b, h) do { _Pragma("unroll") for (int n = 0; n < 2; ++n) _Pragma("unroll") for (int k = 0; k < 2; ++k) dst[n][k] = *(const PG8_LAS bf16x8*)(lds + PG8_SB(b, h) + boff + n * 2048 + k * 1024); } while (0)
; #define PG8_MMA(ai, bj, At, Bt) do { __builtin_amdgcn_s_setprio(1); _Pragma("unroll") for (int m = 0; m < 4; ++m) _Pragma("unroll") for (int n = 0; n < 2; ++n) _Pragma("unroll") for (int k = 0; k < 2; ++k) \
;         acc[ai][bj][m][n] = __builtin_amdgcn_mfma_f32_16x16x32_bf16(Bt[n][k], At[m][k], acc[ai][bj][m][n], 0, 0, 0); __builtin_amdgcn_s_setprio(0); } while (0)
; #define PG8_WAIT_V(n) asm volatile("s_waitcnt vmcnt(" #n ")" ::: "memory")
; #define PG8_WAIT_L(n) asm volatile("s_waitcnt lgkmcnt(" #n ")" ::: "memory")
; #define PG8_BAR __builtin_amdgcn_s_barrier()
; #define PG8_SCHED __builtin_amdgcn_sched_barrier(0)
; template <class Epi, class Sched, bool ALIGN_EPI = false, bool SP2 = false>
; __device__ __forceinline__ void gemm_phase(PG8_LAS unsigned char* lds, const Gemm g, const Sched& S, const Epi& E, const int tid_in) {
;     ...
;             PG8_LDB(B0, 1, 0); PG8_LDB(B1, 1, 1); PG8_SCHED; PG8_LDA(At, 1, 0); PG8_STAGE(PG8_SA(0, 1), a2 + hstepA, voffA);
;             PG8_WAIT_V(8); PG8_WAIT_L(0); PG8_BAR; PG8_MMA(0, 0, At, B0); PG8_MMA(0, 1, At, B1); PG8_BAR; PG8_SCHED;
;             PG8_LDA(At, 1, 1); PG8_STAGE(PG8_SB(1, 0), b3, voffB); PG8_STAGE(PG8_SB(1, 1), b3 + hstepB, voffB); PG8_STAGE(PG8_SA(1, 0), a3, voffA);
;             PG8_WAIT_V(8); PG8_WAIT_L(0); PG8_BAR; PG8_MMA(1, 0, At, B0); PG8_MMA(1, 1, At, B1); PG8_BAR; PG8_SCHED;
	s_add_i32 s55, 0, 0x18000
	s_add_i32 s57, 0, 0x1c000
	ds_read_b128 v[64:67], v249 offset:32768
	ds_read_b128 v[68:71], v249 offset:33792
	ds_read_b128 v[72:75], v249 offset:34816
	ds_read_b128 v[76:79], v249 offset:35840
	ds_read_b128 v[80:83], v249 offset:49152
	ds_read_b128 v[84:87], v249 offset:50176
	ds_read_b128 v[88:91], v249 offset:51200
	ds_read_b128 v[92:95], v249 offset:52224
	s_add_u32 s64, s64, 0x80000
	s_addc_u32 s65, s65, 0
	s_mov_b32 m0, s21
	ds_read_b128 v[96:99], v154 offset:32768
	ds_read_b128 v[100:103], v154 offset:33792
	ds_read_b128 v[104:107], v154 offset:34816
	ds_read_b128 v[108:111], v154 offset:35840
	ds_read_b128 v[112:115], v154 offset:36864
	ds_read_b128 v[116:119], v154 offset:37888
	ds_read_b128 v[120:123], v154 offset:38912
	ds_read_b128 v[124:127], v154 offset:39936
	global_load_lds_dwordx4 v172, s[64:65]
	s_mov_b32 m0, s28
	s_nop 0
	global_load_lds_dwordx4 v128, s[64:65]
	s_waitcnt vmcnt(8)
	s_waitcnt lgkmcnt(0)
	s_barrier
	s_waitcnt lgkmcnt(0)
	v_mfma_f32_16x16x32_bf16 v[60:63], v[64:67], v[96:99], v[60:63]
	v_mfma_f32_16x16x32_bf16 v[56:59], v[72:75], v[96:99], v[56:59]
	v_mfma_f32_16x16x32_bf16 v[48:51], v[64:67], v[104:107], v[48:51]
	v_mfma_f32_16x16x32_bf16 v[40:43], v[72:75], v[104:107], v[40:43]
	v_mfma_f32_16x16x32_bf16 v[32:35], v[64:67], v[112:115], v[32:35]
	v_mfma_f32_16x16x32_bf16 v[24:27], v[72:75], v[112:115], v[24:27]
	v_mfma_f32_16x16x32_bf16 v[16:19], v[64:67], v[120:123], v[16:19]
	v_mfma_f32_16x16x32_bf16 v[8:11], v[72:75], v[120:123], v[8:11]
	v_mfma_f32_16x16x32_bf16 v[60:63], v[68:71], v[100:103], v[60:63]
	v_mfma_f32_16x16x32_bf16 v[56:59], v[76:79], v[100:103], v[56:59]
	v_mfma_f32_16x16x32_bf16 v[48:51], v[68:71], v[108:111], v[48:51]
	v_mfma_f32_16x16x32_bf16 v[40:43], v[76:79], v[108:111], v[40:43]
	v_mfma_f32_16x16x32_bf16 v[32:35], v[68:71], v[116:119], v[32:35]
	v_mfma_f32_16x16x32_bf16 v[24:27], v[76:79], v[116:119], v[24:27]
	v_mfma_f32_16x16x32_bf16 v[16:19], v[68:71], v[124:127], v[16:19]
	v_mfma_f32_16x16x32_bf16 v[8:11], v[76:79], v[124:127], v[8:11]
	v_mfma_f32_16x16x32_bf16 v[52:55], v[80:83], v[96:99], v[52:55]
	v_mfma_f32_16x16x32_bf16 v[44:47], v[88:91], v[96:99], v[44:47]
	v_mfma_f32_16x16x32_bf16 v[36:39], v[80:83], v[104:107], v[36:39]
	v_mfma_f32_16x16x32_bf16 v[28:31], v[88:91], v[104:107], v[28:31]
	v_mfma_f32_16x16x32_bf16 v[20:23], v[80:83], v[112:115], v[20:23]
	v_mfma_f32_16x16x32_bf16 v[12:15], v[88:91], v[112:115], v[12:15]
	v_mfma_f32_16x16x32_bf16 v[4:7], v[80:83], v[120:123], v[4:7]
	v_mfma_f32_16x16x32_bf16 v[0:3], v[88:91], v[120:123], v[0:3]
	v_mfma_f32_16x16x32_bf16 v[52:55], v[84:87], v[100:103], v[52:55]
	v_mfma_f32_16x16x32_bf16 v[44:47], v[92:95], v[100:103], v[44:47]
	v_mfma_f32_16x16x32_bf16 v[36:39], v[84:87], v[108:111], v[36:39]
	v_mfma_f32_16x16x32_bf16 v[28:31], v[92:95], v[108:111], v[28:31]
	v_mfma_f32_16x16x32_bf16 v[20:23], v[84:87], v[116:119], v[20:23]
	v_mfma_f32_16x16x32_bf16 v[12:15], v[92:95], v[116:119], v[12:15]
	v_mfma_f32_16x16x32_bf16 v[4:7], v[84:87], v[124:127], v[4:7]
	v_mfma_f32_16x16x32_bf16 v[0:3], v[92:95], v[124:127], v[0:3]
	s_barrier
	s_add_i32 s55, s55, s6
	s_mov_b32 m0, s55
	s_nop 0
	s_add_u32 s100, s22, 0x80
	s_addc_u32 s101, s23, 0
	global_load_lds_dwordx4 v172, s[100:101]
	s_add_i32 m0, s55, 0x2000
	s_add_u32 s22, s22, 0x80080
	s_addc_u32 s23, s23, 0
	s_add_i32 s55, s57, s6
	global_load_lds_dwordx4 v128, s[100:101]
	s_mov_b32 m0, s55
	s_nop 0
	global_load_lds_dwordx4 v172, s[22:23]
	s_add_i32 m0, s55, 0x2000
	s_nop 0
	global_load_lds_dwordx4 v128, s[22:23]
	s_mov_b32 m0, s29
	s_nop 0
	s_add_u32 s100, s64, 0xfff80080
	s_addc_u32 s101, s65, -1
	global_load_lds_dwordx4 v172, s[100:101]
	s_mov_b32 m0, s30
	s_nop 0
	global_load_lds_dwordx4 v128, s[100:101]
	s_waitcnt vmcnt(8)
	s_waitcnt lgkmcnt(0)
	s_barrier
	s_barrier
	s_add_i32 s53, s53, 2
	s_add_u32 s62, s62, 0x100
	s_addc_u32 s63, s63, 0
	s_add_u32 s35, s35, 0x100
	s_addc_u32 s38, s38, 0
	s_cmp_gt_u32 s53, 5
	s_cbranch_scc0 .LBB0_2059
	s_and_b64 vcc, exec, s[36:37]
	s_cbranch_vccz .LBB0_2062
	s_barrier

;     __device__ __forceinline__ void a_ready(const Unit& u) const { wait_panel(cnt, u.pm, need, tmo, wave); }
;     __device__ __forceinline__ void a_ready(const Unit& u) const { wait_panel(cnt, u.pm, need, tmo, wave); }
; #define PG8_STAGE(bufoff, gbase, voff) do { _Pragma("unroll") for (int _i = 0; _i < 2; ++_i) \
;         __builtin_amdgcn_global_load_lds((const unsigned*)((const char*)(gbase) + (voff)[_i]), (PG8_LAS unsigned*)(lds + (bufoff) + ldsw + _i * 8192), 16, 0, 0); } while (0)
; #define PG8_LDA(dst, b, h) do { _Pragma("unroll") for (int m = 0; m < 4; ++m) _Pragma("unroll") for (int k = 0; k < 2; ++k) dst[m][k] = *(const PG8_LAS bf16x8*)(lds + PG8_SA(b, h) + aoff + m * 2048 + k * 1024); } while (0)
; #define PG8_LDB(dst, b, h) do { _Pragma("unroll") for (int n = 0; n < 2; ++n) _Pragma("unroll") for (int k = 0; k < 2; ++k) dst[n][k] = *(const PG8_LAS bf16x8*)(lds + PG8_SB(b, h) + boff + n * 2048 + k * 1024); } while (0)
; #define PG8_WAIT_V(n) asm volatile("s_waitcnt vmcnt(" #n ")" ::: "memory")
; #define PG8_WAIT_L(n) asm volatile("s_waitcnt lgkmcnt(" #n ")" ::: "memory")
; #define PG8_BAR __builtin_amdgcn_s_barrier()
; #define PG8_SCHED __builtin_amdgcn_sched_barrier(0)
; template <class Epi, class Sched, bool ALIGN_EPI = false, bool SP2 = false>
; __device__ __forceinline__ void gemm_phase(PG8_LAS unsigned char* lds, const Gemm g, const Sched& S, const Epi& E, const int tid_in) {
;     ...
;             const bool last = (t == nt - 2);
;             const char* a1 = cA + (size_t)(t + 1) * kstep;
;             const char* a2 = last ? nA : cA + (size_t)(t + 2) * kstep; const char* b2 = last ? nB : cB + (size_t)(t + 2) * kstep;
;             const char* a3 = a2 + kstep; const char* b3 = b2 + kstep;
;             if (last && has_next) S.a_ready(nxt);
;             if constexpr (SP2) {
;             PG8_LDB(B0, 0, 0); PG8_LDB(B1, 0, 1); PG8_SCHED; PG8_LDA(At, 0, 0); PG8_STAGE(PG8_SA(1, 1), a1 + hstepA, voffA);
;             PG8_WAIT_V(8); PG8_WAIT_L(0); PG8_BAR; PG8_MMA(0, 0, At, B0); PG8_MMA(0, 1, At, B1); PG8_BAR; PG8_SCHED;
;             PG8_LDA(At, 0, 1); PG8_STAGE(PG8_SB(0, 0), b2, voffB); PG8_STAGE(PG8_SB(0, 1), b2 + hstepB, voffB); PG8_STAGE(PG8_SA(0, 0), a2, voffA);
;             PG8_WAIT_V(8); PG8_WAIT_L(0); PG8_BAR; PG8_MMA(1, 0, At, B0); PG8_MMA(1, 1, At, B1); PG8_BAR; PG8_SCHED;
.LBB0_2312:
	s_add_u32 s22, s64, 0xfff80080
	s_addc_u32 s23, s65, -1
	s_add_i32 s55, 0, 0x10000
	s_cmp_eq_u32 s51, 28
	s_cselect_b32 s67, s6, s23
	s_cselect_b32 s66, s16, s22
	s_cselect_b32 s23, s17, s35
	s_cselect_b32 s22, s33, s34
	s_add_i32 s63, 0, 0x14000
	ds_read_b128 v[144:147], v249
	ds_read_b128 v[148:151], v249 offset:1024
	ds_read_b128 v[152:155], v249 offset:2048
	ds_read_b128 v[156:159], v249 offset:3072
	ds_read_b128 v[160:163], v249 offset:16384
	ds_read_b128 v[164:167], v249 offset:17408
	ds_read_b128 v[168:171], v249 offset:18432
	ds_read_b128 v[190:193], v249 offset:19456
	s_add_i32 m0, s37, 0xc000
	ds_read_b128 v[198:201], v143
	ds_read_b128 v[202:205], v143 offset:1024
	ds_read_b128 v[206:209], v143 offset:2048
	ds_read_b128 v[210:213], v143 offset:3072
	ds_read_b128 v[224:227], v143 offset:4096
	ds_read_b128 v[228:231], v143 offset:5120
	ds_read_b128 v[232:235], v143 offset:6144
	ds_read_b128 v[236:239], v143 offset:7168
	global_load_lds_dwordx4 v134, s[64:65]
	s_add_i32 m0, s37, 0xe000
	s_nop 0
	global_load_lds_dwordx4 v136, s[64:65]
	s_waitcnt vmcnt(8)
	s_waitcnt lgkmcnt(0)
	s_barrier
	s_waitcnt lgkmcnt(0)
	v_mfma_f32_16x16x32_bf16 v[124:127], v[144:147], v[198:201], v[124:127]
	v_mfma_f32_16x16x32_bf16 v[116:119], v[152:155], v[198:201], v[116:119]
	v_mfma_f32_16x16x32_bf16 v[108:111], v[144:147], v[206:209], v[108:111]
	v_mfma_f32_16x16x32_bf16 v[100:103], v[152:155], v[206:209], v[100:103]
	v_mfma_f32_16x16x32_bf16 v[92:95], v[144:147], v[224:227], v[92:95]
	v_mfma_f32_16x16x32_bf16 v[84:87], v[152:155], v[224:227], v[84:87]
	v_mfma_f32_16x16x32_bf16 v[76:79], v[144:147], v[232:235], v[76:79]
	v_mfma_f32_16x16x32_bf16 v[68:71], v[152:155], v[232:235], v[68:71]
	v_mfma_f32_16x16x32_bf16 v[124:127], v[148:151], v[202:205], v[124:127]
	v_mfma_f32_16x16x32_bf16 v[116:119], v[156:159], v[202:205], v[116:119]
	v_mfma_f32_16x16x32_bf16 v[108:111], v[148:151], v[210:213], v[108:111]
	v_mfma_f32_16x16x32_bf16 v[100:103], v[156:159], v[210:213], v[100:103]
	v_mfma_f32_16x16x32_bf16 v[92:95], v[148:151], v[228:231], v[92:95]
	v_mfma_f32_16x16x32_bf16 v[84:87], v[156:159], v[228:231], v[84:87]
	v_mfma_f32_16x16x32_bf16 v[76:79], v[148:151], v[236:239], v[76:79]
	v_mfma_f32_16x16x32_bf16 v[68:71], v[156:159], v[236:239], v[68:71]
	v_mfma_f32_16x16x32_bf16 v[120:123], v[160:163], v[198:201], v[120:123]
	v_mfma_f32_16x16x32_bf16 v[112:115], v[168:171], v[198:201], v[112:115]
	v_mfma_f32_16x16x32_bf16 v[104:107], v[160:163], v[206:209], v[104:107]
	v_mfma_f32_16x16x32_bf16 v[96:99], v[168:171], v[206:209], v[96:99]
	v_mfma_f32_16x16x32_bf16 v[88:91], v[160:163], v[224:227], v[88:91]
	v_mfma_f32_16x16x32_bf16 v[80:83], v[168:171], v[224:227], v[80:83]
	v_mfma_f32_16x16x32_bf16 v[72:75], v[160:163], v[232:235], v[72:75]
	v_mfma_f32_16x16x32_bf16 v[64:67], v[168:171], v[232:235], v[64:67]
	v_mfma_f32_16x16x32_bf16 v[120:123], v[164:167], v[202:205], v[120:123]
	v_mfma_f32_16x16x32_bf16 v[112:115], v[190:193], v[202:205], v[112:115]
	v_mfma_f32_16x16x32_bf16 v[104:107], v[164:167], v[210:213], v[104:107]
	v_mfma_f32_16x16x32_bf16 v[96:99], v[190:193], v[210:213], v[96:99]
	v_mfma_f32_16x16x32_bf16 v[88:91], v[164:167], v[228:231], v[88:91]
	v_mfma_f32_16x16x32_bf16 v[80:83], v[190:193], v[228:231], v[80:83]
	v_mfma_f32_16x16x32_bf16 v[72:75], v[164:167], v[236:239], v[72:75]
	v_mfma_f32_16x16x32_bf16 v[64:67], v[190:193], v[236:239], v[64:67]
	s_barrier
	s_add_i32 s55, s55, s69
	s_mov_b32 m0, s55
	ds_read_b128 v[198:201], v143 offset:16384
	ds_read_b128 v[202:205], v143 offset:17408
	ds_read_b128 v[206:209], v143 offset:18432
	ds_read_b128 v[210:213], v143 offset:19456
	ds_read_b128 v[224:227], v143 offset:20480
	ds_read_b128 v[228:231], v143 offset:21504
	ds_read_b128 v[232:235], v143 offset:22528
	ds_read_b128 v[236:239], v143 offset:23552
	global_load_lds_dwordx4 v172, s[22:23]
	s_add_i32 m0, s55, 0x2000
	s_add_u32 vcc_lo, s22, 0x80000
	s_addc_u32 vcc_hi, s23, 0
	s_add_i32 s55, s63, s69
	global_load_lds_dwordx4 v132, s[22:23]
	s_mov_b32 m0, s55
	s_nop 0
	global_load_lds_dwordx4 v172, vcc
	s_add_i32 m0, s55, 0x2000
	s_nop 0
	global_load_lds_dwordx4 v132, vcc
	s_mov_b32 m0, s37
	s_nop 0
	global_load_lds_dwordx4 v128, s[66:67]
	s_mov_b32 m0, s70
	s_nop 0
	global_load_lds_dwordx4 v130, s[66:67]
	s_waitcnt vmcnt(8)
	s_waitcnt lgkmcnt(0)
	s_barrier
	s_waitcnt lgkmcnt(0)
	v_mfma_f32_16x16x32_bf16 v[60:63], v[144:147], v[198:201], v[60:63]
	v_mfma_f32_16x16x32_bf16 v[52:55], v[152:155], v[198:201], v[52:55]
	v_mfma_f32_16x16x32_bf16 v[44:47], v[144:147], v[206:209], v[44:47]
	v_mfma_f32_16x16x32_bf16 v[36:39], v[152:155], v[206:209], v[36:39]
	v_mfma_f32_16x16x32_bf16 v[28:31], v[144:147], v[224:227], v[28:31]
	v_mfma_f32_16x16x32_bf16 v[20:23], v[152:155], v[224:227], v[20:23]
	v_mfma_f32_16x16x32_bf16 v[12:15], v[144:147], v[232:235], v[12:15]
	v_mfma_f32_16x16x32_bf16 v[4:7], v[152:155], v[232:235], v[4:7]
	v_mfma_f32_16x16x32_bf16 v[60:63], v[148:151], v[202:205], v[60:63]
	v_mfma_f32_16x16x32_bf16 v[52:55], v[156:159], v[202:205], v[52:55]
	v_mfma_f32_16x16x32_bf16 v[44:47], v[148:151], v[210:213], v[44:47]
	v_mfma_f32_16x16x32_bf16 v[36:39], v[156:159], v[210:213], v[36:39]
	v_mfma_f32_16x16x32_bf16 v[28:31], v[148:151], v[228:231], v[28:31]
	v_mfma_f32_16x16x32_bf16 v[20:23], v[156:159], v[228:231], v[20:23]
	v_mfma_f32_16x16x32_bf16 v[12:15], v[148:151], v[236:239], v[12:15]
	v_mfma_f32_16x16x32_bf16 v[4:7], v[156:159], v[236:239], v[4:7]
	v_mfma_f32_16x16x32_bf16 v[56:59], v[160:163], v[198:201], v[56:59]
	v_mfma_f32_16x16x32_bf16 v[48:51], v[168:171], v[198:201], v[48:51]
	v_mfma_f32_16x16x32_bf16 v[40:43], v[160:163], v[206:209], v[40:43]
	v_mfma_f32_16x16x32_bf16 v[32:35], v[168:171], v[206:209], v[32:35]
	v_mfma_f32_16x16x32_bf16 v[24:27], v[160:163], v[224:227], v[24:27]
	v_mfma_f32_16x16x32_bf16 v[16:19], v[168:171], v[224:227], v[16:19]
	v_mfma_f32_16x16x32_bf16 v[8:11], v[160:163], v[232:235], v[8:11]
	v_mfma_f32_16x16x32_bf16 v[0:3], v[168:171], v[232:235], v[0:3]
	v_mfma_f32_16x16x32_bf16 v[56:59], v[164:167], v[202:205], v[56:59]
	v_mfma_f32_16x16x32_bf16 v[48:51], v[190:193], v[202:205], v[48:51]
	v_mfma_f32_16x16x32_bf16 v[40:43], v[164:167], v[210:213], v[40:43]
	v_mfma_f32_16x16x32_bf16 v[32:35], v[190:193], v[210:213], v[32:35]
	v_mfma_f32_16x16x32_bf16 v[24:27], v[164:167], v[228:231], v[24:27]
	v_mfma_f32_16x16x32_bf16 v[16:19], v[190:193], v[228:231], v[16:19]
	v_mfma_f32_16x16x32_bf16 v[8:11], v[164:167], v[236:239], v[8:11]
	v_mfma_f32_16x16x32_bf16 v[0:3], v[190:193], v[236:239], v[0:3]
	s_barrier
; #define PG8_STAGE(bufoff, gbase, voff) do { _Pragma("unroll") for (int _i = 0; _i < 2; ++_i) \
;         __builtin_amdgcn_global_load_lds((const unsigned*)((const char*)(gbase) + (voff)[_i]), (PG8_LAS unsigned*)(lds + (bufoff) + ldsw + _i * 8192), 16, 0, 0); } while (0)
; #define PG8_LDA(dst, b, h) do { _Pragma("unroll") for (int m = 0; m < 4; ++m) _Pragma("unroll") for (int k = 0; k < 2; ++k) dst[m][k] = *(const PG8_LAS bf16x8*)(lds + PG8_SA(b, h) + aoff + m * 2048 + k * 1024); } while (0)
; #define PG8_LDB(dst, b, h) do { _Pragma("unroll") for (int n = 0; n < 2; ++n) _Pragma("unroll") for (int k = 0; k < 2; ++k) dst[n][k] = *(const PG8_LAS bf16x8*)(lds + PG8_SB(b, h) + boff + n * 2048 + k * 1024); } while (0)
; #define PG8_MMA(ai, bj, At, Bt) do { __builtin_amdgcn_s_setprio(1); _Pragma("unroll") for (int m = 0; m < 4; ++m) _Pragma("unroll") for (int n = 0; n < 2; ++n) _Pragma("unroll") for (int k = 0; k < 2; ++k) \
;         acc[ai][bj][m][n] = __builtin_amdgcn_mfma_f32_16x16x32_bf16(Bt[n][k], At[m][k], acc[ai][bj][m][n], 0, 0, 0); __builtin_amdgcn_s_setprio(0); } while (0)
; #define PG8_WAIT_V(n) asm volatile("s_waitcnt vmcnt(" #n ")" ::: "memory")
; #define PG8_WAIT_L(n) asm volatile("s_waitcnt lgkmcnt(" #n ")" ::: "memory")
; #define PG8_BAR __builtin_amdgcn_s_barrier()
; #define PG8_SCHED __builtin_amdgcn_sched_barrier(0)
; template <class Epi, class Sched, bool ALIGN_EPI = false, bool SP2 = false>
; __device__ __forceinline__ void gemm_phase(PG8_LAS unsigned char* lds, const Gemm g, const Sched& S, const Epi& E, const int tid_in) {
;     ...
;             PG8_LDB(B0, 1, 0); PG8_LDB(B1, 1, 1); PG8_SCHED; PG8_LDA(At, 1, 0); PG8_STAGE(PG8_SA(0, 1), a2 + hstepA, voffA);
;             PG8_WAIT_V(8); PG8_WAIT_L(0); PG8_BAR; PG8_MMA(0, 0, At, B0); PG8_MMA(0, 1, At, B1); PG8_BAR; PG8_SCHED;
;             PG8_LDA(At, 1, 1); PG8_STAGE(PG8_SB(1, 0), b3, voffB); PG8_STAGE(PG8_SB(1, 1), b3 + hstepB, voffB); PG8_STAGE(PG8_SA(1, 0), a3, voffA);
;             PG8_WAIT_V(8); PG8_WAIT_L(0); PG8_BAR; PG8_MMA(1, 0, At, B0); PG8_MMA(1, 1, At, B1); PG8_BAR; PG8_SCHED;
	s_add_i32 s55, 0, 0x18000
	s_add_i32 s63, 0, 0x1c000
	ds_read_b128 v[144:147], v249 offset:32768
	ds_read_b128 v[148:151], v249 offset:33792
	ds_read_b128 v[152:155], v249 offset:34816
	ds_read_b128 v[156:159], v249 offset:35840
	ds_read_b128 v[160:163], v249 offset:49152
	ds_read_b128 v[164:167], v249 offset:50176
	ds_read_b128 v[168:171], v249 offset:51200
	ds_read_b128 v[190:193], v249 offset:52224
	s_add_u32 s66, s66, 0x80000
	s_addc_u32 s67, s67, 0
	s_mov_b32 m0, s71
	ds_read_b128 v[198:201], v143 offset:32768
	ds_read_b128 v[202:205], v143 offset:33792
	ds_read_b128 v[206:209], v143 offset:34816
	ds_read_b128 v[210:213], v143 offset:35840
	ds_read_b128 v[224:227], v143 offset:36864
	ds_read_b128 v[228:231], v143 offset:37888
	ds_read_b128 v[232:235], v143 offset:38912
	ds_read_b128 v[236:239], v143 offset:39936
	global_load_lds_dwordx4 v128, s[66:67]
	s_mov_b32 m0, s72
	s_nop 0
	global_load_lds_dwordx4 v130, s[66:67]
	s_waitcnt vmcnt(8)
	s_waitcnt lgkmcnt(0)
	s_barrier
	s_waitcnt lgkmcnt(0)
	v_mfma_f32_16x16x32_bf16 v[124:127], v[144:147], v[198:201], v[124:127]
	v_mfma_f32_16x16x32_bf16 v[116:119], v[152:155], v[198:201], v[116:119]
	v_mfma_f32_16x16x32_bf16 v[108:111], v[144:147], v[206:209], v[108:111]
	v_mfma_f32_16x16x32_bf16 v[100:103], v[152:155], v[206:209], v[100:103]
	v_mfma_f32_16x16x32_bf16 v[92:95], v[144:147], v[224:227], v[92:95]
	v_mfma_f32_16x16x32_bf16 v[84:87], v[152:155], v[224:227], v[84:87]
	v_mfma_f32_16x16x32_bf16 v[76:79], v[144:147], v[232:235], v[76:79]
	v_mfma_f32_16x16x32_bf16 v[68:71], v[152:155], v[232:235], v[68:71]
	v_mfma_f32_16x16x32_bf16 v[124:127], v[148:151], v[202:205], v[124:127]
	v_mfma_f32_16x16x32_bf16 v[116:119], v[156:159], v[202:205], v[116:119]
	v_mfma_f32_16x16x32_bf16 v[108:111], v[148:151], v[210:213], v[108:111]
	v_mfma_f32_16x16x32_bf16 v[100:103], v[156:159], v[210:213], v[100:103]
	v_mfma_f32_16x16x32_bf16 v[92:95], v[148:151], v[228:231], v[92:95]
	v_mfma_f32_16x16x32_bf16 v[84:87], v[156:159], v[228:231], v[84:87]
	v_mfma_f32_16x16x32_bf16 v[76:79], v[148:151], v[236:239], v[76:79]
	v_mfma_f32_16x16x32_bf16 v[68:71], v[156:159], v[236:239], v[68:71]
	v_mfma_f32_16x16x32_bf16 v[120:123], v[160:163], v[198:201], v[120:123]
	v_mfma_f32_16x16x32_bf16 v[112:115], v[168:171], v[198:201], v[112:115]
	v_mfma_f32_16x16x32_bf16 v[104:107], v[160:163], v[206:209], v[104:107]
	v_mfma_f32_16x16x32_bf16 v[96:99], v[168:171], v[206:209], v[96:99]
	v_mfma_f32_16x16x32_bf16 v[88:91], v[160:163], v[224:227], v[88:91]
	v_mfma_f32_16x16x32_bf16 v[80:83], v[168:171], v[224:227], v[80:83]
	v_mfma_f32_16x16x32_bf16 v[72:75], v[160:163], v[232:235], v[72:75]
	v_mfma_f32_16x16x32_bf16 v[64:67], v[168:171], v[232:235], v[64:67]
	v_mfma_f32_16x16x32_bf16 v[120:123], v[164:167], v[202:205], v[120:123]
	v_mfma_f32_16x16x32_bf16 v[112:115], v[190:193], v[202:205], v[112:115]
	v_mfma_f32_16x16x32_bf16 v[104:107], v[164:167], v[210:213], v[104:107]
	v_mfma_f32_16x16x32_bf16 v[96:99], v[190:193], v[210:213], v[96:99]
	v_mfma_f32_16x16x32_bf16 v[88:91], v[164:167], v[228:231], v[88:91]
	v_mfma_f32_16x16x32_bf16 v[80:83], v[190:193], v[228:231], v[80:83]
	v_mfma_f32_16x16x32_bf16 v[72:75], v[164:167], v[236:239], v[72:75]
	v_mfma_f32_16x16x32_bf16 v[64:67], v[190:193], v[236:239], v[64:67]
	s_barrier
	s_add_i32 s55, s55, s69
	s_mov_b32 m0, s55
	ds_read_b128 v[198:201], v143 offset:49152
	ds_read_b128 v[202:205], v143 offset:50176
	ds_read_b128 v[206:209], v143 offset:51200
	ds_read_b128 v[210:213], v143 offset:52224
	ds_read_b128 v[224:227], v143 offset:53248
	ds_read_b128 v[228:231], v143 offset:54272
	ds_read_b128 v[232:235], v143 offset:55296
	ds_read_b128 v[236:239], v143 offset:56320
	s_add_u32 s100, s22, 0x80
	s_addc_u32 s101, s23, 0
	global_load_lds_dwordx4 v172, s[100:101]
	s_add_i32 m0, s55, 0x2000
	s_add_u32 s22, s22, 0x80080
	s_addc_u32 s23, s23, 0
	s_add_i32 s55, s63, s69
	global_load_lds_dwordx4 v132, s[100:101]
	s_mov_b32 m0, s55
	s_nop 0
	global_load_lds_dwordx4 v172, s[22:23]
	s_add_i32 m0, s55, 0x2000
	s_nop 0
	global_load_lds_dwordx4 v132, s[22:23]
	s_mov_b32 m0, s73
	s_nop 0
	s_add_u32 s100, s66, 0xfff80080
	s_addc_u32 s101, s67, -1
	global_load_lds_dwordx4 v128, s[100:101]
	s_mov_b32 m0, s74
	s_nop 0
	global_load_lds_dwordx4 v130, s[100:101]
	s_waitcnt vmcnt(8)
	s_waitcnt lgkmcnt(0)
	s_barrier
	s_waitcnt lgkmcnt(0)
	v_mfma_f32_16x16x32_bf16 v[60:63], v[144:147], v[198:201], v[60:63]
	v_mfma_f32_16x16x32_bf16 v[52:55], v[152:155], v[198:201], v[52:55]
	v_mfma_f32_16x16x32_bf16 v[44:47], v[144:147], v[206:209], v[44:47]
	v_mfma_f32_16x16x32_bf16 v[36:39], v[152:155], v[206:209], v[36:39]
	v_mfma_f32_16x16x32_bf16 v[28:31], v[144:147], v[224:227], v[28:31]
	v_mfma_f32_16x16x32_bf16 v[20:23], v[152:155], v[224:227], v[20:23]
	v_mfma_f32_16x16x32_bf16 v[12:15], v[144:147], v[232:235], v[12:15]
	v_mfma_f32_16x16x32_bf16 v[4:7], v[152:155], v[232:235], v[4:7]
	v_mfma_f32_16x16x32_bf16 v[60:63], v[148:151], v[202:205], v[60:63]
	v_mfma_f32_16x16x32_bf16 v[52:55], v[156:159], v[202:205], v[52:55]
	v_mfma_f32_16x16x32_bf16 v[44:47], v[148:151], v[210:213], v[44:47]
	v_mfma_f32_16x16x32_bf16 v[36:39], v[156:159], v[210:213], v[36:39]
	v_mfma_f32_16x16x32_bf16 v[28:31], v[148:151], v[228:231], v[28:31]
	v_mfma_f32_16x16x32_bf16 v[20:23], v[156:159], v[228:231], v[20:23]
	v_mfma_f32_16x16x32_bf16 v[12:15], v[148:151], v[236:239], v[12:15]
	v_mfma_f32_16x16x32_bf16 v[4:7], v[156:159], v[236:239], v[4:7]
	v_mfma_f32_16x16x32_bf16 v[56:59], v[160:163], v[198:201], v[56:59]
	v_mfma_f32_16x16x32_bf16 v[48:51], v[168:171], v[198:201], v[48:51]
	v_mfma_f32_16x16x32_bf16 v[40:43], v[160:163], v[206:209], v[40:43]
	v_mfma_f32_16x16x32_bf16 v[32:35], v[168:171], v[206:209], v[32:35]
	v_mfma_f32_16x16x32_bf16 v[24:27], v[160:163], v[224:227], v[24:27]
	v_mfma_f32_16x16x32_bf16 v[16:19], v[168:171], v[224:227], v[16:19]
	v_mfma_f32_16x16x32_bf16 v[8:11], v[160:163], v[232:235], v[8:11]
	v_mfma_f32_16x16x32_bf16 v[0:3], v[168:171], v[232:235], v[0:3]
	v_mfma_f32_16x16x32_bf16 v[56:59], v[164:167], v[202:205], v[56:59]
	v_mfma_f32_16x16x32_bf16 v[48:51], v[190:193], v[202:205], v[48:51]
	v_mfma_f32_16x16x32_bf16 v[40:43], v[164:167], v[210:213], v[40:43]
	v_mfma_f32_16x16x32_bf16 v[32:35], v[190:193], v[210:213], v[32:35]
	v_mfma_f32_16x16x32_bf16 v[24:27], v[164:167], v[228:231], v[24:27]
	v_mfma_f32_16x16x32_bf16 v[16:19], v[190:193], v[228:231], v[16:19]
	v_mfma_f32_16x16x32_bf16 v[8:11], v[164:167], v[236:239], v[8:11]
	v_mfma_f32_16x16x32_bf16 v[0:3], v[190:193], v[236:239], v[0:3]
	s_barrier
	s_add_i32 s51, s51, 2
	s_add_u32 s64, s64, 0x100
	s_addc_u32 s65, s65, 0
	s_add_u32 s34, s34, 0x100
	s_addc_u32 s35, s35, 0
	s_cmp_gt_u32 s51, 29
	s_cbranch_scc0 .LBB0_2312
	s_and_b64 vcc, exec, s[48:49]
	s_cbranch_vccz .LBB0_2315
	s_barrier

;     __device__ __forceinline__ void a_ready(const Unit& u) const { wait_panel(cnt, u.pm, need, tmo, wave); }
;     __device__ __forceinline__ void a_ready(const Unit& u) const { wait_panel(cnt, u.pm, need, tmo, wave); }
; #define PG8_STAGE(bufoff, gbase, voff) do { _Pragma("unroll") for (int _i = 0; _i < 2; ++_i) \
;         __builtin_amdgcn_global_load_lds((const unsigned*)((const char*)(gbase) + (voff)[_i]), (PG8_LAS unsigned*)(lds + (bufoff) + ldsw + _i * 8192), 16, 0, 0); } while (0)
; #define PG8_LDA(dst, b, h) do { _Pragma("unroll") for (int m = 0; m < 4; ++m) _Pragma("unroll") for (int k = 0; k < 2; ++k) dst[m][k] = *(const PG8_LAS bf16x8*)(lds + PG8_SA(b, h) + aoff + m * 2048 + k * 1024); } while (0)
; #define PG8_LDB(dst, b, h) do { _Pragma("unroll") for (int n = 0; n < 2; ++n) _Pragma("unroll") for (int k = 0; k < 2; ++k) dst[n][k] = *(const PG8_LAS bf16x8*)(lds + PG8_SB(b, h) + boff + n * 2048 + k * 1024); } while (0)
; #define PG8_MMA(ai, bj, At, Bt) do { __builtin_amdgcn_s_setprio(1); _Pragma("unroll") for (int m = 0; m < 4; ++m) _Pragma("unroll") for (int n = 0; n < 2; ++n) _Pragma("unroll") for (int k = 0; k < 2; ++k) \
;         acc[ai][bj][m][n] = __builtin_amdgcn_mfma_f32_16x16x32_bf16(Bt[n][k], At[m][k], acc[ai][bj][m][n], 0, 0, 0); __builtin_amdgcn_s_setprio(0); } while (0)
; template <class Epi, class Sched, bool ALIGN_EPI = false, bool SP2 = false>
; __device__ __forceinline__ void gemm_phase(PG8_LAS unsigned char* lds, const Gemm g, const Sched& S, const Epi& E, const int tid_in) {
;     ...
;             const char* a1 = cA + (size_t)(t + 1) * kstep;
;             const char* a2 = last ? nA : cA + (size_t)(t + 2) * kstep; const char* b2 = last ? nB : cB + (size_t)(t + 2) * kstep;
;             const char* a3 = a2 + kstep; const char* b3 = b2 + kstep;
;             if (last && has_next) S.a_ready(nxt);
;             if constexpr (SP2) {
;             PG8_LDB(B0, 0, 0); PG8_LDB(B1, 0, 1); PG8_SCHED; PG8_LDA(At, 0, 0); PG8_STAGE(PG8_SA(1, 1), a1 + hstepA, voffA);
;             PG8_WAIT_V(8); PG8_WAIT_L(0); PG8_BAR; PG8_MMA(0, 0, At, B0); PG8_MMA(0, 1, At, B1); PG8_BAR; PG8_SCHED;
;             PG8_LDA(At, 0, 1); PG8_STAGE(PG8_SB(0, 0), b2, voffB); PG8_STAGE(PG8_SB(0, 1), b2 + hstepB, voffB); PG8_STAGE(PG8_SA(0, 0), a2, voffA);
;             PG8_WAIT_V(8); PG8_WAIT_L(0); PG8_BAR; PG8_MMA(1, 0, At, B0); PG8_MMA(1, 1, At, B1); PG8_BAR; PG8_SCHED;
.LBB0_2372:
	s_lshl_b32 s72, s85, 7
	s_add_u32 s73, s62, s72
	s_addc_u32 s74, s63, 0
	s_add_u32 s75, s73, 0x100
	s_addc_u32 s76, s74, 0
	s_and_b64 s[70:71], s[22:23], exec
	s_cselect_b32 s71, s59, s76
	s_cselect_b32 s70, s58, s75
	s_add_u32 s72, s64, s72
	s_addc_u32 s75, s65, 0
	s_add_u32 s72, s72, 0x100
	s_addc_u32 s75, s75, 0
	s_and_b64 s[22:23], s[22:23], exec
	s_cselect_b32 s23, s61, s75
	s_cselect_b32 s22, s60, s72
	s_add_i32 s75, 0, 0x10000
	s_add_i32 s76, 0, 0x14000
	ds_read_b128 v[128:131], v249
	ds_read_b128 v[132:135], v249 offset:1024
	ds_read_b128 v[136:139], v249 offset:2048
	ds_read_b128 v[140:143], v249 offset:3072
	ds_read_b128 v[144:147], v249 offset:16384
	ds_read_b128 v[154:157], v249 offset:17408
	ds_read_b128 v[158:161], v249 offset:18432
	ds_read_b128 v[162:165], v249 offset:19456
	s_add_u32 s72, s73, 0x150080
	s_addc_u32 s73, s74, 0
	s_add_i32 m0, s21, 0xc000
	ds_read_b128 v[166:169], v200
	ds_read_b128 v[190:193], v200 offset:1024
	ds_read_b128 v[202:205], v200 offset:2048
	ds_read_b128 v[206:209], v200 offset:3072
	ds_read_b128 v[210:213], v200 offset:4096
	ds_read_b128 v[224:227], v200 offset:5120
	ds_read_b128 v[228:231], v200 offset:6144
	ds_read_b128 v[232:235], v200 offset:7168
	global_load_lds_dwordx4 v148, s[72:73]
	s_add_i32 m0, s21, 0xe000
	s_nop 0
	global_load_lds_dwordx4 v150, s[72:73]
	s_waitcnt vmcnt(8)
	s_waitcnt lgkmcnt(0)
	s_barrier
	s_waitcnt lgkmcnt(0)
	v_mfma_f32_16x16x32_bf16 v[124:127], v[128:131], v[166:169], v[124:127]
	v_mfma_f32_16x16x32_bf16 v[120:123], v[136:139], v[166:169], v[120:123]
	v_mfma_f32_16x16x32_bf16 v[108:111], v[128:131], v[202:205], v[108:111]
	v_mfma_f32_16x16x32_bf16 v[104:107], v[136:139], v[202:205], v[104:107]
	v_mfma_f32_16x16x32_bf16 v[92:95], v[128:131], v[210:213], v[92:95]
	v_mfma_f32_16x16x32_bf16 v[88:91], v[136:139], v[210:213], v[88:91]
	v_mfma_f32_16x16x32_bf16 v[76:79], v[128:131], v[228:231], v[76:79]
	v_mfma_f32_16x16x32_bf16 v[72:75], v[136:139], v[228:231], v[72:75]
	v_mfma_f32_16x16x32_bf16 v[124:127], v[132:135], v[190:193], v[124:127]
	v_mfma_f32_16x16x32_bf16 v[120:123], v[140:143], v[190:193], v[120:123]
	v_mfma_f32_16x16x32_bf16 v[108:111], v[132:135], v[206:209], v[108:111]
	v_mfma_f32_16x16x32_bf16 v[104:107], v[140:143], v[206:209], v[104:107]
	v_mfma_f32_16x16x32_bf16 v[92:95], v[132:135], v[224:227], v[92:95]
	v_mfma_f32_16x16x32_bf16 v[88:91], v[140:143], v[224:227], v[88:91]
	v_mfma_f32_16x16x32_bf16 v[76:79], v[132:135], v[232:235], v[76:79]
	v_mfma_f32_16x16x32_bf16 v[72:75], v[140:143], v[232:235], v[72:75]
	v_mfma_f32_16x16x32_bf16 v[116:119], v[144:147], v[166:169], v[116:119]
	v_mfma_f32_16x16x32_bf16 v[112:115], v[158:161], v[166:169], v[112:115]
	v_mfma_f32_16x16x32_bf16 v[100:103], v[144:147], v[202:205], v[100:103]
	v_mfma_f32_16x16x32_bf16 v[96:99], v[158:161], v[202:205], v[96:99]
	v_mfma_f32_16x16x32_bf16 v[84:87], v[144:147], v[210:213], v[84:87]
	v_mfma_f32_16x16x32_bf16 v[80:83], v[158:161], v[210:213], v[80:83]
	v_mfma_f32_16x16x32_bf16 v[68:71], v[144:147], v[228:231], v[68:71]
	v_mfma_f32_16x16x32_bf16 v[64:67], v[158:161], v[228:231], v[64:67]
	v_mfma_f32_16x16x32_bf16 v[116:119], v[154:157], v[190:193], v[116:119]
	v_mfma_f32_16x16x32_bf16 v[112:115], v[162:165], v[190:193], v[112:115]
	v_mfma_f32_16x16x32_bf16 v[100:103], v[154:157], v[206:209], v[100:103]
	v_mfma_f32_16x16x32_bf16 v[96:99], v[162:165], v[206:209], v[96:99]
	v_mfma_f32_16x16x32_bf16 v[84:87], v[154:157], v[224:227], v[84:87]
	v_mfma_f32_16x16x32_bf16 v[80:83], v[162:165], v[224:227], v[80:83]
	v_mfma_f32_16x16x32_bf16 v[68:71], v[154:157], v[232:235], v[68:71]
	v_mfma_f32_16x16x32_bf16 v[64:67], v[162:165], v[232:235], v[64:67]
	s_barrier
	s_add_i32 s72, s75, s20
	s_mov_b32 m0, s72
	ds_read_b128 v[166:169], v200 offset:16384
	ds_read_b128 v[190:193], v200 offset:17408
	ds_read_b128 v[202:205], v200 offset:18432
	ds_read_b128 v[206:209], v200 offset:19456
	ds_read_b128 v[210:213], v200 offset:20480
	ds_read_b128 v[224:227], v200 offset:21504
	ds_read_b128 v[228:231], v200 offset:22528
	ds_read_b128 v[232:235], v200 offset:23552
	global_load_lds_dwordx4 v172, s[22:23]
	s_add_i32 m0, s72, 0x2000
	s_add_u32 s72, s22, 0x150000
	s_addc_u32 s73, s23, 0
	s_add_i32 s74, s76, s20
	global_load_lds_dwordx4 v152, s[22:23]
	s_mov_b32 m0, s74
	s_nop 0
	global_load_lds_dwordx4 v172, s[72:73]
	s_add_i32 m0, s74, 0x2000
	s_nop 0
	global_load_lds_dwordx4 v152, s[72:73]
	s_add_u32 vcc_lo, s70, 0x80
	s_addc_u32 vcc_hi, s71, 0
	s_mov_b32 m0, s21
	s_nop 0
	global_load_lds_dwordx4 v148, s[70:71]
	s_mov_b32 m0, s6
	s_nop 0
	global_load_lds_dwordx4 v150, s[70:71]
	s_waitcnt vmcnt(8)
	s_waitcnt lgkmcnt(0)
	s_barrier
; #define PG8_STAGE(bufoff, gbase, voff) do { _Pragma("unroll") for (int _i = 0; _i < 2; ++_i) \
;         __builtin_amdgcn_global_load_lds((const unsigned*)((const char*)(gbase) + (voff)[_i]), (PG8_LAS unsigned*)(lds + (bufoff) + ldsw + _i * 8192), 16, 0, 0); } while (0)
; #define PG8_LDA(dst, b, h) do { _Pragma("unroll") for (int m = 0; m < 4; ++m) _Pragma("unroll") for (int k = 0; k < 2; ++k) dst[m][k] = *(const PG8_LAS bf16x8*)(lds + PG8_SA(b, h) + aoff + m * 2048 + k * 1024); } while (0)
; #define PG8_LDB(dst, b, h) do { _Pragma("unroll") for (int n = 0; n < 2; ++n) _Pragma("unroll") for (int k = 0; k < 2; ++k) dst[n][k] = *(const PG8_LAS bf16x8*)(lds + PG8_SB(b, h) + boff + n * 2048 + k * 1024); } while (0)
; #define PG8_MMA(ai, bj, At, Bt) do { __builtin_amdgcn_s_setprio(1); _Pragma("unroll") for (int m = 0; m < 4; ++m) _Pragma("unroll") for (int n = 0; n < 2; ++n) _Pragma("unroll") for (int k = 0; k < 2; ++k) \
;         acc[ai][bj][m][n] = __builtin_amdgcn_mfma_f32_16x16x32_bf16(Bt[n][k], At[m][k], acc[ai][bj][m][n], 0, 0, 0); __builtin_amdgcn_s_setprio(0); } while (0)
; #define PG8_WAIT_V(n) asm volatile("s_waitcnt vmcnt(" #n ")" ::: "memory")
; #define PG8_WAIT_L(n) asm volatile("s_waitcnt lgkmcnt(" #n ")" ::: "memory")
; #define PG8_BAR __builtin_amdgcn_s_barrier()
; #define PG8_SCHED __builtin_amdgcn_sched_barrier(0)
; template <class Epi, class Sched, bool ALIGN_EPI = false, bool SP2 = false>
; __device__ __forceinline__ void gemm_phase(PG8_LAS unsigned char* lds, const Gemm g, const Sched& S, const Epi& E, const int tid_in) {
;     ...
;             PG8_WAIT_V(8); PG8_WAIT_L(0); PG8_BAR; PG8_MMA(1, 0, At, B0); PG8_MMA(1, 1, At, B1); PG8_BAR; PG8_SCHED;
;             PG8_LDB(B0, 1, 0); PG8_LDB(B1, 1, 1); PG8_SCHED; PG8_LDA(At, 1, 0); PG8_STAGE(PG8_SA(0, 1), a2 + hstepA, voffA);
;             PG8_WAIT_V(8); PG8_WAIT_L(0); PG8_BAR; PG8_MMA(0, 0, At, B0); PG8_MMA(0, 1, At, B1); PG8_BAR; PG8_SCHED;
;             PG8_LDA(At, 1, 1); PG8_STAGE(PG8_SB(1, 0), b3, voffB); PG8_STAGE(PG8_SB(1, 1), b3 + hstepB, voffB); PG8_STAGE(PG8_SA(1, 0), a3, voffA);
;             PG8_WAIT_V(8); PG8_WAIT_L(0); PG8_BAR; PG8_MMA(1, 0, At, B0); PG8_MMA(1, 1, At, B1); PG8_BAR; PG8_SCHED;
	s_waitcnt lgkmcnt(0)
	v_mfma_f32_16x16x32_bf16 v[60:63], v[128:131], v[166:169], v[60:63]
	v_mfma_f32_16x16x32_bf16 v[56:59], v[136:139], v[166:169], v[56:59]
	v_mfma_f32_16x16x32_bf16 v[44:47], v[128:131], v[202:205], v[44:47]
	v_mfma_f32_16x16x32_bf16 v[40:43], v[136:139], v[202:205], v[40:43]
	v_mfma_f32_16x16x32_bf16 v[28:31], v[128:131], v[210:213], v[28:31]
	v_mfma_f32_16x16x32_bf16 v[24:27], v[136:139], v[210:213], v[24:27]
	v_mfma_f32_16x16x32_bf16 v[12:15], v[128:131], v[228:231], v[12:15]
	v_mfma_f32_16x16x32_bf16 v[8:11], v[136:139], v[228:231], v[8:11]
	v_mfma_f32_16x16x32_bf16 v[60:63], v[132:135], v[190:193], v[60:63]
	v_mfma_f32_16x16x32_bf16 v[56:59], v[140:143], v[190:193], v[56:59]
	v_mfma_f32_16x16x32_bf16 v[44:47], v[132:135], v[206:209], v[44:47]
	v_mfma_f32_16x16x32_bf16 v[40:43], v[140:143], v[206:209], v[40:43]
	v_mfma_f32_16x16x32_bf16 v[28:31], v[132:135], v[224:227], v[28:31]
	v_mfma_f32_16x16x32_bf16 v[24:27], v[140:143], v[224:227], v[24:27]
	v_mfma_f32_16x16x32_bf16 v[12:15], v[132:135], v[232:235], v[12:15]
	v_mfma_f32_16x16x32_bf16 v[8:11], v[140:143], v[232:235], v[8:11]
	v_mfma_f32_16x16x32_bf16 v[52:55], v[144:147], v[166:169], v[52:55]
	v_mfma_f32_16x16x32_bf16 v[48:51], v[158:161], v[166:169], v[48:51]
	v_mfma_f32_16x16x32_bf16 v[36:39], v[144:147], v[202:205], v[36:39]
	v_mfma_f32_16x16x32_bf16 v[32:35], v[158:161], v[202:205], v[32:35]
	v_mfma_f32_16x16x32_bf16 v[20:23], v[144:147], v[210:213], v[20:23]
	v_mfma_f32_16x16x32_bf16 v[16:19], v[158:161], v[210:213], v[16:19]
	v_mfma_f32_16x16x32_bf16 v[4:7], v[144:147], v[228:231], v[4:7]
	v_mfma_f32_16x16x32_bf16 v[0:3], v[158:161], v[228:231], v[0:3]
	v_mfma_f32_16x16x32_bf16 v[52:55], v[154:157], v[190:193], v[52:55]
	v_mfma_f32_16x16x32_bf16 v[48:51], v[162:165], v[190:193], v[48:51]
	v_mfma_f32_16x16x32_bf16 v[36:39], v[154:157], v[206:209], v[36:39]
	v_mfma_f32_16x16x32_bf16 v[32:35], v[162:165], v[206:209], v[32:35]
	v_mfma_f32_16x16x32_bf16 v[20:23], v[154:157], v[224:227], v[20:23]
	v_mfma_f32_16x16x32_bf16 v[16:19], v[162:165], v[224:227], v[16:19]
	v_mfma_f32_16x16x32_bf16 v[4:7], v[154:157], v[232:235], v[4:7]
	v_mfma_f32_16x16x32_bf16 v[0:3], v[162:165], v[232:235], v[0:3]
	s_barrier
	s_add_i32 s72, 0, 0x18000
	s_add_i32 s73, 0, 0x1c000
	ds_read_b128 v[128:131], v249 offset:32768
	ds_read_b128 v[132:135], v249 offset:33792
	ds_read_b128 v[136:139], v249 offset:34816
	ds_read_b128 v[140:143], v249 offset:35840
	ds_read_b128 v[144:147], v249 offset:49152
	ds_read_b128 v[154:157], v249 offset:50176
	ds_read_b128 v[158:161], v249 offset:51200
	ds_read_b128 v[162:165], v249 offset:52224
	s_add_u32 s70, s70, 0x150000
	s_addc_u32 s71, s71, 0
	s_mov_b32 m0, s34
	ds_read_b128 v[166:169], v200 offset:32768
	ds_read_b128 v[190:193], v200 offset:33792
	ds_read_b128 v[202:205], v200 offset:34816
	ds_read_b128 v[206:209], v200 offset:35840
	ds_read_b128 v[210:213], v200 offset:36864
	ds_read_b128 v[224:227], v200 offset:37888
	ds_read_b128 v[228:231], v200 offset:38912
	ds_read_b128 v[232:235], v200 offset:39936
	global_load_lds_dwordx4 v148, s[70:71]
	s_mov_b32 m0, s35
	s_nop 0
	global_load_lds_dwordx4 v150, s[70:71]
	s_waitcnt vmcnt(8)
	s_waitcnt lgkmcnt(0)
	s_barrier
	s_waitcnt lgkmcnt(0)
	v_mfma_f32_16x16x32_bf16 v[124:127], v[128:131], v[166:169], v[124:127]
	v_mfma_f32_16x16x32_bf16 v[120:123], v[136:139], v[166:169], v[120:123]
	v_mfma_f32_16x16x32_bf16 v[108:111], v[128:131], v[202:205], v[108:111]
	v_mfma_f32_16x16x32_bf16 v[104:107], v[136:139], v[202:205], v[104:107]
	v_mfma_f32_16x16x32_bf16 v[92:95], v[128:131], v[210:213], v[92:95]
	v_mfma_f32_16x16x32_bf16 v[88:91], v[136:139], v[210:213], v[88:91]
	v_mfma_f32_16x16x32_bf16 v[76:79], v[128:131], v[228:231], v[76:79]
	v_mfma_f32_16x16x32_bf16 v[72:75], v[136:139], v[228:231], v[72:75]
	v_mfma_f32_16x16x32_bf16 v[124:127], v[132:135], v[190:193], v[124:127]
	v_mfma_f32_16x16x32_bf16 v[120:123], v[140:143], v[190:193], v[120:123]
	v_mfma_f32_16x16x32_bf16 v[108:111], v[132:135], v[206:209], v[108:111]
	v_mfma_f32_16x16x32_bf16 v[104:107], v[140:143], v[206:209], v[104:107]
	v_mfma_f32_16x16x32_bf16 v[92:95], v[132:135], v[224:227], v[92:95]
	v_mfma_f32_16x16x32_bf16 v[88:91], v[140:143], v[224:227], v[88:91]
	v_mfma_f32_16x16x32_bf16 v[76:79], v[132:135], v[232:235], v[76:79]
	v_mfma_f32_16x16x32_bf16 v[72:75], v[140:143], v[232:235], v[72:75]
	v_mfma_f32_16x16x32_bf16 v[116:119], v[144:147], v[166:169], v[116:119]
	v_mfma_f32_16x16x32_bf16 v[112:115], v[158:161], v[166:169], v[112:115]
	v_mfma_f32_16x16x32_bf16 v[100:103], v[144:147], v[202:205], v[100:103]
	v_mfma_f32_16x16x32_bf16 v[96:99], v[158:161], v[202:205], v[96:99]
	v_mfma_f32_16x16x32_bf16 v[84:87], v[144:147], v[210:213], v[84:87]
	v_mfma_f32_16x16x32_bf16 v[80:83], v[158:161], v[210:213], v[80:83]
	v_mfma_f32_16x16x32_bf16 v[68:71], v[144:147], v[228:231], v[68:71]
	v_mfma_f32_16x16x32_bf16 v[64:67], v[158:161], v[228:231], v[64:67]
	v_mfma_f32_16x16x32_bf16 v[116:119], v[154:157], v[190:193], v[116:119]
	v_mfma_f32_16x16x32_bf16 v[112:115], v[162:165], v[190:193], v[112:115]
	v_mfma_f32_16x16x32_bf16 v[100:103], v[154:157], v[206:209], v[100:103]
	v_mfma_f32_16x16x32_bf16 v[96:99], v[162:165], v[206:209], v[96:99]
	v_mfma_f32_16x16x32_bf16 v[84:87], v[154:157], v[224:227], v[84:87]
	v_mfma_f32_16x16x32_bf16 v[80:83], v[162:165], v[224:227], v[80:83]
	v_mfma_f32_16x16x32_bf16 v[68:71], v[154:157], v[232:235], v[68:71]
	v_mfma_f32_16x16x32_bf16 v[64:67], v[162:165], v[232:235], v[64:67]
	s_barrier
; #define PG8_STAGE(bufoff, gbase, voff) do { _Pragma("unroll") for (int _i = 0; _i < 2; ++_i) \
;         __builtin_amdgcn_global_load_lds((const unsigned*)((const char*)(gbase) + (voff)[_i]), (PG8_LAS unsigned*)(lds + (bufoff) + ldsw + _i * 8192), 16, 0, 0); } while (0)
; #define PG8_LDA(dst, b, h) do { _Pragma("unroll") for (int m = 0; m < 4; ++m) _Pragma("unroll") for (int k = 0; k < 2; ++k) dst[m][k] = *(const PG8_LAS bf16x8*)(lds + PG8_SA(b, h) + aoff + m * 2048 + k * 1024); } while (0)
; #define PG8_MMA(ai, bj, At, Bt) do { __builtin_amdgcn_s_setprio(1); _Pragma("unroll") for (int m = 0; m < 4; ++m) _Pragma("unroll") for (int n = 0; n < 2; ++n) _Pragma("unroll") for (int k = 0; k < 2; ++k) \
;         acc[ai][bj][m][n] = __builtin_amdgcn_mfma_f32_16x16x32_bf16(Bt[n][k], At[m][k], acc[ai][bj][m][n], 0, 0, 0); __builtin_amdgcn_s_setprio(0); } while (0)
; #define PG8_WAIT_V(n) asm volatile("s_waitcnt vmcnt(" #n ")" ::: "memory")
; #define PG8_WAIT_L(n) asm volatile("s_waitcnt lgkmcnt(" #n ")" ::: "memory")
; #define PG8_BAR __builtin_amdgcn_s_barrier()
; #define PG8_SCHED __builtin_amdgcn_sched_barrier(0)
; template <class Epi, class Sched, bool ALIGN_EPI = false, bool SP2 = false>
; __device__ __forceinline__ void gemm_phase(PG8_LAS unsigned char* lds, const Gemm g, const Sched& S, const Epi& E, const int tid_in) {
;     ...
;             PG8_LDA(At, 1, 1); PG8_STAGE(PG8_SB(1, 0), b3, voffB); PG8_STAGE(PG8_SB(1, 1), b3 + hstepB, voffB); PG8_STAGE(PG8_SA(1, 0), a3, voffA);
;             PG8_WAIT_V(8); PG8_WAIT_L(0); PG8_BAR; PG8_MMA(1, 0, At, B0); PG8_MMA(1, 1, At, B1); PG8_BAR; PG8_SCHED;
	s_add_i32 s70, s72, s20
	s_mov_b32 m0, s70
	ds_read_b128 v[166:169], v200 offset:49152
	ds_read_b128 v[190:193], v200 offset:50176
	ds_read_b128 v[202:205], v200 offset:51200
	ds_read_b128 v[206:209], v200 offset:52224
	ds_read_b128 v[210:213], v200 offset:53248
	ds_read_b128 v[224:227], v200 offset:54272
	ds_read_b128 v[228:231], v200 offset:55296
	ds_read_b128 v[232:235], v200 offset:56320
	s_add_u32 s100, s22, 0x80
	s_addc_u32 s101, s23, 0
	global_load_lds_dwordx4 v172, s[100:101]
	s_add_i32 m0, s70, 0x2000
	s_add_u32 s22, s22, 0x150080
	s_addc_u32 s23, s23, 0
	s_add_i32 s70, s73, s20
	global_load_lds_dwordx4 v152, s[100:101]
	s_mov_b32 m0, s70
	s_nop 0
	global_load_lds_dwordx4 v172, s[22:23]
	s_add_i32 m0, s70, 0x2000
	s_nop 0
	global_load_lds_dwordx4 v152, s[22:23]
	s_mov_b32 m0, s93
	s_nop 0
	global_load_lds_dwordx4 v148, vcc
	s_mov_b32 m0, s94
	s_nop 0
	global_load_lds_dwordx4 v150, vcc
	s_waitcnt vmcnt(8)
	s_waitcnt lgkmcnt(0)
	s_barrier
	s_waitcnt lgkmcnt(0)
	v_mfma_f32_16x16x32_bf16 v[60:63], v[128:131], v[166:169], v[60:63]
	v_mfma_f32_16x16x32_bf16 v[56:59], v[136:139], v[166:169], v[56:59]
	v_mfma_f32_16x16x32_bf16 v[44:47], v[128:131], v[202:205], v[44:47]
	v_mfma_f32_16x16x32_bf16 v[40:43], v[136:139], v[202:205], v[40:43]
	v_mfma_f32_16x16x32_bf16 v[28:31], v[128:131], v[210:213], v[28:31]
	v_mfma_f32_16x16x32_bf16 v[24:27], v[136:139], v[210:213], v[24:27]
	v_mfma_f32_16x16x32_bf16 v[12:15], v[128:131], v[228:231], v[12:15]
	v_mfma_f32_16x16x32_bf16 v[8:11], v[136:139], v[228:231], v[8:11]
	v_mfma_f32_16x16x32_bf16 v[60:63], v[132:135], v[190:193], v[60:63]
	v_mfma_f32_16x16x32_bf16 v[56:59], v[140:143], v[190:193], v[56:59]
	v_mfma_f32_16x16x32_bf16 v[44:47], v[132:135], v[206:209], v[44:47]
	v_mfma_f32_16x16x32_bf16 v[40:43], v[140:143], v[206:209], v[40:43]
	v_mfma_f32_16x16x32_bf16 v[28:31], v[132:135], v[224:227], v[28:31]
	v_mfma_f32_16x16x32_bf16 v[24:27], v[140:143], v[224:227], v[24:27]
	v_mfma_f32_16x16x32_bf16 v[12:15], v[132:135], v[232:235], v[12:15]
	v_mfma_f32_16x16x32_bf16 v[8:11], v[140:143], v[232:235], v[8:11]
	v_mfma_f32_16x16x32_bf16 v[52:55], v[144:147], v[166:169], v[52:55]
	v_mfma_f32_16x16x32_bf16 v[48:51], v[158:161], v[166:169], v[48:51]
	v_mfma_f32_16x16x32_bf16 v[36:39], v[144:147], v[202:205], v[36:39]
	v_mfma_f32_16x16x32_bf16 v[32:35], v[158:161], v[202:205], v[32:35]
	v_mfma_f32_16x16x32_bf16 v[20:23], v[144:147], v[210:213], v[20:23]
	v_mfma_f32_16x16x32_bf16 v[16:19], v[158:161], v[210:213], v[16:19]
	v_mfma_f32_16x16x32_bf16 v[4:7], v[144:147], v[228:231], v[4:7]
	v_mfma_f32_16x16x32_bf16 v[0:3], v[158:161], v[228:231], v[0:3]
	v_mfma_f32_16x16x32_bf16 v[52:55], v[154:157], v[190:193], v[52:55]
	v_mfma_f32_16x16x32_bf16 v[48:51], v[162:165], v[190:193], v[48:51]
	v_mfma_f32_16x16x32_bf16 v[36:39], v[154:157], v[206:209], v[36:39]
	v_mfma_f32_16x16x32_bf16 v[32:35], v[162:165], v[206:209], v[32:35]
	v_mfma_f32_16x16x32_bf16 v[20:23], v[154:157], v[224:227], v[20:23]
	v_mfma_f32_16x16x32_bf16 v[16:19], v[162:165], v[224:227], v[16:19]
	v_mfma_f32_16x16x32_bf16 v[4:7], v[154:157], v[232:235], v[4:7]
	v_mfma_f32_16x16x32_bf16 v[0:3], v[162:165], v[232:235], v[0:3]
	s_barrier
	s_add_i32 s22, s85, 2
	s_cmpk_gt_u32 s85, 0x51
	s_mov_b32 s85, s22
	s_cbranch_scc1 .LBB0_2387

;     __device__ __forceinline__ void a_ready(const Unit& u) const { wait_panel(cnt, u.pm, need, tmo, wave); }
;     __device__ __forceinline__ void a_ready(const Unit& u) const { wait_panel(cnt, u.pm, need, tmo, wave); }
; #define PG8_STAGE(bufoff, gbase, voff) do { _Pragma("unroll") for (int _i = 0; _i < 2; ++_i) \
;         __builtin_amdgcn_global_load_lds((const unsigned*)((const char*)(gbase) + (voff)[_i]), (PG8_LAS unsigned*)(lds + (bufoff) + ldsw + _i * 8192), 16, 0, 0); } while (0)
; #define PG8_LDA(dst, b, h) do { _Pragma("unroll") for (int m = 0; m < 4; ++m) _Pragma("unroll") for (int k = 0; k < 2; ++k) dst[m][k] = *(const PG8_LAS bf16x8*)(lds + PG8_SA(b, h) + aoff + m * 2048 + k * 1024); } while (0)
; #define PG8_LDB(dst, b, h) do { _Pragma("unroll") for (int n = 0; n < 2; ++n) _Pragma("unroll") for (int k = 0; k < 2; ++k) dst[n][k] = *(const PG8_LAS bf16x8*)(lds + PG8_SB(b, h) + boff + n * 2048 + k * 1024); } while (0)
; #define PG8_WAIT_V(n) asm volatile("s_waitcnt vmcnt(" #n ")" ::: "memory")
; #define PG8_WAIT_L(n) asm volatile("s_waitcnt lgkmcnt(" #n ")" ::: "memory")
; #define PG8_BAR __builtin_amdgcn_s_barrier()
; #define PG8_SCHED __builtin_amdgcn_sched_barrier(0)
; template <class Epi, class Sched, bool ALIGN_EPI = false, bool SP2 = false>
; __device__ __forceinline__ void gemm_phase(PG8_LAS unsigned char* lds, const Gemm g, const Sched& S, const Epi& E, const int tid_in) {
;     ...
;         for (int t = 0; t < nt; t += 2) {
;             const bool last = (t == nt - 2);
;             const char* a1 = cA + (size_t)(t + 1) * kstep;
;             const char* a2 = last ? nA : cA + (size_t)(t + 2) * kstep; const char* b2 = last ? nB : cB + (size_t)(t + 2) * kstep;
;             const char* a3 = a2 + kstep; const char* b3 = b2 + kstep;
;             if (last && has_next) S.a_ready(nxt);
;             if constexpr (SP2) {
;             PG8_LDB(B0, 0, 0); PG8_LDB(B1, 0, 1); PG8_SCHED; PG8_LDA(At, 0, 0); PG8_STAGE(PG8_SA(1, 1), a1 + hstepA, voffA);
;             PG8_WAIT_V(8); PG8_WAIT_L(0); PG8_BAR; PG8_MMA(0, 0, At, B0); PG8_MMA(0, 1, At, B1); PG8_BAR; PG8_SCHED;
;             PG8_LDA(At, 0, 1); PG8_STAGE(PG8_SB(0, 0), b2, voffB); PG8_STAGE(PG8_SB(0, 1), b2 + hstepB, voffB); PG8_STAGE(PG8_SA(0, 0), a2, voffA);
;             PG8_WAIT_V(8); PG8_WAIT_L(0); PG8_BAR; PG8_MMA(1, 0, At, B0); PG8_MMA(1, 1, At, B1); PG8_BAR; PG8_SCHED;
.LBB0_2427:
	s_lshl_b32 s74, s37, 7
	s_add_u32 s75, s62, s74
	s_addc_u32 s76, s63, 0
	s_add_u32 s77, s75, 0x100
	s_addc_u32 s85, s76, 0
	s_and_b64 s[72:73], s[22:23], exec
	s_cselect_b32 s73, s65, s85
	s_cselect_b32 s72, s64, s77
	s_add_u32 s74, s66, s74
	s_addc_u32 s77, s67, 0
	s_add_u32 s74, s74, 0x100
	s_addc_u32 s77, s77, 0
	s_and_b64 s[22:23], s[22:23], exec
	s_cselect_b32 s23, s69, s77
	s_cselect_b32 s22, s68, s74
	s_add_i32 s77, 0, 0x10000
	s_add_i32 s85, 0, 0x14000
	ds_read_b128 v[64:67], v249
	ds_read_b128 v[68:71], v249 offset:1024
	ds_read_b128 v[72:75], v249 offset:2048
	ds_read_b128 v[76:79], v249 offset:3072
	ds_read_b128 v[80:83], v249 offset:16384
	ds_read_b128 v[84:87], v249 offset:17408
	ds_read_b128 v[88:91], v249 offset:18432
	ds_read_b128 v[92:95], v249 offset:19456
	s_add_u32 s74, s75, 0x150080
	s_addc_u32 s75, s76, 0
	s_add_i32 m0, s17, 0xc000
	ds_read_b128 v[96:99], v150
	ds_read_b128 v[100:103], v150 offset:1024
	ds_read_b128 v[104:107], v150 offset:2048
	ds_read_b128 v[108:111], v150 offset:3072
	ds_read_b128 v[112:115], v150 offset:4096
	ds_read_b128 v[116:119], v150 offset:5120
	ds_read_b128 v[120:123], v150 offset:6144
	ds_read_b128 v[124:127], v150 offset:7168
	global_load_lds_dwordx4 v172, s[74:75]
	s_add_i32 m0, s17, 0xe000
	s_nop 0
	global_load_lds_dwordx4 v128, s[74:75]
	s_waitcnt vmcnt(8)
	s_waitcnt lgkmcnt(0)
	s_barrier
	s_waitcnt lgkmcnt(0)
	v_mfma_f32_16x16x32_bf16 v[60:63], v[64:67], v[96:99], v[60:63]
	v_mfma_f32_16x16x32_bf16 v[56:59], v[72:75], v[96:99], v[56:59]
	v_mfma_f32_16x16x32_bf16 v[44:47], v[64:67], v[104:107], v[44:47]
	v_mfma_f32_16x16x32_bf16 v[40:43], v[72:75], v[104:107], v[40:43]
	v_mfma_f32_16x16x32_bf16 v[32:35], v[64:67], v[112:115], v[32:35]
	v_mfma_f32_16x16x32_bf16 v[24:27], v[72:75], v[112:115], v[24:27]
	v_mfma_f32_16x16x32_bf16 v[16:19], v[64:67], v[120:123], v[16:19]
	v_mfma_f32_16x16x32_bf16 v[8:11], v[72:75], v[120:123], v[8:11]
	v_mfma_f32_16x16x32_bf16 v[60:63], v[68:71], v[100:103], v[60:63]
	v_mfma_f32_16x16x32_bf16 v[56:59], v[76:79], v[100:103], v[56:59]
	v_mfma_f32_16x16x32_bf16 v[44:47], v[68:71], v[108:111], v[44:47]
	v_mfma_f32_16x16x32_bf16 v[40:43], v[76:79], v[108:111], v[40:43]
	v_mfma_f32_16x16x32_bf16 v[32:35], v[68:71], v[116:119], v[32:35]
	v_mfma_f32_16x16x32_bf16 v[24:27], v[76:79], v[116:119], v[24:27]
	v_mfma_f32_16x16x32_bf16 v[16:19], v[68:71], v[124:127], v[16:19]
	v_mfma_f32_16x16x32_bf16 v[8:11], v[76:79], v[124:127], v[8:11]
	v_mfma_f32_16x16x32_bf16 v[52:55], v[80:83], v[96:99], v[52:55]
	v_mfma_f32_16x16x32_bf16 v[48:51], v[88:91], v[96:99], v[48:51]
	v_mfma_f32_16x16x32_bf16 v[36:39], v[80:83], v[104:107], v[36:39]
	v_mfma_f32_16x16x32_bf16 v[28:31], v[88:91], v[104:107], v[28:31]
	v_mfma_f32_16x16x32_bf16 v[20:23], v[80:83], v[112:115], v[20:23]
	v_mfma_f32_16x16x32_bf16 v[12:15], v[88:91], v[112:115], v[12:15]
	v_mfma_f32_16x16x32_bf16 v[4:7], v[80:83], v[120:123], v[4:7]
	v_mfma_f32_16x16x32_bf16 v[0:3], v[88:91], v[120:123], v[0:3]
	v_mfma_f32_16x16x32_bf16 v[52:55], v[84:87], v[100:103], v[52:55]
	v_mfma_f32_16x16x32_bf16 v[48:51], v[92:95], v[100:103], v[48:51]
	v_mfma_f32_16x16x32_bf16 v[36:39], v[84:87], v[108:111], v[36:39]
	v_mfma_f32_16x16x32_bf16 v[28:31], v[92:95], v[108:111], v[28:31]
	v_mfma_f32_16x16x32_bf16 v[20:23], v[84:87], v[116:119], v[20:23]
	v_mfma_f32_16x16x32_bf16 v[12:15], v[92:95], v[116:119], v[12:15]
	v_mfma_f32_16x16x32_bf16 v[4:7], v[84:87], v[124:127], v[4:7]
	v_mfma_f32_16x16x32_bf16 v[0:3], v[92:95], v[124:127], v[0:3]
	s_barrier
	s_add_i32 s74, s77, s16
	s_mov_b32 m0, s74
	s_nop 0
	global_load_lds_dwordx4 v172, s[22:23]
	s_add_i32 m0, s74, 0x2000
	s_add_u32 s74, s22, 0x150000
	s_addc_u32 s75, s23, 0
	s_add_i32 s76, s85, s16
	global_load_lds_dwordx4 v128, s[22:23]
	s_mov_b32 m0, s76
	s_add_u32 vcc_lo, s72, 0x80
	s_addc_u32 vcc_hi, s73, 0
	global_load_lds_dwordx4 v172, s[74:75]
	s_add_i32 m0, s76, 0x2000
	s_nop 0
	global_load_lds_dwordx4 v128, s[74:75]
	s_mov_b32 m0, s17
	s_nop 0
	global_load_lds_dwordx4 v172, s[72:73]
	s_mov_b32 m0, s20
	s_nop 0
	global_load_lds_dwordx4 v128, s[72:73]
	s_waitcnt vmcnt(8)
	s_waitcnt lgkmcnt(0)
	s_barrier
; #define PG8_STAGE(bufoff, gbase, voff) do { _Pragma("unroll") for (int _i = 0; _i < 2; ++_i) \
;         __builtin_amdgcn_global_load_lds((const unsigned*)((const char*)(gbase) + (voff)[_i]), (PG8_LAS unsigned*)(lds + (bufoff) + ldsw + _i * 8192), 16, 0, 0); } while (0)
; #define PG8_LDA(dst, b, h) do { _Pragma("unroll") for (int m = 0; m < 4; ++m) _Pragma("unroll") for (int k = 0; k < 2; ++k) dst[m][k] = *(const PG8_LAS bf16x8*)(lds + PG8_SA(b, h) + aoff + m * 2048 + k * 1024); } while (0)
; #define PG8_LDB(dst, b, h) do { _Pragma("unroll") for (int n = 0; n < 2; ++n) _Pragma("unroll") for (int k = 0; k < 2; ++k) dst[n][k] = *(const PG8_LAS bf16x8*)(lds + PG8_SB(b, h) + boff + n * 2048 + k * 1024); } while (0)
; #define PG8_MMA(ai, bj, At, Bt) do { __builtin_amdgcn_s_setprio(1); _Pragma("unroll") for (int m = 0; m < 4; ++m) _Pragma("unroll") for (int n = 0; n < 2; ++n) _Pragma("unroll") for (int k = 0; k < 2; ++k) \
;         acc[ai][bj][m][n] = __builtin_amdgcn_mfma_f32_16x16x32_bf16(Bt[n][k], At[m][k], acc[ai][bj][m][n], 0, 0, 0); __builtin_amdgcn_s_setprio(0); } while (0)
; #define PG8_WAIT_V(n) asm volatile("s_waitcnt vmcnt(" #n ")" ::: "memory")
; #define PG8_WAIT_L(n) asm volatile("s_waitcnt lgkmcnt(" #n ")" ::: "memory")
; #define PG8_BAR __builtin_amdgcn_s_barrier()
; #define PG8_SCHED __builtin_amdgcn_sched_barrier(0)
; template <class Epi, class Sched, bool ALIGN_EPI = false, bool SP2 = false>
; __device__ __forceinline__ void gemm_phase(PG8_LAS unsigned char* lds, const Gemm g, const Sched& S, const Epi& E, const int tid_in) {
;     ...
;             PG8_WAIT_V(8); PG8_WAIT_L(0); PG8_BAR; PG8_MMA(1, 0, At, B0); PG8_MMA(1, 1, At, B1); PG8_BAR; PG8_SCHED;
;             PG8_LDB(B0, 1, 0); PG8_LDB(B1, 1, 1); PG8_SCHED; PG8_LDA(At, 1, 0); PG8_STAGE(PG8_SA(0, 1), a2 + hstepA, voffA);
;             PG8_WAIT_V(8); PG8_WAIT_L(0); PG8_BAR; PG8_MMA(0, 0, At, B0); PG8_MMA(0, 1, At, B1); PG8_BAR; PG8_SCHED;
;             PG8_LDA(At, 1, 1); PG8_STAGE(PG8_SB(1, 0), b3, voffB); PG8_STAGE(PG8_SB(1, 1), b3 + hstepB, voffB); PG8_STAGE(PG8_SA(1, 0), a3, voffA);
;             PG8_WAIT_V(8); PG8_WAIT_L(0); PG8_BAR; PG8_MMA(1, 0, At, B0); PG8_MMA(1, 1, At, B1); PG8_BAR; PG8_SCHED;
	s_barrier
	s_add_i32 s74, 0, 0x18000
	s_add_i32 s75, 0, 0x1c000
	ds_read_b128 v[64:67], v249 offset:32768
	ds_read_b128 v[68:71], v249 offset:33792
	ds_read_b128 v[72:75], v249 offset:34816
	ds_read_b128 v[76:79], v249 offset:35840
	ds_read_b128 v[80:83], v249 offset:49152
	ds_read_b128 v[84:87], v249 offset:50176
	ds_read_b128 v[88:91], v249 offset:51200
	ds_read_b128 v[92:95], v249 offset:52224
	s_add_u32 s72, s72, 0x150000
	s_addc_u32 s73, s73, 0
	s_mov_b32 m0, s21
	ds_read_b128 v[96:99], v150 offset:32768
	ds_read_b128 v[100:103], v150 offset:33792
	ds_read_b128 v[104:107], v150 offset:34816
	ds_read_b128 v[108:111], v150 offset:35840
	ds_read_b128 v[112:115], v150 offset:36864
	ds_read_b128 v[116:119], v150 offset:37888
	ds_read_b128 v[120:123], v150 offset:38912
	ds_read_b128 v[124:127], v150 offset:39936
	global_load_lds_dwordx4 v172, s[72:73]
	s_mov_b32 m0, s31
	s_nop 0
	global_load_lds_dwordx4 v128, s[72:73]
	s_waitcnt vmcnt(8)
	s_waitcnt lgkmcnt(0)
	s_barrier
	s_waitcnt lgkmcnt(0)
	v_mfma_f32_16x16x32_bf16 v[60:63], v[64:67], v[96:99], v[60:63]
	v_mfma_f32_16x16x32_bf16 v[56:59], v[72:75], v[96:99], v[56:59]
	v_mfma_f32_16x16x32_bf16 v[44:47], v[64:67], v[104:107], v[44:47]
	v_mfma_f32_16x16x32_bf16 v[40:43], v[72:75], v[104:107], v[40:43]
	v_mfma_f32_16x16x32_bf16 v[32:35], v[64:67], v[112:115], v[32:35]
	v_mfma_f32_16x16x32_bf16 v[24:27], v[72:75], v[112:115], v[24:27]
	v_mfma_f32_16x16x32_bf16 v[16:19], v[64:67], v[120:123], v[16:19]
	v_mfma_f32_16x16x32_bf16 v[8:11], v[72:75], v[120:123], v[8:11]
	v_mfma_f32_16x16x32_bf16 v[60:63], v[68:71], v[100:103], v[60:63]
	v_mfma_f32_16x16x32_bf16 v[56:59], v[76:79], v[100:103], v[56:59]
	v_mfma_f32_16x16x32_bf16 v[44:47], v[68:71], v[108:111], v[44:47]
	v_mfma_f32_16x16x32_bf16 v[40:43], v[76:79], v[108:111], v[40:43]
	v_mfma_f32_16x16x32_bf16 v[32:35], v[68:71], v[116:119], v[32:35]
	v_mfma_f32_16x16x32_bf16 v[24:27], v[76:79], v[116:119], v[24:27]
	v_mfma_f32_16x16x32_bf16 v[16:19], v[68:71], v[124:127], v[16:19]
	v_mfma_f32_16x16x32_bf16 v[8:11], v[76:79], v[124:127], v[8:11]
	v_mfma_f32_16x16x32_bf16 v[52:55], v[80:83], v[96:99], v[52:55]
	v_mfma_f32_16x16x32_bf16 v[48:51], v[88:91], v[96:99], v[48:51]
	v_mfma_f32_16x16x32_bf16 v[36:39], v[80:83], v[104:107], v[36:39]
	v_mfma_f32_16x16x32_bf16 v[28:31], v[88:91], v[104:107], v[28:31]
	v_mfma_f32_16x16x32_bf16 v[20:23], v[80:83], v[112:115], v[20:23]
	v_mfma_f32_16x16x32_bf16 v[12:15], v[88:91], v[112:115], v[12:15]
	v_mfma_f32_16x16x32_bf16 v[4:7], v[80:83], v[120:123], v[4:7]
	v_mfma_f32_16x16x32_bf16 v[0:3], v[88:91], v[120:123], v[0:3]
	v_mfma_f32_16x16x32_bf16 v[52:55], v[84:87], v[100:103], v[52:55]
	v_mfma_f32_16x16x32_bf16 v[48:51], v[92:95], v[100:103], v[48:51]
	v_mfma_f32_16x16x32_bf16 v[36:39], v[84:87], v[108:111], v[36:39]
	v_mfma_f32_16x16x32_bf16 v[28:31], v[92:95], v[108:111], v[28:31]
	v_mfma_f32_16x16x32_bf16 v[20:23], v[84:87], v[116:119], v[20:23]
	v_mfma_f32_16x16x32_bf16 v[12:15], v[92:95], v[116:119], v[12:15]
	v_mfma_f32_16x16x32_bf16 v[4:7], v[84:87], v[124:127], v[4:7]
	v_mfma_f32_16x16x32_bf16 v[0:3], v[92:95], v[124:127], v[0:3]
	s_barrier
	s_add_i32 s72, s74, s16
	s_mov_b32 m0, s72
	s_nop 0
	s_add_u32 s100, s22, 0x80
	s_addc_u32 s101, s23, 0
	global_load_lds_dwordx4 v172, s[100:101]
	s_add_i32 m0, s72, 0x2000
	s_add_u32 s22, s22, 0x150080
	s_addc_u32 s23, s23, 0
	s_add_i32 s72, s75, s16
	global_load_lds_dwordx4 v128, s[100:101]
	s_mov_b32 m0, s72
	s_nop 0
	global_load_lds_dwordx4 v172, s[22:23]
	s_add_i32 m0, s72, 0x2000
	s_nop 0
	global_load_lds_dwordx4 v128, s[22:23]
	s_mov_b32 m0, s33
	s_nop 0
	global_load_lds_dwordx4 v172, vcc
	s_mov_b32 m0, s34
	s_nop 0
	global_load_lds_dwordx4 v128, vcc
	s_waitcnt vmcnt(8)
	s_waitcnt lgkmcnt(0)
	s_barrier
	s_barrier
	s_add_i32 s22, s37, 2
	s_cmp_gt_u32 s37, 9
	s_mov_b32 s37, s22
	s_cbranch_scc1 .LBB0_2442
